# panel-section stores go through L2 (plain) when the 4 owners of a row panel are verified to share an XCD at run time; write-through fallback otherwise
# speedup vs baseline: 1.0143x; 1.0143x over previous
; #define LAS __attribute__((address_space(3)))
; __device__ __forceinline__ unsigned xb_add(unsigned* p, unsigned v) { return __hip_atomic_fetch_add(p, v, __ATOMIC_RELAXED, __HIP_MEMORY_SCOPE_AGENT); }
; __device__ __forceinline__ unsigned xb_xcc_id() { return (unsigned)__builtin_amdgcn_s_getreg((3 << 11) | 20) & 0xFu; }
; __device__ __forceinline__ XcdBarrier xcd_barrier_post(unsigned* bar, volatile LAS unsigned* st) {
;     XcdBarrier b; b.bar = bar; b.x = xb_xcc_id(); b.st = st;
;     if (threadIdx.x == 0) (void)xb_add(&bar[XB_XCNT(b.x)], 1u);
;     return b;
; }
.LBB0_14:
	s_add_u32 s82, s84, 0x1000
	s_getreg_b32 s4, hwreg(HW_REG_XCC_ID, 0, 4)
	s_addc_u32 s83, s85, 0
	s_and_b32 s4, s4, 15
	v_writelane_b32 v255, s4, 1
	v_cmp_eq_u32_e64 s[6:7], 0, v128
	s_mov_b64 s[4:5], exec
	s_nop 0
	v_writelane_b32 v255, s6, 2
	s_nop 1
	v_writelane_b32 v255, s7, 3
	s_and_b64 s[6:7], s[4:5], s[6:7]
	s_mov_b64 exec, s[6:7]
	s_cbranch_execz .LBB0_17
	s_mov_b64 s[6:7], exec
	v_mbcnt_lo_u32_b32 v0, s6, 0
	v_mbcnt_hi_u32_b32 v0, s7, v0
	v_cmp_eq_u32_e32 vcc, 0, v0
	s_and_b64 s[8:9], exec, vcc
	s_mov_b64 exec, s[8:9]
	s_cbranch_execz .LBB0_17
	v_readlane_b32 s8, v255, 1
	s_lshl_b32 s8, s8, 8
	s_bcnt1_i32_b64 s6, s[6:7]
	v_mov_b32_e32 v0, s8
	v_mov_b32_e32 v1, s6
	global_atomic_add v0, v1, s[82:83] offset:1024
	v_readlane_b32 s8, v255, 1
	s_lshl_b32 s9, s2, 2
	s_add_i32 s9, s9, 0x7000
	s_add_i32 s8, s8, 1
	v_mov_b32_e32 v2, s9
	v_mov_b32_e32 v3, s8
	global_store_dword v2, v3, s[82:83] sc1

;     __host__ __device__ bool next(int i, Unit& u) const {
;         const long L = (long)i * G + c; if (L >= nwg) return false;
;         int wgid = (int)L; { const int q = nwg / NXCD, r = nwg % NXCD, xcd = wgid % NXCD, off = wgid / NXCD; wgid = (xcd < r ? xcd * (q + 1) : r * (q + 1) + (xcd - r) * q) + off; }
;         const int nig = WGM * nN, gid = wgid / nig, fm = gid * WGM, gsz = (nM - fm) < WGM ? (nM - fm) : WGM;
;         u.pm = fm + ((wgid % nig) % gsz); u.pn = (wgid % nig) / gsz; return true;
; __global__ void __launch_bounds__(512, 2) fwd_mega(Args a) {
;     ...
;     const bool panel_mode = (G == 256);
;     pg8::Unit myu; { pg8::StaticOrder S; S.init(M, D, G, bid); if (!S.next(0, myu)) { myu.pm = 0; myu.pn = 0; } }
;     unsigned* pbar = (unsigned*)(ws + WS_CTL + 327680) + 64 * myu.pm;
.LBB0_494:
	s_and_b32 s4, s2, 63
	s_lshl_b32 s4, s4, 2
	s_add_i32 s4, s4, 0x8000
	v_mov_b32_e32 v0, s4
	global_load_dword v1, v0, s[84:85] sc1
	global_load_dword v2, v0, s[84:85] offset:256 sc1
	global_load_dword v3, v0, s[84:85] offset:512 sc1
	global_load_dword v4, v0, s[84:85] offset:768 sc1
	s_waitcnt vmcnt(0)
	v_cmp_eq_u32_e64 s[4:5], v1, v2
	v_cmp_eq_u32_e64 s[6:7], v1, v3
	v_cmp_eq_u32_e64 s[8:9], v1, v4
	v_cmp_ne_u32_e64 s[10:11], 0, v1
	s_and_b64 s[4:5], s[4:5], s[6:7]
	s_and_b64 s[8:9], s[8:9], s[10:11]
	s_and_b64 s[4:5], s[4:5], s[8:9]
	s_cmp_eq_u64 s[4:5], exec
	s_cselect_b32 s4, 1, 0
	v_writelane_b32 v255, s4, 59
	s_cmpk_lt_i32 s2, 0x100
	s_mov_b32 s12, 0
	s_cselect_b64 s[4:5], -1, 0
	s_cmpk_gt_i32 s2, 0xff
	s_mov_b32 s33, 0
	s_cbranch_scc1 .LBB0_500
	s_ashr_i32 s3, s2, 31
	s_lshr_b32 s3, s3, 29
	s_add_i32 s3, s2, s3
	s_and_b32 s6, s3, -8
	s_sub_i32 s8, s2, s6
	s_cmp_gt_i32 s8, -1
	s_cbranch_scc0 .LBB0_497
	s_lshl_b32 s9, s8, 5
	s_cbranch_execz .LBB0_498
	s_branch .LBB0_499

; __device__ __forceinline__ unsigned cvt_pk_bf16(float lo, float hi) { f32x2_t v = {lo, hi}; bf16x2_t b = __builtin_convertvector(v, bf16x2_t); return __builtin_bit_cast(unsigned, b); }
;     __device__ __forceinline__ void operator()(const f32x4 (&acc)[2][2][4][2], const Unit& u, int wr, int wc, int fr, int fq) const {
;     ...
;             for (int m = 0; m < 4; ++m) { const int row = u.pm * BM + ai * HALF + wr * 64 + m * 16 + fr; const size_t off = (size_t)row * ldc + col0; float ss = 0.f;
; #pragma unroll
;                 for (int bj = 0; bj < 2; ++bj) { const size_t o2 = off + bj * HALF; f32x4 b0, b1;
;                     if (MODE == 0) { b0 = *(const f32x4*)(basef + o2); b1 = *(const f32x4*)(basef + o2 + 4); }
;                     else { const u32x4 w = *(const u32x4*)(xb + o2);
;                         b0 = (f32x4){__uint_as_float(w.x << 16), __uint_as_float(w.x & 0xffff0000u), __uint_as_float(w.y << 16), __uint_as_float(w.y & 0xffff0000u)};
;                         b1 = (f32x4){__uint_as_float(w.z << 16), __uint_as_float(w.z & 0xffff0000u), __uint_as_float(w.w << 16), __uint_as_float(w.w & 0xffff0000u)}; }
;                     const f32x4 v0 = b0 + acc[ai][bj][m][0], v1 = b1 + acc[ai][bj][m][1];
;                     if (MODE == 2) { *(f32x4*)(outf + o2) = v0; *(f32x4*)(outf + o2 + 4) = v1; }
;                     else { ss += (v0[0] * v0[0] + v0[1] * v0[1]) + (v0[2] * v0[2] + v0[3] * v0[3]) + (v1[0] * v1[0] + v1[1] * v1[1]) + (v1[2] * v1[2] + v1[3] * v1[3]);
;                         u32x4 w; w.x = cvt_pk_bf16(v0[0], v0[1]); w.y = cvt_pk_bf16(v0[2], v0[3]); w.z = cvt_pk_bf16(v1[0], v1[1]); w.w = cvt_pk_bf16(v1[2], v1[3]);
;                         __builtin_amdgcn_raw_buffer_store_b128(w, rsrc, (unsigned)(o2 * 2), 0, 16); } }
;                 if (MODE != 2) { ss += __shfl_xor(ss, 16); ss += __shfl_xor(ss, 32); if (fq == 0) atomicAdd(rowsq + row, ss); } }
.LBB0_523:
	v_readlane_b32 vcc_lo, v255, 59
	s_mov_b32 vcc_hi, 0
	s_nop 1
	s_mov_b64 vcc, vcc
	s_nop 1
	s_cbranch_vccnz .Lpp5_plain
	v_lshl_add_u32 v148, s40, 8, v129
	v_lshl_or_b32 v146, s42, 8, v151
	v_ashrrev_i32_e32 v149, 31, v148
	v_ashrrev_i32_e32 v147, 31, v146
	v_lshlrev_b64 v[156:157], 10, v[148:149]
	v_lshl_add_u64 v[160:161], v[156:157], 0, v[146:147]
	v_lshl_add_u64 v[156:157], v[160:161], 1, s[96:97]
	global_load_dwordx4 v[156:159], v[156:157], off
	v_lshlrev_b32_e32 v168, 1, v160
	v_or_b32_e32 v160, 0x80, v160
	v_lshl_add_u64 v[162:163], v[160:161], 1, s[96:97]
	v_xor_b32_e32 v161, 32, v155
	s_waitcnt vmcnt(0)
	v_lshlrev_b32_e32 v164, 16, v156
	v_and_b32_e32 v165, 0xffff0000, v156
	v_lshlrev_b32_e32 v156, 16, v157
	v_and_b32_e32 v157, 0xffff0000, v157
	v_lshlrev_b32_e32 v166, 16, v158
	v_and_b32_e32 v167, 0xffff0000, v158
	v_lshlrev_b32_e32 v158, 16, v159
	v_and_b32_e32 v159, 0xffff0000, v159
	v_pk_add_f32 v[126:127], v[126:127], v[156:157]
	v_pk_add_f32 v[156:157], v[124:125], v[164:165]
	v_pk_add_f32 v[158:159], v[122:123], v[158:159]
	v_pk_add_f32 v[164:165], v[120:121], v[166:167]
	v_cvt_pk_bf16_f32 v120, v156, v157
	v_cvt_pk_bf16_f32 v121, v126, v127
	v_cvt_pk_bf16_f32 v122, v164, v165
	v_cvt_pk_bf16_f32 v123, v158, v159
	buffer_store_dwordx4 v[120:123], v168, s[8:11], 0 offen sc1
	global_load_dwordx4 v[122:125], v[162:163], off
	v_mul_f32_e32 v157, v157, v157
	v_mul_f32_e32 v127, v127, v127
	v_mul_f32_e32 v162, v165, v165
	v_fmac_f32_e32 v157, v156, v156
	v_fmac_f32_e32 v127, v126, v126
	v_mul_f32_e32 v159, v159, v159
	v_fmac_f32_e32 v162, v164, v164
	v_add_f32_e32 v126, v157, v127
	v_fmac_f32_e32 v159, v158, v158
	v_add_f32_e32 v126, v162, v126
	v_add_f32_e32 v158, v159, v126
	v_and_b32_e32 v121, 64, v155
	v_xor_b32_e32 v120, 16, v155
	v_add_u32_e32 v121, 64, v121
	v_cmp_lt_i32_e32 vcc, v120, v121
	s_waitcnt vmcnt(0)
	v_lshlrev_b32_e32 v126, 16, v122
	v_and_b32_e32 v127, 0xffff0000, v122
	v_lshlrev_b32_e32 v122, 16, v123
	v_and_b32_e32 v123, 0xffff0000, v123
	v_lshlrev_b32_e32 v156, 16, v124
	v_and_b32_e32 v157, 0xffff0000, v124
	v_lshlrev_b32_e32 v124, 16, v125
	v_and_b32_e32 v125, 0xffff0000, v125
	v_pk_add_f32 v[118:119], v[118:119], v[122:123]
	v_pk_add_f32 v[116:117], v[116:117], v[126:127]
	v_pk_add_f32 v[122:123], v[114:115], v[124:125]
	v_pk_add_f32 v[124:125], v[112:113], v[156:157]
	v_mul_f32_e32 v112, v117, v117
	v_mul_f32_e32 v113, v119, v119
	v_mul_f32_e32 v114, v125, v125
	v_fmac_f32_e32 v112, v116, v116
	v_fmac_f32_e32 v113, v118, v118
	v_mul_f32_e32 v115, v123, v123
	v_fmac_f32_e32 v114, v124, v124
	v_add_f32_e32 v112, v112, v113
	v_fmac_f32_e32 v115, v122, v122
	v_add_f32_e32 v112, v114, v112
	v_cndmask_b32_e32 v120, v155, v120, vcc
	v_add_f32_e32 v112, v115, v112
	v_lshlrev_b32_e32 v120, 2, v120
	v_add_f32_e32 v112, v158, v112
	ds_bpermute_b32 v113, v120, v112
	v_cmp_lt_i32_e32 vcc, v161, v121
	v_cvt_pk_bf16_f32 v116, v116, v117
	v_cvt_pk_bf16_f32 v117, v118, v119
	v_cndmask_b32_e32 v114, v155, v161, vcc
	v_lshlrev_b32_e32 v114, 2, v114
	s_waitcnt lgkmcnt(0)
	v_add_f32_e32 v112, v112, v113
	ds_bpermute_b32 v113, v114, v112
	v_cvt_pk_bf16_f32 v118, v124, v125
	v_cvt_pk_bf16_f32 v119, v122, v123
	v_lshlrev_b32_e32 v115, 1, v160
	buffer_store_dwordx4 v[116:119], v115, s[8:11], 0 offen sc1
	s_and_saveexec_b64 s[40:41], s[4:5]
	s_cbranch_execz .LBB0_525
	v_lshl_add_u64 v[116:117], v[148:149], 2, s[22:23]
	s_waitcnt lgkmcnt(0)
	v_add_f32_e32 v112, v112, v113
	global_atomic_add_f32 v[116:117], v112, off

; __device__ __forceinline__ unsigned cvt_pk_bf16(float lo, float hi) { f32x2_t v = {lo, hi}; bf16x2_t b = __builtin_convertvector(v, bf16x2_t); return __builtin_bit_cast(unsigned, b); }
;     __device__ __forceinline__ void operator()(const f32x4 (&acc)[2][2][4][2], const Unit& u, int wr, int wc, int fr, int fq) const {
;     ...
;             for (int m = 0; m < 4; ++m) { const int row = u.pm * BM + ai * HALF + wr * 64 + m * 16 + fr; const size_t off = (size_t)row * ldc + col0; float ss = 0.f;
; #pragma unroll
;                 for (int bj = 0; bj < 2; ++bj) { const size_t o2 = off + bj * HALF; f32x4 b0, b1;
;                     if (MODE == 0) { b0 = *(const f32x4*)(basef + o2); b1 = *(const f32x4*)(basef + o2 + 4); }
;                     else { const u32x4 w = *(const u32x4*)(xb + o2);
;                         b0 = (f32x4){__uint_as_float(w.x << 16), __uint_as_float(w.x & 0xffff0000u), __uint_as_float(w.y << 16), __uint_as_float(w.y & 0xffff0000u)};
;                         b1 = (f32x4){__uint_as_float(w.z << 16), __uint_as_float(w.z & 0xffff0000u), __uint_as_float(w.w << 16), __uint_as_float(w.w & 0xffff0000u)}; }
;                     const f32x4 v0 = b0 + acc[ai][bj][m][0], v1 = b1 + acc[ai][bj][m][1];
;                     if (MODE == 2) { *(f32x4*)(outf + o2) = v0; *(f32x4*)(outf + o2 + 4) = v1; }
;                     else { ss += (v0[0] * v0[0] + v0[1] * v0[1]) + (v0[2] * v0[2] + v0[3] * v0[3]) + (v1[0] * v1[0] + v1[1] * v1[1]) + (v1[2] * v1[2] + v1[3] * v1[3]);
;                         u32x4 w; w.x = cvt_pk_bf16(v0[0], v0[1]); w.y = cvt_pk_bf16(v0[2], v0[3]); w.z = cvt_pk_bf16(v1[0], v1[1]); w.w = cvt_pk_bf16(v1[2], v1[3]);
;                         __builtin_amdgcn_raw_buffer_store_b128(w, rsrc, (unsigned)(o2 * 2), 0, 16); } }
;                 if (MODE != 2) { ss += __shfl_xor(ss, 16); ss += __shfl_xor(ss, 32); if (fq == 0) atomicAdd(rowsq + row, ss); } }
.LBB0_539:
	s_or_b64 exec, exec, s[40:41]
	s_branch .Lpp5_done
.Lpp5_plain:
	v_lshl_add_u32 v148, s40, 8, v129
	v_lshl_or_b32 v146, s42, 8, v151
	v_ashrrev_i32_e32 v149, 31, v148
	v_ashrrev_i32_e32 v147, 31, v146
	v_lshlrev_b64 v[156:157], 10, v[148:149]
	v_lshl_add_u64 v[160:161], v[156:157], 0, v[146:147]
	v_lshl_add_u64 v[156:157], v[160:161], 1, s[96:97]
	global_load_dwordx4 v[156:159], v[156:157], off
	v_lshlrev_b32_e32 v168, 1, v160
	v_or_b32_e32 v160, 0x80, v160
	v_lshl_add_u64 v[162:163], v[160:161], 1, s[96:97]
	v_xor_b32_e32 v161, 32, v155
	s_waitcnt vmcnt(0)
	v_lshlrev_b32_e32 v164, 16, v156
	v_and_b32_e32 v165, 0xffff0000, v156
	v_lshlrev_b32_e32 v156, 16, v157
	v_and_b32_e32 v157, 0xffff0000, v157
	v_lshlrev_b32_e32 v166, 16, v158
	v_and_b32_e32 v167, 0xffff0000, v158
	v_lshlrev_b32_e32 v158, 16, v159
	v_and_b32_e32 v159, 0xffff0000, v159
	v_pk_add_f32 v[126:127], v[126:127], v[156:157]
	v_pk_add_f32 v[156:157], v[124:125], v[164:165]
	v_pk_add_f32 v[158:159], v[122:123], v[158:159]
	v_pk_add_f32 v[164:165], v[120:121], v[166:167]
	v_cvt_pk_bf16_f32 v120, v156, v157
	v_cvt_pk_bf16_f32 v121, v126, v127
	v_cvt_pk_bf16_f32 v122, v164, v165
	v_cvt_pk_bf16_f32 v123, v158, v159
	buffer_store_dwordx4 v[120:123], v168, s[8:11], 0 offen
	global_load_dwordx4 v[122:125], v[162:163], off
	v_mul_f32_e32 v157, v157, v157
	v_mul_f32_e32 v127, v127, v127
	v_mul_f32_e32 v162, v165, v165
	v_fmac_f32_e32 v157, v156, v156
	v_fmac_f32_e32 v127, v126, v126
	v_mul_f32_e32 v159, v159, v159
	v_fmac_f32_e32 v162, v164, v164
	v_add_f32_e32 v126, v157, v127
	v_fmac_f32_e32 v159, v158, v158
	v_add_f32_e32 v126, v162, v126
	v_add_f32_e32 v158, v159, v126
	v_and_b32_e32 v121, 64, v155
	v_xor_b32_e32 v120, 16, v155
	v_add_u32_e32 v121, 64, v121
	v_cmp_lt_i32_e32 vcc, v120, v121
	s_waitcnt vmcnt(0)
	v_lshlrev_b32_e32 v126, 16, v122
	v_and_b32_e32 v127, 0xffff0000, v122
	v_lshlrev_b32_e32 v122, 16, v123
	v_and_b32_e32 v123, 0xffff0000, v123
	v_lshlrev_b32_e32 v156, 16, v124
	v_and_b32_e32 v157, 0xffff0000, v124
	v_lshlrev_b32_e32 v124, 16, v125
	v_and_b32_e32 v125, 0xffff0000, v125
	v_pk_add_f32 v[118:119], v[118:119], v[122:123]
	v_pk_add_f32 v[116:117], v[116:117], v[126:127]
	v_pk_add_f32 v[122:123], v[114:115], v[124:125]
	v_pk_add_f32 v[124:125], v[112:113], v[156:157]
	v_mul_f32_e32 v112, v117, v117
	v_mul_f32_e32 v113, v119, v119
	v_mul_f32_e32 v114, v125, v125
	v_fmac_f32_e32 v112, v116, v116
	v_fmac_f32_e32 v113, v118, v118
	v_mul_f32_e32 v115, v123, v123
	v_fmac_f32_e32 v114, v124, v124
	v_add_f32_e32 v112, v112, v113
	v_fmac_f32_e32 v115, v122, v122
	v_add_f32_e32 v112, v114, v112
	v_cndmask_b32_e32 v120, v155, v120, vcc
	v_add_f32_e32 v112, v115, v112
	v_lshlrev_b32_e32 v120, 2, v120
	v_add_f32_e32 v112, v158, v112
	ds_bpermute_b32 v113, v120, v112
	v_cmp_lt_i32_e32 vcc, v161, v121
	v_cvt_pk_bf16_f32 v116, v116, v117
	v_cvt_pk_bf16_f32 v117, v118, v119
	v_cndmask_b32_e32 v114, v155, v161, vcc
	v_lshlrev_b32_e32 v114, 2, v114
	s_waitcnt lgkmcnt(0)
	v_add_f32_e32 v112, v112, v113
	ds_bpermute_b32 v113, v114, v112
	v_cvt_pk_bf16_f32 v118, v124, v125
	v_cvt_pk_bf16_f32 v119, v122, v123
	v_lshlrev_b32_e32 v115, 1, v160
	buffer_store_dwordx4 v[116:119], v115, s[8:11], 0 offen
	s_and_saveexec_b64 s[40:41], s[4:5]
	s_cbranch_execz .Lpp5_525
	v_lshl_add_u64 v[116:117], v[148:149], 2, s[22:23]
	s_waitcnt lgkmcnt(0)
	v_add_f32_e32 v112, v112, v113
	global_atomic_add_f32 v[116:117], v112, off
.Lpp5_525:
	s_or_b64 exec, exec, s[40:41]
	v_or_b32_e32 v112, 16, v148
	s_waitcnt lgkmcnt(0)
	v_ashrrev_i32_e32 v113, 31, v112
	v_lshlrev_b64 v[116:117], 10, v[112:113]
	v_lshl_add_u64 v[122:123], v[116:117], 0, v[146:147]
	v_lshl_add_u64 v[116:117], v[122:123], 1, s[96:97]
	global_load_dwordx4 v[116:119], v[116:117], off
	v_lshlrev_b32_e32 v115, 1, v122
	v_or_b32_e32 v122, 0x80, v122
	v_lshl_add_u64 v[124:125], v[122:123], 1, s[96:97]
	s_waitcnt vmcnt(0)
	v_lshlrev_b32_e32 v126, 16, v116
	v_and_b32_e32 v127, 0xffff0000, v116
	v_lshlrev_b32_e32 v116, 16, v117
	v_and_b32_e32 v117, 0xffff0000, v117
	v_lshlrev_b32_e32 v156, 16, v118
	v_and_b32_e32 v157, 0xffff0000, v118
	v_lshlrev_b32_e32 v118, 16, v119
	v_and_b32_e32 v119, 0xffff0000, v119
	v_pk_add_f32 v[110:111], v[110:111], v[116:117]
	v_pk_add_f32 v[108:109], v[108:109], v[126:127]
	v_pk_add_f32 v[116:117], v[106:107], v[118:119]
	v_pk_add_f32 v[118:119], v[104:105], v[156:157]
	v_cvt_pk_bf16_f32 v104, v108, v109
	v_cvt_pk_bf16_f32 v105, v110, v111
	v_cvt_pk_bf16_f32 v106, v118, v119
	v_cvt_pk_bf16_f32 v107, v116, v117
	buffer_store_dwordx4 v[104:107], v115, s[8:11], 0 offen
	global_load_dwordx4 v[104:107], v[124:125], off
	v_mul_f32_e32 v109, v109, v109
	v_mul_f32_e32 v111, v111, v111
	v_mul_f32_e32 v115, v119, v119
	v_fmac_f32_e32 v109, v108, v108
	v_fmac_f32_e32 v111, v110, v110
	v_mul_f32_e32 v117, v117, v117
	v_fmac_f32_e32 v115, v118, v118
	v_add_f32_e32 v108, v109, v111
	v_fmac_f32_e32 v117, v116, v116
	v_add_f32_e32 v108, v115, v108
	v_add_f32_e32 v115, v117, v108
	s_waitcnt vmcnt(0)
	v_lshlrev_b32_e32 v108, 16, v104
	v_and_b32_e32 v109, 0xffff0000, v104
	v_lshlrev_b32_e32 v104, 16, v105
	v_and_b32_e32 v105, 0xffff0000, v105
	v_lshlrev_b32_e32 v110, 16, v106
	v_and_b32_e32 v111, 0xffff0000, v106
	v_lshlrev_b32_e32 v106, 16, v107
	v_and_b32_e32 v107, 0xffff0000, v107
	v_pk_add_f32 v[102:103], v[102:103], v[104:105]
	v_pk_add_f32 v[100:101], v[100:101], v[108:109]
	v_pk_add_f32 v[104:105], v[98:99], v[106:107]
	v_pk_add_f32 v[106:107], v[96:97], v[110:111]
	v_mul_f32_e32 v96, v101, v101
	v_mul_f32_e32 v97, v103, v103
	v_mul_f32_e32 v98, v107, v107
	v_fmac_f32_e32 v96, v100, v100
	v_fmac_f32_e32 v97, v102, v102
	v_mul_f32_e32 v99, v105, v105
	v_fmac_f32_e32 v98, v106, v106
	v_add_f32_e32 v96, v96, v97
	v_add_f32_e32 v96, v98, v96
	v_fmac_f32_e32 v99, v104, v104
	v_add_f32_e32 v96, v99, v96
	v_add_f32_e32 v96, v115, v96
	ds_bpermute_b32 v97, v120, v96
	v_cvt_pk_bf16_f32 v98, v100, v101
	v_cvt_pk_bf16_f32 v99, v102, v103
	v_cvt_pk_bf16_f32 v100, v106, v107
	v_cvt_pk_bf16_f32 v101, v104, v105
	s_waitcnt lgkmcnt(0)
	v_add_f32_e32 v96, v96, v97
	ds_bpermute_b32 v97, v114, v96
	v_lshlrev_b32_e32 v102, 1, v122
	buffer_store_dwordx4 v[98:101], v102, s[8:11], 0 offen
	s_and_saveexec_b64 s[40:41], s[4:5]
	s_cbranch_execz .Lpp5_527
	v_lshl_add_u64 v[98:99], v[112:113], 2, s[22:23]
	s_waitcnt lgkmcnt(0)
	v_add_f32_e32 v96, v96, v97
	global_atomic_add_f32 v[98:99], v96, off
; __device__ __forceinline__ unsigned cvt_pk_bf16(float lo, float hi) { f32x2_t v = {lo, hi}; bf16x2_t b = __builtin_convertvector(v, bf16x2_t); return __builtin_bit_cast(unsigned, b); }
;     __device__ __forceinline__ void operator()(const f32x4 (&acc)[2][2][4][2], const Unit& u, int wr, int wc, int fr, int fq) const {
;     ...
;             for (int m = 0; m < 4; ++m) { const int row = u.pm * BM + ai * HALF + wr * 64 + m * 16 + fr; const size_t off = (size_t)row * ldc + col0; float ss = 0.f;
; #pragma unroll
;                 for (int bj = 0; bj < 2; ++bj) { const size_t o2 = off + bj * HALF; f32x4 b0, b1;
;                     if (MODE == 0) { b0 = *(const f32x4*)(basef + o2); b1 = *(const f32x4*)(basef + o2 + 4); }
;                     else { const u32x4 w = *(const u32x4*)(xb + o2);
;                         b0 = (f32x4){__uint_as_float(w.x << 16), __uint_as_float(w.x & 0xffff0000u), __uint_as_float(w.y << 16), __uint_as_float(w.y & 0xffff0000u)};
;                         b1 = (f32x4){__uint_as_float(w.z << 16), __uint_as_float(w.z & 0xffff0000u), __uint_as_float(w.w << 16), __uint_as_float(w.w & 0xffff0000u)}; }
;                     const f32x4 v0 = b0 + acc[ai][bj][m][0], v1 = b1 + acc[ai][bj][m][1];
;                     if (MODE == 2) { *(f32x4*)(outf + o2) = v0; *(f32x4*)(outf + o2 + 4) = v1; }
;                     else { ss += (v0[0] * v0[0] + v0[1] * v0[1]) + (v0[2] * v0[2] + v0[3] * v0[3]) + (v1[0] * v1[0] + v1[1] * v1[1]) + (v1[2] * v1[2] + v1[3] * v1[3]);
;                         u32x4 w; w.x = cvt_pk_bf16(v0[0], v0[1]); w.y = cvt_pk_bf16(v0[2], v0[3]); w.z = cvt_pk_bf16(v1[0], v1[1]); w.w = cvt_pk_bf16(v1[2], v1[3]);
;                         __builtin_amdgcn_raw_buffer_store_b128(w, rsrc, (unsigned)(o2 * 2), 0, 16); } }
;                 if (MODE != 2) { ss += __shfl_xor(ss, 16); ss += __shfl_xor(ss, 32); if (fq == 0) atomicAdd(rowsq + row, ss); } }
.Lpp5_527:
	s_or_b64 exec, exec, s[40:41]
	v_or_b32_e32 v96, 32, v148
	s_waitcnt lgkmcnt(0)
	v_ashrrev_i32_e32 v97, 31, v96
	v_lshlrev_b64 v[98:99], 10, v[96:97]
	v_lshl_add_u64 v[102:103], v[98:99], 0, v[146:147]
	v_lshl_add_u64 v[98:99], v[102:103], 1, s[96:97]
	global_load_dwordx4 v[98:101], v[98:99], off
	v_lshlrev_b32_e32 v110, 1, v102
	v_or_b32_e32 v102, 0x80, v102
	v_lshl_add_u64 v[104:105], v[102:103], 1, s[96:97]
	s_waitcnt vmcnt(0)
	v_lshlrev_b32_e32 v106, 16, v98
	v_and_b32_e32 v107, 0xffff0000, v98
	v_lshlrev_b32_e32 v98, 16, v99
	v_and_b32_e32 v99, 0xffff0000, v99
	v_lshlrev_b32_e32 v108, 16, v100
	v_and_b32_e32 v109, 0xffff0000, v100
	v_lshlrev_b32_e32 v100, 16, v101
	v_and_b32_e32 v101, 0xffff0000, v101
	v_pk_add_f32 v[94:95], v[94:95], v[98:99]
	v_pk_add_f32 v[92:93], v[92:93], v[106:107]
	v_pk_add_f32 v[98:99], v[90:91], v[100:101]
	v_pk_add_f32 v[100:101], v[88:89], v[108:109]
	v_cvt_pk_bf16_f32 v88, v92, v93
	v_cvt_pk_bf16_f32 v89, v94, v95
	v_cvt_pk_bf16_f32 v90, v100, v101
	v_cvt_pk_bf16_f32 v91, v98, v99
	buffer_store_dwordx4 v[88:91], v110, s[8:11], 0 offen
	global_load_dwordx4 v[88:91], v[104:105], off
	v_mul_f32_e32 v93, v93, v93
	v_mul_f32_e32 v95, v95, v95
	v_mul_f32_e32 v101, v101, v101
	v_fmac_f32_e32 v93, v92, v92
	v_fmac_f32_e32 v95, v94, v94
	v_mul_f32_e32 v99, v99, v99
	v_fmac_f32_e32 v101, v100, v100
	v_add_f32_e32 v92, v93, v95
	v_fmac_f32_e32 v99, v98, v98
	v_add_f32_e32 v92, v101, v92
	v_add_f32_e32 v98, v99, v92
	s_waitcnt vmcnt(0)
	v_lshlrev_b32_e32 v92, 16, v88
	v_and_b32_e32 v93, 0xffff0000, v88
	v_lshlrev_b32_e32 v88, 16, v89
	v_and_b32_e32 v89, 0xffff0000, v89
	v_lshlrev_b32_e32 v94, 16, v90
	v_and_b32_e32 v95, 0xffff0000, v90
	v_lshlrev_b32_e32 v90, 16, v91
	v_and_b32_e32 v91, 0xffff0000, v91
	v_pk_add_f32 v[86:87], v[86:87], v[88:89]
	v_pk_add_f32 v[84:85], v[84:85], v[92:93]
	v_pk_add_f32 v[88:89], v[82:83], v[90:91]
	v_pk_add_f32 v[90:91], v[80:81], v[94:95]
	v_mul_f32_e32 v80, v85, v85
	v_mul_f32_e32 v81, v87, v87
	v_mul_f32_e32 v82, v91, v91
	v_fmac_f32_e32 v80, v84, v84
	v_fmac_f32_e32 v81, v86, v86
	v_mul_f32_e32 v83, v89, v89
	v_fmac_f32_e32 v82, v90, v90
	v_add_f32_e32 v80, v80, v81
	v_add_f32_e32 v80, v82, v80
	v_fmac_f32_e32 v83, v88, v88
	v_add_f32_e32 v80, v83, v80
	v_add_f32_e32 v80, v98, v80
	ds_bpermute_b32 v81, v120, v80
	v_cvt_pk_bf16_f32 v82, v84, v85
	v_cvt_pk_bf16_f32 v83, v86, v87
	v_cvt_pk_bf16_f32 v84, v90, v91
	v_cvt_pk_bf16_f32 v85, v88, v89
	s_waitcnt lgkmcnt(0)
	v_add_f32_e32 v80, v80, v81
	ds_bpermute_b32 v81, v114, v80
	v_lshlrev_b32_e32 v86, 1, v102
	buffer_store_dwordx4 v[82:85], v86, s[8:11], 0 offen
	s_and_saveexec_b64 s[40:41], s[4:5]
	s_cbranch_execz .Lpp5_529
	v_lshl_add_u64 v[82:83], v[96:97], 2, s[22:23]
	s_waitcnt lgkmcnt(0)
	v_add_f32_e32 v80, v80, v81
	global_atomic_add_f32 v[82:83], v80, off
.Lpp5_529:
	s_or_b64 exec, exec, s[40:41]
	v_or_b32_e32 v80, 48, v148
	s_waitcnt lgkmcnt(0)
	v_ashrrev_i32_e32 v81, 31, v80
	v_lshlrev_b64 v[82:83], 10, v[80:81]
	v_lshl_add_u64 v[86:87], v[82:83], 0, v[146:147]
	v_lshl_add_u64 v[82:83], v[86:87], 1, s[96:97]
	global_load_dwordx4 v[82:85], v[82:83], off
	v_lshlrev_b32_e32 v94, 1, v86
	v_or_b32_e32 v86, 0x80, v86
	v_lshl_add_u64 v[88:89], v[86:87], 1, s[96:97]
	s_waitcnt vmcnt(0)
	v_lshlrev_b32_e32 v90, 16, v82
	v_and_b32_e32 v91, 0xffff0000, v82
	v_lshlrev_b32_e32 v82, 16, v83
	v_and_b32_e32 v83, 0xffff0000, v83
	v_lshlrev_b32_e32 v92, 16, v84
	v_and_b32_e32 v93, 0xffff0000, v84
	v_lshlrev_b32_e32 v84, 16, v85
	v_and_b32_e32 v85, 0xffff0000, v85
	v_pk_add_f32 v[78:79], v[78:79], v[82:83]
	v_pk_add_f32 v[76:77], v[76:77], v[90:91]
	v_pk_add_f32 v[82:83], v[74:75], v[84:85]
	v_pk_add_f32 v[84:85], v[72:73], v[92:93]
	v_cvt_pk_bf16_f32 v72, v76, v77
	v_cvt_pk_bf16_f32 v73, v78, v79
	v_cvt_pk_bf16_f32 v74, v84, v85
	v_cvt_pk_bf16_f32 v75, v82, v83
	buffer_store_dwordx4 v[72:75], v94, s[8:11], 0 offen
	global_load_dwordx4 v[72:75], v[88:89], off
	v_mul_f32_e32 v77, v77, v77
	v_mul_f32_e32 v79, v79, v79
	v_mul_f32_e32 v85, v85, v85
	v_fmac_f32_e32 v77, v76, v76
	v_fmac_f32_e32 v79, v78, v78
	v_mul_f32_e32 v83, v83, v83
	v_fmac_f32_e32 v85, v84, v84
	v_add_f32_e32 v76, v77, v79
	v_fmac_f32_e32 v83, v82, v82
	v_add_f32_e32 v76, v85, v76
	v_add_f32_e32 v82, v83, v76
	s_waitcnt vmcnt(0)
	v_lshlrev_b32_e32 v76, 16, v72
	v_and_b32_e32 v77, 0xffff0000, v72
	v_lshlrev_b32_e32 v72, 16, v73
	v_and_b32_e32 v73, 0xffff0000, v73
	v_lshlrev_b32_e32 v78, 16, v74
	v_and_b32_e32 v79, 0xffff0000, v74
	v_lshlrev_b32_e32 v74, 16, v75
	v_and_b32_e32 v75, 0xffff0000, v75
	v_pk_add_f32 v[70:71], v[70:71], v[72:73]
	v_pk_add_f32 v[68:69], v[68:69], v[76:77]
	v_pk_add_f32 v[72:73], v[66:67], v[74:75]
	v_pk_add_f32 v[74:75], v[64:65], v[78:79]
	v_mul_f32_e32 v64, v69, v69
	v_mul_f32_e32 v65, v71, v71
	v_mul_f32_e32 v66, v75, v75
	v_fmac_f32_e32 v64, v68, v68
	v_fmac_f32_e32 v65, v70, v70
	v_mul_f32_e32 v67, v73, v73
	v_fmac_f32_e32 v66, v74, v74
	v_add_f32_e32 v64, v64, v65
	v_add_f32_e32 v64, v66, v64
	v_fmac_f32_e32 v67, v72, v72
	v_add_f32_e32 v64, v67, v64
	v_add_f32_e32 v64, v82, v64
	ds_bpermute_b32 v65, v120, v64
	v_cvt_pk_bf16_f32 v66, v68, v69
	v_cvt_pk_bf16_f32 v67, v70, v71
	v_cvt_pk_bf16_f32 v68, v74, v75
	v_cvt_pk_bf16_f32 v69, v72, v73
	s_waitcnt lgkmcnt(0)
	v_add_f32_e32 v64, v64, v65
	ds_bpermute_b32 v65, v114, v64
	v_lshlrev_b32_e32 v70, 1, v86
	buffer_store_dwordx4 v[66:69], v70, s[8:11], 0 offen
	s_and_saveexec_b64 s[40:41], s[4:5]
	s_cbranch_execz .Lpp5_531
	v_lshl_add_u64 v[66:67], v[80:81], 2, s[22:23]
	s_waitcnt lgkmcnt(0)
	v_add_f32_e32 v64, v64, v65
	global_atomic_add_f32 v[66:67], v64, off
; __device__ __forceinline__ unsigned cvt_pk_bf16(float lo, float hi) { f32x2_t v = {lo, hi}; bf16x2_t b = __builtin_convertvector(v, bf16x2_t); return __builtin_bit_cast(unsigned, b); }
;     __device__ __forceinline__ void operator()(const f32x4 (&acc)[2][2][4][2], const Unit& u, int wr, int wc, int fr, int fq) const {
;     ...
;             for (int m = 0; m < 4; ++m) { const int row = u.pm * BM + ai * HALF + wr * 64 + m * 16 + fr; const size_t off = (size_t)row * ldc + col0; float ss = 0.f;
; #pragma unroll
;                 for (int bj = 0; bj < 2; ++bj) { const size_t o2 = off + bj * HALF; f32x4 b0, b1;
;                     if (MODE == 0) { b0 = *(const f32x4*)(basef + o2); b1 = *(const f32x4*)(basef + o2 + 4); }
;                     else { const u32x4 w = *(const u32x4*)(xb + o2);
;                         b0 = (f32x4){__uint_as_float(w.x << 16), __uint_as_float(w.x & 0xffff0000u), __uint_as_float(w.y << 16), __uint_as_float(w.y & 0xffff0000u)};
;                         b1 = (f32x4){__uint_as_float(w.z << 16), __uint_as_float(w.z & 0xffff0000u), __uint_as_float(w.w << 16), __uint_as_float(w.w & 0xffff0000u)}; }
;                     const f32x4 v0 = b0 + acc[ai][bj][m][0], v1 = b1 + acc[ai][bj][m][1];
;                     if (MODE == 2) { *(f32x4*)(outf + o2) = v0; *(f32x4*)(outf + o2 + 4) = v1; }
;                     else { ss += (v0[0] * v0[0] + v0[1] * v0[1]) + (v0[2] * v0[2] + v0[3] * v0[3]) + (v1[0] * v1[0] + v1[1] * v1[1]) + (v1[2] * v1[2] + v1[3] * v1[3]);
;                         u32x4 w; w.x = cvt_pk_bf16(v0[0], v0[1]); w.y = cvt_pk_bf16(v0[2], v0[3]); w.z = cvt_pk_bf16(v1[0], v1[1]); w.w = cvt_pk_bf16(v1[2], v1[3]);
;                         __builtin_amdgcn_raw_buffer_store_b128(w, rsrc, (unsigned)(o2 * 2), 0, 16); } }
;                 if (MODE != 2) { ss += __shfl_xor(ss, 16); ss += __shfl_xor(ss, 32); if (fq == 0) atomicAdd(rowsq + row, ss); } }
.Lpp5_531:
	s_or_b64 exec, exec, s[40:41]
	v_add_u32_e32 v64, 0x80, v148
	s_waitcnt lgkmcnt(0)
	v_ashrrev_i32_e32 v65, 31, v64
	v_lshlrev_b64 v[66:67], 10, v[64:65]
	v_lshl_add_u64 v[70:71], v[66:67], 0, v[146:147]
	v_lshl_add_u64 v[66:67], v[70:71], 1, s[96:97]
	global_load_dwordx4 v[66:69], v[66:67], off
	v_lshlrev_b32_e32 v78, 1, v70
	v_or_b32_e32 v70, 0x80, v70
	v_lshl_add_u64 v[72:73], v[70:71], 1, s[96:97]
	s_waitcnt vmcnt(0)
	v_lshlrev_b32_e32 v74, 16, v66
	v_and_b32_e32 v75, 0xffff0000, v66
	v_lshlrev_b32_e32 v66, 16, v67
	v_and_b32_e32 v67, 0xffff0000, v67
	v_lshlrev_b32_e32 v76, 16, v68
	v_and_b32_e32 v77, 0xffff0000, v68
	v_lshlrev_b32_e32 v68, 16, v69
	v_and_b32_e32 v69, 0xffff0000, v69
	v_pk_add_f32 v[62:63], v[62:63], v[66:67]
	v_pk_add_f32 v[60:61], v[60:61], v[74:75]
	v_pk_add_f32 v[66:67], v[58:59], v[68:69]
	v_pk_add_f32 v[68:69], v[56:57], v[76:77]
	v_cvt_pk_bf16_f32 v56, v60, v61
	v_cvt_pk_bf16_f32 v57, v62, v63
	v_cvt_pk_bf16_f32 v58, v68, v69
	v_cvt_pk_bf16_f32 v59, v66, v67
	buffer_store_dwordx4 v[56:59], v78, s[8:11], 0 offen
	global_load_dwordx4 v[56:59], v[72:73], off
	v_mul_f32_e32 v61, v61, v61
	v_mul_f32_e32 v63, v63, v63
	v_mul_f32_e32 v69, v69, v69
	v_fmac_f32_e32 v61, v60, v60
	v_fmac_f32_e32 v63, v62, v62
	v_mul_f32_e32 v67, v67, v67
	v_fmac_f32_e32 v69, v68, v68
	v_add_f32_e32 v60, v61, v63
	v_fmac_f32_e32 v67, v66, v66
	v_add_f32_e32 v60, v69, v60
	v_add_f32_e32 v66, v67, v60
	s_waitcnt vmcnt(0)
	v_lshlrev_b32_e32 v60, 16, v56
	v_and_b32_e32 v61, 0xffff0000, v56
	v_lshlrev_b32_e32 v56, 16, v57
	v_and_b32_e32 v57, 0xffff0000, v57
	v_lshlrev_b32_e32 v62, 16, v58
	v_and_b32_e32 v63, 0xffff0000, v58
	v_lshlrev_b32_e32 v58, 16, v59
	v_and_b32_e32 v59, 0xffff0000, v59
	v_pk_add_f32 v[54:55], v[54:55], v[56:57]
	v_pk_add_f32 v[52:53], v[52:53], v[60:61]
	v_pk_add_f32 v[56:57], v[50:51], v[58:59]
	v_pk_add_f32 v[58:59], v[48:49], v[62:63]
	v_mul_f32_e32 v48, v53, v53
	v_mul_f32_e32 v49, v55, v55
	v_mul_f32_e32 v50, v59, v59
	v_fmac_f32_e32 v48, v52, v52
	v_fmac_f32_e32 v49, v54, v54
	v_mul_f32_e32 v51, v57, v57
	v_fmac_f32_e32 v50, v58, v58
	v_add_f32_e32 v48, v48, v49
	v_add_f32_e32 v48, v50, v48
	v_fmac_f32_e32 v51, v56, v56
	v_add_f32_e32 v48, v51, v48
	v_add_f32_e32 v48, v66, v48
	ds_bpermute_b32 v49, v120, v48
	v_cvt_pk_bf16_f32 v50, v52, v53
	v_cvt_pk_bf16_f32 v51, v54, v55
	v_cvt_pk_bf16_f32 v52, v58, v59
	v_cvt_pk_bf16_f32 v53, v56, v57
	s_waitcnt lgkmcnt(0)
	v_add_f32_e32 v48, v48, v49
	ds_bpermute_b32 v49, v114, v48
	v_lshlrev_b32_e32 v54, 1, v70
	buffer_store_dwordx4 v[50:53], v54, s[8:11], 0 offen
	s_and_saveexec_b64 s[40:41], s[4:5]
	s_cbranch_execz .Lpp5_533
	v_lshl_add_u64 v[50:51], v[64:65], 2, s[22:23]
	s_waitcnt lgkmcnt(0)
	v_add_f32_e32 v48, v48, v49
	global_atomic_add_f32 v[50:51], v48, off
.Lpp5_533:
	s_or_b64 exec, exec, s[40:41]
	v_add_u32_e32 v48, 0x90, v148
	s_waitcnt lgkmcnt(0)
	v_ashrrev_i32_e32 v49, 31, v48
	v_lshlrev_b64 v[50:51], 10, v[48:49]
	v_lshl_add_u64 v[54:55], v[50:51], 0, v[146:147]
	v_lshl_add_u64 v[50:51], v[54:55], 1, s[96:97]
	global_load_dwordx4 v[50:53], v[50:51], off
	v_lshlrev_b32_e32 v62, 1, v54
	v_or_b32_e32 v54, 0x80, v54
	v_lshl_add_u64 v[56:57], v[54:55], 1, s[96:97]
	s_waitcnt vmcnt(0)
	v_lshlrev_b32_e32 v58, 16, v50
	v_and_b32_e32 v59, 0xffff0000, v50
	v_lshlrev_b32_e32 v50, 16, v51
	v_and_b32_e32 v51, 0xffff0000, v51
	v_lshlrev_b32_e32 v60, 16, v52
	v_and_b32_e32 v61, 0xffff0000, v52
	v_lshlrev_b32_e32 v52, 16, v53
	v_and_b32_e32 v53, 0xffff0000, v53
	v_pk_add_f32 v[46:47], v[46:47], v[50:51]
	v_pk_add_f32 v[44:45], v[44:45], v[58:59]
	v_pk_add_f32 v[50:51], v[42:43], v[52:53]
	v_pk_add_f32 v[52:53], v[40:41], v[60:61]
	v_cvt_pk_bf16_f32 v40, v44, v45
	v_cvt_pk_bf16_f32 v41, v46, v47
	v_cvt_pk_bf16_f32 v42, v52, v53
	v_cvt_pk_bf16_f32 v43, v50, v51
	buffer_store_dwordx4 v[40:43], v62, s[8:11], 0 offen
	global_load_dwordx4 v[40:43], v[56:57], off
	v_mul_f32_e32 v45, v45, v45
	v_mul_f32_e32 v47, v47, v47
	v_mul_f32_e32 v53, v53, v53
	v_fmac_f32_e32 v45, v44, v44
	v_fmac_f32_e32 v47, v46, v46
	v_mul_f32_e32 v51, v51, v51
	v_fmac_f32_e32 v53, v52, v52
	v_add_f32_e32 v44, v45, v47
	v_fmac_f32_e32 v51, v50, v50
	v_add_f32_e32 v44, v53, v44
	v_add_f32_e32 v50, v51, v44
	s_waitcnt vmcnt(0)
	v_lshlrev_b32_e32 v44, 16, v40
	v_and_b32_e32 v45, 0xffff0000, v40
	v_lshlrev_b32_e32 v40, 16, v41
	v_and_b32_e32 v41, 0xffff0000, v41
	v_lshlrev_b32_e32 v46, 16, v42
	v_and_b32_e32 v47, 0xffff0000, v42
	v_lshlrev_b32_e32 v42, 16, v43
	v_and_b32_e32 v43, 0xffff0000, v43
	v_pk_add_f32 v[38:39], v[38:39], v[40:41]
	v_pk_add_f32 v[36:37], v[36:37], v[44:45]
	v_pk_add_f32 v[40:41], v[34:35], v[42:43]
	v_pk_add_f32 v[42:43], v[32:33], v[46:47]
	v_mul_f32_e32 v32, v37, v37
	v_mul_f32_e32 v33, v39, v39
	v_mul_f32_e32 v34, v43, v43
	v_fmac_f32_e32 v32, v36, v36
	v_fmac_f32_e32 v33, v38, v38
	v_mul_f32_e32 v35, v41, v41
	v_fmac_f32_e32 v34, v42, v42
	v_add_f32_e32 v32, v32, v33
	v_add_f32_e32 v32, v34, v32
	v_fmac_f32_e32 v35, v40, v40
	v_add_f32_e32 v32, v35, v32
	v_add_f32_e32 v32, v50, v32
	ds_bpermute_b32 v33, v120, v32
	v_cvt_pk_bf16_f32 v34, v36, v37
	v_cvt_pk_bf16_f32 v35, v38, v39
	v_cvt_pk_bf16_f32 v36, v42, v43
	v_cvt_pk_bf16_f32 v37, v40, v41
	s_waitcnt lgkmcnt(0)
	v_add_f32_e32 v32, v32, v33
	ds_bpermute_b32 v33, v114, v32
	v_lshlrev_b32_e32 v38, 1, v54
	buffer_store_dwordx4 v[34:37], v38, s[8:11], 0 offen
	s_and_saveexec_b64 s[40:41], s[4:5]
	s_cbranch_execz .Lpp5_535
	v_lshl_add_u64 v[34:35], v[48:49], 2, s[22:23]
	s_waitcnt lgkmcnt(0)
	v_add_f32_e32 v32, v32, v33
	global_atomic_add_f32 v[34:35], v32, off
; __device__ __forceinline__ unsigned cvt_pk_bf16(float lo, float hi) { f32x2_t v = {lo, hi}; bf16x2_t b = __builtin_convertvector(v, bf16x2_t); return __builtin_bit_cast(unsigned, b); }
;     __device__ __forceinline__ void operator()(const f32x4 (&acc)[2][2][4][2], const Unit& u, int wr, int wc, int fr, int fq) const {
;     ...
;             for (int m = 0; m < 4; ++m) { const int row = u.pm * BM + ai * HALF + wr * 64 + m * 16 + fr; const size_t off = (size_t)row * ldc + col0; float ss = 0.f;
; #pragma unroll
;                 for (int bj = 0; bj < 2; ++bj) { const size_t o2 = off + bj * HALF; f32x4 b0, b1;
;                     if (MODE == 0) { b0 = *(const f32x4*)(basef + o2); b1 = *(const f32x4*)(basef + o2 + 4); }
;                     else { const u32x4 w = *(const u32x4*)(xb + o2);
;                         b0 = (f32x4){__uint_as_float(w.x << 16), __uint_as_float(w.x & 0xffff0000u), __uint_as_float(w.y << 16), __uint_as_float(w.y & 0xffff0000u)};
;                         b1 = (f32x4){__uint_as_float(w.z << 16), __uint_as_float(w.z & 0xffff0000u), __uint_as_float(w.w << 16), __uint_as_float(w.w & 0xffff0000u)}; }
;                     const f32x4 v0 = b0 + acc[ai][bj][m][0], v1 = b1 + acc[ai][bj][m][1];
;                     if (MODE == 2) { *(f32x4*)(outf + o2) = v0; *(f32x4*)(outf + o2 + 4) = v1; }
;                     else { ss += (v0[0] * v0[0] + v0[1] * v0[1]) + (v0[2] * v0[2] + v0[3] * v0[3]) + (v1[0] * v1[0] + v1[1] * v1[1]) + (v1[2] * v1[2] + v1[3] * v1[3]);
;                         u32x4 w; w.x = cvt_pk_bf16(v0[0], v0[1]); w.y = cvt_pk_bf16(v0[2], v0[3]); w.z = cvt_pk_bf16(v1[0], v1[1]); w.w = cvt_pk_bf16(v1[2], v1[3]);
;                         __builtin_amdgcn_raw_buffer_store_b128(w, rsrc, (unsigned)(o2 * 2), 0, 16); } }
;                 if (MODE != 2) { ss += __shfl_xor(ss, 16); ss += __shfl_xor(ss, 32); if (fq == 0) atomicAdd(rowsq + row, ss); } }
.Lpp5_535:
	s_or_b64 exec, exec, s[40:41]
	v_add_u32_e32 v32, 0xa0, v148
	s_waitcnt lgkmcnt(0)
	v_ashrrev_i32_e32 v33, 31, v32
	v_lshlrev_b64 v[34:35], 10, v[32:33]
	v_lshl_add_u64 v[38:39], v[34:35], 0, v[146:147]
	v_lshl_add_u64 v[34:35], v[38:39], 1, s[96:97]
	global_load_dwordx4 v[34:37], v[34:35], off
	v_lshlrev_b32_e32 v46, 1, v38
	v_or_b32_e32 v38, 0x80, v38
	v_lshl_add_u64 v[40:41], v[38:39], 1, s[96:97]
	s_waitcnt vmcnt(0)
	v_lshlrev_b32_e32 v42, 16, v34
	v_and_b32_e32 v43, 0xffff0000, v34
	v_lshlrev_b32_e32 v34, 16, v35
	v_and_b32_e32 v35, 0xffff0000, v35
	v_lshlrev_b32_e32 v44, 16, v36
	v_and_b32_e32 v45, 0xffff0000, v36
	v_lshlrev_b32_e32 v36, 16, v37
	v_and_b32_e32 v37, 0xffff0000, v37
	v_pk_add_f32 v[30:31], v[30:31], v[34:35]
	v_pk_add_f32 v[28:29], v[28:29], v[42:43]
	v_pk_add_f32 v[34:35], v[26:27], v[36:37]
	v_pk_add_f32 v[36:37], v[24:25], v[44:45]
	v_cvt_pk_bf16_f32 v24, v28, v29
	v_cvt_pk_bf16_f32 v25, v30, v31
	v_cvt_pk_bf16_f32 v26, v36, v37
	v_cvt_pk_bf16_f32 v27, v34, v35
	buffer_store_dwordx4 v[24:27], v46, s[8:11], 0 offen
	global_load_dwordx4 v[24:27], v[40:41], off
	v_mul_f32_e32 v29, v29, v29
	v_mul_f32_e32 v31, v31, v31
	v_mul_f32_e32 v37, v37, v37
	v_fmac_f32_e32 v29, v28, v28
	v_fmac_f32_e32 v31, v30, v30
	v_mul_f32_e32 v35, v35, v35
	v_fmac_f32_e32 v37, v36, v36
	v_add_f32_e32 v28, v29, v31
	v_fmac_f32_e32 v35, v34, v34
	v_add_f32_e32 v28, v37, v28
	v_add_f32_e32 v34, v35, v28
	s_waitcnt vmcnt(0)
	v_lshlrev_b32_e32 v28, 16, v24
	v_and_b32_e32 v29, 0xffff0000, v24
	v_lshlrev_b32_e32 v24, 16, v25
	v_and_b32_e32 v25, 0xffff0000, v25
	v_lshlrev_b32_e32 v30, 16, v26
	v_and_b32_e32 v31, 0xffff0000, v26
	v_lshlrev_b32_e32 v26, 16, v27
	v_and_b32_e32 v27, 0xffff0000, v27
	v_pk_add_f32 v[22:23], v[22:23], v[24:25]
	v_pk_add_f32 v[20:21], v[20:21], v[28:29]
	v_pk_add_f32 v[24:25], v[18:19], v[26:27]
	v_pk_add_f32 v[26:27], v[16:17], v[30:31]
	v_mul_f32_e32 v16, v21, v21
	v_mul_f32_e32 v17, v23, v23
	v_mul_f32_e32 v18, v27, v27
	v_fmac_f32_e32 v16, v20, v20
	v_fmac_f32_e32 v17, v22, v22
	v_mul_f32_e32 v19, v25, v25
	v_fmac_f32_e32 v18, v26, v26
	v_add_f32_e32 v16, v16, v17
	v_add_f32_e32 v16, v18, v16
	v_fmac_f32_e32 v19, v24, v24
	v_add_f32_e32 v16, v19, v16
	v_add_f32_e32 v16, v34, v16
	ds_bpermute_b32 v17, v120, v16
	v_cvt_pk_bf16_f32 v18, v20, v21
	v_cvt_pk_bf16_f32 v19, v22, v23
	v_cvt_pk_bf16_f32 v20, v26, v27
	v_cvt_pk_bf16_f32 v21, v24, v25
	s_waitcnt lgkmcnt(0)
	v_add_f32_e32 v16, v16, v17
	ds_bpermute_b32 v17, v114, v16
	v_lshlrev_b32_e32 v22, 1, v38
	buffer_store_dwordx4 v[18:21], v22, s[8:11], 0 offen
	s_and_saveexec_b64 s[40:41], s[4:5]
	s_cbranch_execz .Lpp5_537
	v_lshl_add_u64 v[18:19], v[32:33], 2, s[22:23]
	s_waitcnt lgkmcnt(0)
	v_add_f32_e32 v16, v16, v17
	global_atomic_add_f32 v[18:19], v16, off
.Lpp5_537:
	s_or_b64 exec, exec, s[40:41]
	v_add_u32_e32 v16, 0xb0, v148
	s_waitcnt lgkmcnt(0)
	v_ashrrev_i32_e32 v17, 31, v16
	v_lshlrev_b64 v[18:19], 10, v[16:17]
	v_lshl_add_u64 v[22:23], v[18:19], 0, v[146:147]
	v_lshl_add_u64 v[18:19], v[22:23], 1, s[96:97]
	global_load_dwordx4 v[18:21], v[18:19], off
	v_lshlrev_b32_e32 v30, 1, v22
	v_or_b32_e32 v22, 0x80, v22
	v_lshl_add_u64 v[24:25], v[22:23], 1, s[96:97]
	s_waitcnt vmcnt(0)
	v_lshlrev_b32_e32 v26, 16, v18
	v_and_b32_e32 v27, 0xffff0000, v18
	v_lshlrev_b32_e32 v18, 16, v19
	v_and_b32_e32 v19, 0xffff0000, v19
	v_lshlrev_b32_e32 v28, 16, v20
	v_and_b32_e32 v29, 0xffff0000, v20
	v_lshlrev_b32_e32 v20, 16, v21
	v_and_b32_e32 v21, 0xffff0000, v21
	v_pk_add_f32 v[14:15], v[14:15], v[18:19]
	v_pk_add_f32 v[12:13], v[12:13], v[26:27]
	v_pk_add_f32 v[18:19], v[10:11], v[20:21]
	v_pk_add_f32 v[20:21], v[8:9], v[28:29]
	v_cvt_pk_bf16_f32 v8, v12, v13
	v_cvt_pk_bf16_f32 v9, v14, v15
	v_cvt_pk_bf16_f32 v10, v20, v21
	v_cvt_pk_bf16_f32 v11, v18, v19
	buffer_store_dwordx4 v[8:11], v30, s[8:11], 0 offen
	global_load_dwordx4 v[8:11], v[24:25], off
	v_mul_f32_e32 v13, v13, v13
	v_mul_f32_e32 v15, v15, v15
	v_mul_f32_e32 v21, v21, v21
	v_fmac_f32_e32 v13, v12, v12
	v_fmac_f32_e32 v15, v14, v14
	v_mul_f32_e32 v19, v19, v19
	v_fmac_f32_e32 v21, v20, v20
	v_add_f32_e32 v12, v13, v15
	v_fmac_f32_e32 v19, v18, v18
	v_add_f32_e32 v12, v21, v12
	v_add_f32_e32 v18, v19, v12
	s_waitcnt vmcnt(0)
	v_lshlrev_b32_e32 v12, 16, v8
	v_and_b32_e32 v13, 0xffff0000, v8
	v_lshlrev_b32_e32 v8, 16, v9
	v_and_b32_e32 v9, 0xffff0000, v9
	v_lshlrev_b32_e32 v14, 16, v10
	v_and_b32_e32 v15, 0xffff0000, v10
	v_lshlrev_b32_e32 v10, 16, v11
	v_and_b32_e32 v11, 0xffff0000, v11
	v_pk_add_f32 v[6:7], v[6:7], v[8:9]
	v_pk_add_f32 v[4:5], v[4:5], v[12:13]
	v_pk_add_f32 v[8:9], v[2:3], v[10:11]
	v_pk_add_f32 v[10:11], v[0:1], v[14:15]
	v_mul_f32_e32 v0, v5, v5
	v_mul_f32_e32 v1, v7, v7
	v_mul_f32_e32 v2, v11, v11
	v_fmac_f32_e32 v0, v4, v4
	v_fmac_f32_e32 v1, v6, v6
	v_mul_f32_e32 v3, v9, v9
	v_fmac_f32_e32 v2, v10, v10
	v_add_f32_e32 v0, v0, v1
	v_add_f32_e32 v0, v2, v0
	v_fmac_f32_e32 v3, v8, v8
	v_add_f32_e32 v0, v3, v0
	v_add_f32_e32 v0, v18, v0
	ds_bpermute_b32 v1, v120, v0
	v_cvt_pk_bf16_f32 v2, v4, v5
	v_cvt_pk_bf16_f32 v3, v6, v7
	v_cvt_pk_bf16_f32 v4, v10, v11
	v_cvt_pk_bf16_f32 v5, v8, v9
	s_waitcnt lgkmcnt(0)
	v_add_f32_e32 v0, v0, v1
	ds_bpermute_b32 v1, v114, v0
	v_lshlrev_b32_e32 v6, 1, v22
	buffer_store_dwordx4 v[2:5], v6, s[8:11], 0 offen
	s_and_saveexec_b64 s[40:41], s[4:5]
	s_cbranch_execz .Lpp5_539
	v_lshl_add_u64 v[2:3], v[16:17], 2, s[22:23]
	s_waitcnt lgkmcnt(0)
	v_add_f32_e32 v0, v0, v1
	global_atomic_add_f32 v[2:3], v0, off

; #define PG8_BAR __builtin_amdgcn_s_barrier()
; template <class Epi, class Sched, bool ALIGN_EPI = false, bool SP2 = false>
; __device__ __forceinline__ void gemm_phase(PG8_LAS unsigned char* lds, const Gemm g, const Sched& S, const Epi& E) {
;     ...
;         if constexpr (!Epi::AFTER_DRAIN) { E(acc, cur, wr, wc, fr, fq); S.done(cur); }
;         if (!has_next) break;
; #pragma unroll
;         for (int a = 0; a < 2; ++a)
; #pragma unroll
;             for (int b = 0; b < 2; ++b)
; #pragma unroll
;                 for (int m = 0; m < 4; ++m)
; #pragma unroll
;                     for (int n = 0; n < 2; ++n) acc[a][b][m][n] = (f32x4){0.f, 0.f, 0.f, 0.f};
;         cur = nxt; cA = nA; cB = nB; ++ui;
;         if constexpr (ALIGN_EPI) { if (wr == 1) PG8_BAR; }
;     }
.Lpp5_done:
	s_andn2_b64 vcc, exec, s[6:7]
	s_mov_b64 s[6:7], -1
	s_cbranch_vccnz .LBB0_512
	s_andn2_b64 vcc, exec, s[18:19]
	s_cbranch_vccnz .LBB0_511
	s_barrier
	s_branch .LBB0_511

; __device__ __forceinline__ unsigned cvt_pk_bf16(float lo, float hi) { f32x2_t v = {lo, hi}; bf16x2_t b = __builtin_convertvector(v, bf16x2_t); return __builtin_bit_cast(unsigned, b); }
;     __device__ __forceinline__ void operator()(const f32x4 (&acc)[2][2][4][2], const Unit& u, int wr, int wc, int fr, int fq) const {
;         const int row0 = u.pm * BM + wr * 64 + fr; const int col0 = u.pn * BM + wc * 32 + 8 * fq;
;         const __amdgpu_buffer_rsrc_t rsrc = __builtin_amdgcn_make_buffer_rsrc((void*)O, (short)0, 16384 * ldc * 2, 0x00020000);
; #pragma unroll
;         for (int ai = 0; ai < 2; ++ai)
; #pragma unroll
;             for (int m = 0; m < 4; ++m) { const int row = row0 + ai * HALF + m * 16;
;                 const float rs = rowsq ? rsqrtf(rowsq[row] * (1.0f / 1024.0f) + 1e-6f) : 1.0f;
; #pragma unroll
;                 for (int bj = 0; bj < 2; ++bj) { f32x4 v0 = acc[ai][bj][m][0] * rs, v1 = acc[ai][bj][m][1] * rs;
;                     if (ACT == 1) {
; #pragma unroll
;                         for (int e = 0; e < 4; ++e) { const float a0 = fmaxf(v0[e], 0.f), a1 = fmaxf(v1[e], 0.f); v0[e] = a0 * a0; v1[e] = a1 * a1; } }
;                     u32x4 w; w.x = cvt_pk_bf16(v0[0], v0[1]); w.y = cvt_pk_bf16(v0[2], v0[3]); w.z = cvt_pk_bf16(v1[0], v1[1]); w.w = cvt_pk_bf16(v1[2], v1[3]);
;                     __builtin_amdgcn_raw_buffer_store_b128(w, rsrc, (unsigned)(((size_t)row * ldc + col0 + bj * HALF) * 2), 0,   16); } }
;     }
.LBB0_630:
	v_readlane_b32 vcc_lo, v255, 59
	s_mov_b32 vcc_hi, 0
	s_nop 1
	s_mov_b64 vcc, vcc
	s_nop 1
	s_cbranch_vccnz .Lpp7_plain
	v_lshl_add_u32 v154, s6, 8, v129
	v_ashrrev_i32_e32 v155, 31, v154
	v_lshl_add_u64 v[146:147], v[154:155], 2, s[22:23]
	global_load_dword v155, v[146:147], off
	v_lshl_or_b32 v164, s7, 9, v153
	v_lshl_add_u32 v165, v154, 11, v164
	s_waitcnt vmcnt(0)
	v_fmamk_f32 v155, v155, 0x3a800000, v152
	v_mul_f32_e32 v156, 0x4b800000, v155
	v_cmp_gt_f32_e32 vcc, s59, v155
	s_nop 1
	v_cndmask_b32_e32 v155, v155, v156, vcc
	v_rsq_f32_e32 v155, v155
	v_or_b32_e32 v156, 16, v154
	v_ashrrev_i32_e32 v157, 31, v156
	v_lshl_add_u64 v[158:159], v[156:157], 2, s[22:23]
	v_mul_f32_e32 v157, 0x45800000, v155
	v_cndmask_b32_e32 v160, v155, v157, vcc
	v_pk_mul_f32 v[126:127], v[126:127], v[160:161] op_sel_hi:[1,0]
	v_pk_mul_f32 v[124:125], v[124:125], v[160:161] op_sel_hi:[1,0]
	v_pk_mul_f32 v[122:123], v[122:123], v[160:161] op_sel_hi:[1,0]
	v_pk_mul_f32 v[120:121], v[120:121], v[160:161] op_sel_hi:[1,0]
	v_pk_mul_f32 v[118:119], v[118:119], v[160:161] op_sel_hi:[1,0]
	v_pk_mul_f32 v[116:117], v[116:117], v[160:161] op_sel_hi:[1,0]
	v_pk_mul_f32 v[162:163], v[114:115], v[160:161] op_sel_hi:[1,0]
	v_pk_mul_f32 v[160:161], v[112:113], v[160:161] op_sel_hi:[1,0]
	v_cvt_pk_bf16_f32 v112, v124, v125
	v_cvt_pk_bf16_f32 v113, v126, v127
	v_cvt_pk_bf16_f32 v114, v120, v121
	v_cvt_pk_bf16_f32 v115, v122, v123
	v_cvt_pk_bf16_f32 v116, v116, v117
	v_cvt_pk_bf16_f32 v117, v118, v119
	v_cvt_pk_bf16_f32 v118, v160, v161
	v_cvt_pk_bf16_f32 v119, v162, v163
	buffer_store_dwordx4 v[112:115], v165, s[8:11], 0 offen sc1
	buffer_store_dwordx4 v[116:119], v165, s[8:11], 0 offen offset:256 sc1
	global_load_dword v113, v[158:159], off
	v_or_b32_e32 v112, 32, v154
	v_lshl_add_u32 v120, v156, 11, v164
	s_waitcnt vmcnt(0)
	v_fmamk_f32 v113, v113, 0x3a800000, v152
	v_mul_f32_e32 v114, 0x4b800000, v113
	v_cmp_gt_f32_e32 vcc, s59, v113
	s_nop 1
	v_cndmask_b32_e32 v113, v113, v114, vcc
	v_rsq_f32_e32 v116, v113
	v_ashrrev_i32_e32 v113, 31, v112
	v_lshl_add_u64 v[114:115], v[112:113], 2, s[22:23]
	v_mul_f32_e32 v113, 0x45800000, v116
	v_cndmask_b32_e32 v116, v116, v113, vcc
	v_pk_mul_f32 v[110:111], v[110:111], v[116:117] op_sel_hi:[1,0]
	v_pk_mul_f32 v[108:109], v[108:109], v[116:117] op_sel_hi:[1,0]
	v_pk_mul_f32 v[106:107], v[106:107], v[116:117] op_sel_hi:[1,0]
	v_pk_mul_f32 v[104:105], v[104:105], v[116:117] op_sel_hi:[1,0]
	v_pk_mul_f32 v[102:103], v[102:103], v[116:117] op_sel_hi:[1,0]
	v_pk_mul_f32 v[100:101], v[100:101], v[116:117] op_sel_hi:[1,0]
	v_pk_mul_f32 v[118:119], v[98:99], v[116:117] op_sel_hi:[1,0]
	v_pk_mul_f32 v[116:117], v[96:97], v[116:117] op_sel_hi:[1,0]
	v_cvt_pk_bf16_f32 v96, v108, v109
	v_cvt_pk_bf16_f32 v97, v110, v111
	v_cvt_pk_bf16_f32 v98, v104, v105
	v_cvt_pk_bf16_f32 v99, v106, v107
	v_cvt_pk_bf16_f32 v100, v100, v101
	v_cvt_pk_bf16_f32 v101, v102, v103
	v_cvt_pk_bf16_f32 v102, v116, v117
	v_cvt_pk_bf16_f32 v103, v118, v119
	buffer_store_dwordx4 v[96:99], v120, s[8:11], 0 offen sc1
	buffer_store_dwordx4 v[100:103], v120, s[8:11], 0 offen offset:256 sc1
	global_load_dword v97, v[114:115], off
	v_or_b32_e32 v96, 48, v154
	v_lshl_add_u32 v104, v112, 11, v164
	s_waitcnt vmcnt(0)
	v_fmamk_f32 v97, v97, 0x3a800000, v152
	v_mul_f32_e32 v98, 0x4b800000, v97
	v_cmp_gt_f32_e32 vcc, s59, v97
	s_nop 1
	v_cndmask_b32_e32 v97, v97, v98, vcc
	v_rsq_f32_e32 v100, v97
	v_ashrrev_i32_e32 v97, 31, v96
	v_lshl_add_u64 v[98:99], v[96:97], 2, s[22:23]
	v_mul_f32_e32 v97, 0x45800000, v100
	v_cndmask_b32_e32 v100, v100, v97, vcc
	v_pk_mul_f32 v[94:95], v[94:95], v[100:101] op_sel_hi:[1,0]
	v_pk_mul_f32 v[92:93], v[92:93], v[100:101] op_sel_hi:[1,0]
	v_pk_mul_f32 v[90:91], v[90:91], v[100:101] op_sel_hi:[1,0]
	v_pk_mul_f32 v[88:89], v[88:89], v[100:101] op_sel_hi:[1,0]
	v_pk_mul_f32 v[86:87], v[86:87], v[100:101] op_sel_hi:[1,0]
	v_pk_mul_f32 v[84:85], v[84:85], v[100:101] op_sel_hi:[1,0]
	v_pk_mul_f32 v[102:103], v[82:83], v[100:101] op_sel_hi:[1,0]
	v_pk_mul_f32 v[100:101], v[80:81], v[100:101] op_sel_hi:[1,0]
	v_cvt_pk_bf16_f32 v80, v92, v93
	v_cvt_pk_bf16_f32 v81, v94, v95
	v_cvt_pk_bf16_f32 v82, v88, v89
	v_cvt_pk_bf16_f32 v83, v90, v91
	v_cvt_pk_bf16_f32 v84, v84, v85
	v_cvt_pk_bf16_f32 v85, v86, v87
	v_cvt_pk_bf16_f32 v86, v100, v101
	v_cvt_pk_bf16_f32 v87, v102, v103
	buffer_store_dwordx4 v[80:83], v104, s[8:11], 0 offen sc1
	buffer_store_dwordx4 v[84:87], v104, s[8:11], 0 offen offset:256 sc1
	global_load_dword v80, v[98:99], off
	s_waitcnt vmcnt(0)
	v_fmamk_f32 v80, v80, 0x3a800000, v152
	v_mul_f32_e32 v81, 0x4b800000, v80
	v_cmp_gt_f32_e32 vcc, s59, v80
	v_lshl_add_u32 v84, v96, 11, v164
	s_nop 0
	v_cndmask_b32_e32 v80, v80, v81, vcc
	v_rsq_f32_e32 v80, v80
	s_nop 0
	v_mul_f32_e32 v81, 0x45800000, v80
	v_cndmask_b32_e32 v80, v80, v81, vcc
	v_pk_mul_f32 v[78:79], v[78:79], v[80:81] op_sel_hi:[1,0]
	v_pk_mul_f32 v[76:77], v[76:77], v[80:81] op_sel_hi:[1,0]
	v_pk_mul_f32 v[74:75], v[74:75], v[80:81] op_sel_hi:[1,0]
	v_pk_mul_f32 v[72:73], v[72:73], v[80:81] op_sel_hi:[1,0]
	v_pk_mul_f32 v[70:71], v[70:71], v[80:81] op_sel_hi:[1,0]
	v_pk_mul_f32 v[68:69], v[68:69], v[80:81] op_sel_hi:[1,0]
	v_pk_mul_f32 v[82:83], v[66:67], v[80:81] op_sel_hi:[1,0]
	v_pk_mul_f32 v[80:81], v[64:65], v[80:81] op_sel_hi:[1,0]
	v_cvt_pk_bf16_f32 v64, v76, v77
	v_cvt_pk_bf16_f32 v65, v78, v79
	v_cvt_pk_bf16_f32 v66, v72, v73
	v_cvt_pk_bf16_f32 v67, v74, v75
	v_cvt_pk_bf16_f32 v68, v68, v69
	v_cvt_pk_bf16_f32 v69, v70, v71
	v_cvt_pk_bf16_f32 v70, v80, v81
	v_cvt_pk_bf16_f32 v71, v82, v83
	buffer_store_dwordx4 v[64:67], v84, s[8:11], 0 offen sc1
	buffer_store_dwordx4 v[68:71], v84, s[8:11], 0 offen offset:256 sc1
	global_load_dword v64, v[146:147], off offset:512
	s_waitcnt vmcnt(0)
; __device__ __forceinline__ unsigned cvt_pk_bf16(float lo, float hi) { f32x2_t v = {lo, hi}; bf16x2_t b = __builtin_convertvector(v, bf16x2_t); return __builtin_bit_cast(unsigned, b); }
;     __device__ __forceinline__ void operator()(const f32x4 (&acc)[2][2][4][2], const Unit& u, int wr, int wc, int fr, int fq) const {
;         const int row0 = u.pm * BM + wr * 64 + fr; const int col0 = u.pn * BM + wc * 32 + 8 * fq;
;         const __amdgpu_buffer_rsrc_t rsrc = __builtin_amdgcn_make_buffer_rsrc((void*)O, (short)0, 16384 * ldc * 2, 0x00020000);
; #pragma unroll
;         for (int ai = 0; ai < 2; ++ai)
; #pragma unroll
;             for (int m = 0; m < 4; ++m) { const int row = row0 + ai * HALF + m * 16;
;                 const float rs = rowsq ? rsqrtf(rowsq[row] * (1.0f / 1024.0f) + 1e-6f) : 1.0f;
; #pragma unroll
;                 for (int bj = 0; bj < 2; ++bj) { f32x4 v0 = acc[ai][bj][m][0] * rs, v1 = acc[ai][bj][m][1] * rs;
;                     if (ACT == 1) {
; #pragma unroll
;                         for (int e = 0; e < 4; ++e) { const float a0 = fmaxf(v0[e], 0.f), a1 = fmaxf(v1[e], 0.f); v0[e] = a0 * a0; v1[e] = a1 * a1; } }
;                     u32x4 w; w.x = cvt_pk_bf16(v0[0], v0[1]); w.y = cvt_pk_bf16(v0[2], v0[3]); w.z = cvt_pk_bf16(v1[0], v1[1]); w.w = cvt_pk_bf16(v1[2], v1[3]);
;                     __builtin_amdgcn_raw_buffer_store_b128(w, rsrc, (unsigned)(((size_t)row * ldc + col0 + bj * HALF) * 2), 0,   16); } }
;     }
	v_fmamk_f32 v64, v64, 0x3a800000, v152
	v_mul_f32_e32 v65, 0x4b800000, v64
	v_cmp_gt_f32_e32 vcc, s59, v64
	v_add_u32_e32 v68, 0x40000, v165
	s_nop 0
	v_cndmask_b32_e32 v64, v64, v65, vcc
	v_rsq_f32_e32 v64, v64
	s_nop 0
	v_mul_f32_e32 v65, 0x45800000, v64
	v_cndmask_b32_e32 v64, v64, v65, vcc
	v_pk_mul_f32 v[62:63], v[62:63], v[64:65] op_sel_hi:[1,0]
	v_pk_mul_f32 v[60:61], v[60:61], v[64:65] op_sel_hi:[1,0]
	v_pk_mul_f32 v[58:59], v[58:59], v[64:65] op_sel_hi:[1,0]
	v_pk_mul_f32 v[56:57], v[56:57], v[64:65] op_sel_hi:[1,0]
	v_pk_mul_f32 v[54:55], v[54:55], v[64:65] op_sel_hi:[1,0]
	v_pk_mul_f32 v[52:53], v[52:53], v[64:65] op_sel_hi:[1,0]
	v_pk_mul_f32 v[66:67], v[50:51], v[64:65] op_sel_hi:[1,0]
	v_pk_mul_f32 v[64:65], v[48:49], v[64:65] op_sel_hi:[1,0]
	v_cvt_pk_bf16_f32 v48, v60, v61
	v_cvt_pk_bf16_f32 v49, v62, v63
	v_cvt_pk_bf16_f32 v50, v56, v57
	v_cvt_pk_bf16_f32 v51, v58, v59
	v_cvt_pk_bf16_f32 v52, v52, v53
	v_cvt_pk_bf16_f32 v53, v54, v55
	v_cvt_pk_bf16_f32 v54, v64, v65
	v_cvt_pk_bf16_f32 v55, v66, v67
	buffer_store_dwordx4 v[48:51], v68, s[8:11], 0 offen sc1
	buffer_store_dwordx4 v[52:55], v68, s[8:11], 0 offen offset:256 sc1
	global_load_dword v48, v[146:147], off offset:576
	s_waitcnt vmcnt(0)
	v_fmamk_f32 v48, v48, 0x3a800000, v152
	v_mul_f32_e32 v49, 0x4b800000, v48
	v_cmp_gt_f32_e32 vcc, s59, v48
	v_add_u32_e32 v52, 0x48000, v165
	s_nop 0
	v_cndmask_b32_e32 v48, v48, v49, vcc
	v_rsq_f32_e32 v48, v48
	s_nop 0
	v_mul_f32_e32 v49, 0x45800000, v48
	v_cndmask_b32_e32 v48, v48, v49, vcc
	v_pk_mul_f32 v[46:47], v[46:47], v[48:49] op_sel_hi:[1,0]
	v_pk_mul_f32 v[44:45], v[44:45], v[48:49] op_sel_hi:[1,0]
	v_pk_mul_f32 v[42:43], v[42:43], v[48:49] op_sel_hi:[1,0]
	v_pk_mul_f32 v[40:41], v[40:41], v[48:49] op_sel_hi:[1,0]
	v_pk_mul_f32 v[38:39], v[38:39], v[48:49] op_sel_hi:[1,0]
	v_pk_mul_f32 v[36:37], v[36:37], v[48:49] op_sel_hi:[1,0]
	v_pk_mul_f32 v[50:51], v[34:35], v[48:49] op_sel_hi:[1,0]
	v_pk_mul_f32 v[48:49], v[32:33], v[48:49] op_sel_hi:[1,0]
	v_cvt_pk_bf16_f32 v32, v44, v45
	v_cvt_pk_bf16_f32 v33, v46, v47
	v_cvt_pk_bf16_f32 v34, v40, v41
	v_cvt_pk_bf16_f32 v35, v42, v43
	v_cvt_pk_bf16_f32 v36, v36, v37
	v_cvt_pk_bf16_f32 v37, v38, v39
	v_cvt_pk_bf16_f32 v38, v48, v49
	v_cvt_pk_bf16_f32 v39, v50, v51
	buffer_store_dwordx4 v[32:35], v52, s[8:11], 0 offen sc1
	buffer_store_dwordx4 v[36:39], v52, s[8:11], 0 offen offset:256 sc1
	global_load_dword v32, v[146:147], off offset:640
	s_waitcnt vmcnt(0)
	v_fmamk_f32 v32, v32, 0x3a800000, v152
	v_mul_f32_e32 v33, 0x4b800000, v32
	v_cmp_gt_f32_e32 vcc, s59, v32
	v_add_u32_e32 v36, 0x50000, v165
	s_nop 0
	v_cndmask_b32_e32 v32, v32, v33, vcc
	v_rsq_f32_e32 v32, v32
	s_nop 0
	v_mul_f32_e32 v33, 0x45800000, v32
	v_cndmask_b32_e32 v32, v32, v33, vcc
	v_pk_mul_f32 v[30:31], v[30:31], v[32:33] op_sel_hi:[1,0]
	v_pk_mul_f32 v[28:29], v[28:29], v[32:33] op_sel_hi:[1,0]
	v_pk_mul_f32 v[26:27], v[26:27], v[32:33] op_sel_hi:[1,0]
	v_pk_mul_f32 v[24:25], v[24:25], v[32:33] op_sel_hi:[1,0]
	v_pk_mul_f32 v[22:23], v[22:23], v[32:33] op_sel_hi:[1,0]
	v_pk_mul_f32 v[20:21], v[20:21], v[32:33] op_sel_hi:[1,0]
	v_pk_mul_f32 v[34:35], v[18:19], v[32:33] op_sel_hi:[1,0]
	v_pk_mul_f32 v[32:33], v[16:17], v[32:33] op_sel_hi:[1,0]
	v_cvt_pk_bf16_f32 v16, v28, v29
	v_cvt_pk_bf16_f32 v17, v30, v31
	v_cvt_pk_bf16_f32 v18, v24, v25
	v_cvt_pk_bf16_f32 v19, v26, v27
	v_cvt_pk_bf16_f32 v20, v20, v21
	v_cvt_pk_bf16_f32 v21, v22, v23
	v_cvt_pk_bf16_f32 v22, v32, v33
	v_cvt_pk_bf16_f32 v23, v34, v35
	buffer_store_dwordx4 v[16:19], v36, s[8:11], 0 offen sc1
	buffer_store_dwordx4 v[20:23], v36, s[8:11], 0 offen offset:256 sc1
	global_load_dword v16, v[146:147], off offset:704
	s_andn2_b64 vcc, exec, s[4:5]
	v_add_u32_e32 v20, 0x58000, v165
	s_mov_b64 s[4:5], -1
	s_waitcnt vmcnt(0)
	v_fmamk_f32 v16, v16, 0x3a800000, v152
	v_mul_f32_e32 v17, 0x4b800000, v16
	v_cmp_gt_f32_e64 s[6:7], s59, v16
	s_nop 1
	v_cndmask_b32_e64 v16, v16, v17, s[6:7]
	v_rsq_f32_e32 v16, v16
	s_nop 0
	v_mul_f32_e32 v17, 0x45800000, v16
	v_cndmask_b32_e64 v16, v16, v17, s[6:7]
	v_pk_mul_f32 v[14:15], v[14:15], v[16:17] op_sel_hi:[1,0]
	v_pk_mul_f32 v[12:13], v[12:13], v[16:17] op_sel_hi:[1,0]
	v_pk_mul_f32 v[10:11], v[10:11], v[16:17] op_sel_hi:[1,0]
	v_pk_mul_f32 v[8:9], v[8:9], v[16:17] op_sel_hi:[1,0]
	v_pk_mul_f32 v[6:7], v[6:7], v[16:17] op_sel_hi:[1,0]
	v_pk_mul_f32 v[4:5], v[4:5], v[16:17] op_sel_hi:[1,0]
	v_pk_mul_f32 v[18:19], v[2:3], v[16:17] op_sel_hi:[1,0]
	v_pk_mul_f32 v[16:17], v[0:1], v[16:17] op_sel_hi:[1,0]
	v_cvt_pk_bf16_f32 v0, v12, v13
	v_cvt_pk_bf16_f32 v1, v14, v15
	v_cvt_pk_bf16_f32 v2, v8, v9
	v_cvt_pk_bf16_f32 v3, v10, v11
	v_cvt_pk_bf16_f32 v4, v4, v5
	v_cvt_pk_bf16_f32 v5, v6, v7
	v_cvt_pk_bf16_f32 v6, v16, v17
	v_cvt_pk_bf16_f32 v7, v18, v19
	buffer_store_dwordx4 v[0:3], v20, s[8:11], 0 offen sc1
	buffer_store_dwordx4 v[4:7], v20, s[8:11], 0 offen offset:256 sc1
	s_branch .Lpp7_done
; __device__ __forceinline__ unsigned cvt_pk_bf16(float lo, float hi) { f32x2_t v = {lo, hi}; bf16x2_t b = __builtin_convertvector(v, bf16x2_t); return __builtin_bit_cast(unsigned, b); }
;     __device__ __forceinline__ void operator()(const f32x4 (&acc)[2][2][4][2], const Unit& u, int wr, int wc, int fr, int fq) const {
;         const int row0 = u.pm * BM + wr * 64 + fr; const int col0 = u.pn * BM + wc * 32 + 8 * fq;
;         const __amdgpu_buffer_rsrc_t rsrc = __builtin_amdgcn_make_buffer_rsrc((void*)O, (short)0, 16384 * ldc * 2, 0x00020000);
; #pragma unroll
;         for (int ai = 0; ai < 2; ++ai)
; #pragma unroll
;             for (int m = 0; m < 4; ++m) { const int row = row0 + ai * HALF + m * 16;
;                 const float rs = rowsq ? rsqrtf(rowsq[row] * (1.0f / 1024.0f) + 1e-6f) : 1.0f;
; #pragma unroll
;                 for (int bj = 0; bj < 2; ++bj) { f32x4 v0 = acc[ai][bj][m][0] * rs, v1 = acc[ai][bj][m][1] * rs;
;                     if (ACT == 1) {
; #pragma unroll
;                         for (int e = 0; e < 4; ++e) { const float a0 = fmaxf(v0[e], 0.f), a1 = fmaxf(v1[e], 0.f); v0[e] = a0 * a0; v1[e] = a1 * a1; } }
;                     u32x4 w; w.x = cvt_pk_bf16(v0[0], v0[1]); w.y = cvt_pk_bf16(v0[2], v0[3]); w.z = cvt_pk_bf16(v1[0], v1[1]); w.w = cvt_pk_bf16(v1[2], v1[3]);
;                     __builtin_amdgcn_raw_buffer_store_b128(w, rsrc, (unsigned)(((size_t)row * ldc + col0 + bj * HALF) * 2), 0,   16); } }
;     }
.Lpp7_plain:
	v_lshl_add_u32 v154, s6, 8, v129
	v_ashrrev_i32_e32 v155, 31, v154
	v_lshl_add_u64 v[146:147], v[154:155], 2, s[22:23]
	global_load_dword v155, v[146:147], off
	v_lshl_or_b32 v164, s7, 9, v153
	v_lshl_add_u32 v165, v154, 11, v164
	s_waitcnt vmcnt(0)
	v_fmamk_f32 v155, v155, 0x3a800000, v152
	v_mul_f32_e32 v156, 0x4b800000, v155
	v_cmp_gt_f32_e32 vcc, s59, v155
	s_nop 1
	v_cndmask_b32_e32 v155, v155, v156, vcc
	v_rsq_f32_e32 v155, v155
	v_or_b32_e32 v156, 16, v154
	v_ashrrev_i32_e32 v157, 31, v156
	v_lshl_add_u64 v[158:159], v[156:157], 2, s[22:23]
	v_mul_f32_e32 v157, 0x45800000, v155
	v_cndmask_b32_e32 v160, v155, v157, vcc
	v_pk_mul_f32 v[126:127], v[126:127], v[160:161] op_sel_hi:[1,0]
	v_pk_mul_f32 v[124:125], v[124:125], v[160:161] op_sel_hi:[1,0]
	v_pk_mul_f32 v[122:123], v[122:123], v[160:161] op_sel_hi:[1,0]
	v_pk_mul_f32 v[120:121], v[120:121], v[160:161] op_sel_hi:[1,0]
	v_pk_mul_f32 v[118:119], v[118:119], v[160:161] op_sel_hi:[1,0]
	v_pk_mul_f32 v[116:117], v[116:117], v[160:161] op_sel_hi:[1,0]
	v_pk_mul_f32 v[162:163], v[114:115], v[160:161] op_sel_hi:[1,0]
	v_pk_mul_f32 v[160:161], v[112:113], v[160:161] op_sel_hi:[1,0]
	v_cvt_pk_bf16_f32 v112, v124, v125
	v_cvt_pk_bf16_f32 v113, v126, v127
	v_cvt_pk_bf16_f32 v114, v120, v121
	v_cvt_pk_bf16_f32 v115, v122, v123
	v_cvt_pk_bf16_f32 v116, v116, v117
	v_cvt_pk_bf16_f32 v117, v118, v119
	v_cvt_pk_bf16_f32 v118, v160, v161
	v_cvt_pk_bf16_f32 v119, v162, v163
	buffer_store_dwordx4 v[112:115], v165, s[8:11], 0 offen
	buffer_store_dwordx4 v[116:119], v165, s[8:11], 0 offen offset:256
	global_load_dword v113, v[158:159], off
	v_or_b32_e32 v112, 32, v154
	v_lshl_add_u32 v120, v156, 11, v164
	s_waitcnt vmcnt(0)
	v_fmamk_f32 v113, v113, 0x3a800000, v152
	v_mul_f32_e32 v114, 0x4b800000, v113
	v_cmp_gt_f32_e32 vcc, s59, v113
	s_nop 1
	v_cndmask_b32_e32 v113, v113, v114, vcc
	v_rsq_f32_e32 v116, v113
	v_ashrrev_i32_e32 v113, 31, v112
	v_lshl_add_u64 v[114:115], v[112:113], 2, s[22:23]
	v_mul_f32_e32 v113, 0x45800000, v116
	v_cndmask_b32_e32 v116, v116, v113, vcc
	v_pk_mul_f32 v[110:111], v[110:111], v[116:117] op_sel_hi:[1,0]
	v_pk_mul_f32 v[108:109], v[108:109], v[116:117] op_sel_hi:[1,0]
	v_pk_mul_f32 v[106:107], v[106:107], v[116:117] op_sel_hi:[1,0]
	v_pk_mul_f32 v[104:105], v[104:105], v[116:117] op_sel_hi:[1,0]
	v_pk_mul_f32 v[102:103], v[102:103], v[116:117] op_sel_hi:[1,0]
	v_pk_mul_f32 v[100:101], v[100:101], v[116:117] op_sel_hi:[1,0]
	v_pk_mul_f32 v[118:119], v[98:99], v[116:117] op_sel_hi:[1,0]
	v_pk_mul_f32 v[116:117], v[96:97], v[116:117] op_sel_hi:[1,0]
	v_cvt_pk_bf16_f32 v96, v108, v109
	v_cvt_pk_bf16_f32 v97, v110, v111
	v_cvt_pk_bf16_f32 v98, v104, v105
	v_cvt_pk_bf16_f32 v99, v106, v107
	v_cvt_pk_bf16_f32 v100, v100, v101
	v_cvt_pk_bf16_f32 v101, v102, v103
	v_cvt_pk_bf16_f32 v102, v116, v117
	v_cvt_pk_bf16_f32 v103, v118, v119
	buffer_store_dwordx4 v[96:99], v120, s[8:11], 0 offen
	buffer_store_dwordx4 v[100:103], v120, s[8:11], 0 offen offset:256
	global_load_dword v97, v[114:115], off
	v_or_b32_e32 v96, 48, v154
	v_lshl_add_u32 v104, v112, 11, v164
	s_waitcnt vmcnt(0)
	v_fmamk_f32 v97, v97, 0x3a800000, v152
	v_mul_f32_e32 v98, 0x4b800000, v97
	v_cmp_gt_f32_e32 vcc, s59, v97
	s_nop 1
	v_cndmask_b32_e32 v97, v97, v98, vcc
	v_rsq_f32_e32 v100, v97
	v_ashrrev_i32_e32 v97, 31, v96
	v_lshl_add_u64 v[98:99], v[96:97], 2, s[22:23]
	v_mul_f32_e32 v97, 0x45800000, v100
	v_cndmask_b32_e32 v100, v100, v97, vcc
	v_pk_mul_f32 v[94:95], v[94:95], v[100:101] op_sel_hi:[1,0]
	v_pk_mul_f32 v[92:93], v[92:93], v[100:101] op_sel_hi:[1,0]
	v_pk_mul_f32 v[90:91], v[90:91], v[100:101] op_sel_hi:[1,0]
	v_pk_mul_f32 v[88:89], v[88:89], v[100:101] op_sel_hi:[1,0]
	v_pk_mul_f32 v[86:87], v[86:87], v[100:101] op_sel_hi:[1,0]
	v_pk_mul_f32 v[84:85], v[84:85], v[100:101] op_sel_hi:[1,0]
	v_pk_mul_f32 v[102:103], v[82:83], v[100:101] op_sel_hi:[1,0]
	v_pk_mul_f32 v[100:101], v[80:81], v[100:101] op_sel_hi:[1,0]
	v_cvt_pk_bf16_f32 v80, v92, v93
	v_cvt_pk_bf16_f32 v81, v94, v95
	v_cvt_pk_bf16_f32 v82, v88, v89
	v_cvt_pk_bf16_f32 v83, v90, v91
	v_cvt_pk_bf16_f32 v84, v84, v85
	v_cvt_pk_bf16_f32 v85, v86, v87
	v_cvt_pk_bf16_f32 v86, v100, v101
	v_cvt_pk_bf16_f32 v87, v102, v103
	buffer_store_dwordx4 v[80:83], v104, s[8:11], 0 offen
	buffer_store_dwordx4 v[84:87], v104, s[8:11], 0 offen offset:256
	global_load_dword v80, v[98:99], off
	s_waitcnt vmcnt(0)
	v_fmamk_f32 v80, v80, 0x3a800000, v152
	v_mul_f32_e32 v81, 0x4b800000, v80
	v_cmp_gt_f32_e32 vcc, s59, v80
	v_lshl_add_u32 v84, v96, 11, v164
	s_nop 0
	v_cndmask_b32_e32 v80, v80, v81, vcc
	v_rsq_f32_e32 v80, v80
	s_nop 0
	v_mul_f32_e32 v81, 0x45800000, v80
	v_cndmask_b32_e32 v80, v80, v81, vcc
	v_pk_mul_f32 v[78:79], v[78:79], v[80:81] op_sel_hi:[1,0]
	v_pk_mul_f32 v[76:77], v[76:77], v[80:81] op_sel_hi:[1,0]
	v_pk_mul_f32 v[74:75], v[74:75], v[80:81] op_sel_hi:[1,0]
	v_pk_mul_f32 v[72:73], v[72:73], v[80:81] op_sel_hi:[1,0]
	v_pk_mul_f32 v[70:71], v[70:71], v[80:81] op_sel_hi:[1,0]
	v_pk_mul_f32 v[68:69], v[68:69], v[80:81] op_sel_hi:[1,0]
	v_pk_mul_f32 v[82:83], v[66:67], v[80:81] op_sel_hi:[1,0]
	v_pk_mul_f32 v[80:81], v[64:65], v[80:81] op_sel_hi:[1,0]
	v_cvt_pk_bf16_f32 v64, v76, v77
	v_cvt_pk_bf16_f32 v65, v78, v79
	v_cvt_pk_bf16_f32 v66, v72, v73
	v_cvt_pk_bf16_f32 v67, v74, v75
	v_cvt_pk_bf16_f32 v68, v68, v69
	v_cvt_pk_bf16_f32 v69, v70, v71
	v_cvt_pk_bf16_f32 v70, v80, v81
	v_cvt_pk_bf16_f32 v71, v82, v83
	buffer_store_dwordx4 v[64:67], v84, s[8:11], 0 offen
	buffer_store_dwordx4 v[68:71], v84, s[8:11], 0 offen offset:256
	global_load_dword v64, v[146:147], off offset:512
	s_waitcnt vmcnt(0)
; __device__ __forceinline__ unsigned cvt_pk_bf16(float lo, float hi) { f32x2_t v = {lo, hi}; bf16x2_t b = __builtin_convertvector(v, bf16x2_t); return __builtin_bit_cast(unsigned, b); }
;     __device__ __forceinline__ void operator()(const f32x4 (&acc)[2][2][4][2], const Unit& u, int wr, int wc, int fr, int fq) const {
;         const int row0 = u.pm * BM + wr * 64 + fr; const int col0 = u.pn * BM + wc * 32 + 8 * fq;
;         const __amdgpu_buffer_rsrc_t rsrc = __builtin_amdgcn_make_buffer_rsrc((void*)O, (short)0, 16384 * ldc * 2, 0x00020000);
; #pragma unroll
;         for (int ai = 0; ai < 2; ++ai)
; #pragma unroll
;             for (int m = 0; m < 4; ++m) { const int row = row0 + ai * HALF + m * 16;
;                 const float rs = rowsq ? rsqrtf(rowsq[row] * (1.0f / 1024.0f) + 1e-6f) : 1.0f;
; #pragma unroll
;                 for (int bj = 0; bj < 2; ++bj) { f32x4 v0 = acc[ai][bj][m][0] * rs, v1 = acc[ai][bj][m][1] * rs;
;                     if (ACT == 1) {
; #pragma unroll
;                         for (int e = 0; e < 4; ++e) { const float a0 = fmaxf(v0[e], 0.f), a1 = fmaxf(v1[e], 0.f); v0[e] = a0 * a0; v1[e] = a1 * a1; } }
;                     u32x4 w; w.x = cvt_pk_bf16(v0[0], v0[1]); w.y = cvt_pk_bf16(v0[2], v0[3]); w.z = cvt_pk_bf16(v1[0], v1[1]); w.w = cvt_pk_bf16(v1[2], v1[3]);
;                     __builtin_amdgcn_raw_buffer_store_b128(w, rsrc, (unsigned)(((size_t)row * ldc + col0 + bj * HALF) * 2), 0,   16); } }
;     }
	v_fmamk_f32 v64, v64, 0x3a800000, v152
	v_mul_f32_e32 v65, 0x4b800000, v64
	v_cmp_gt_f32_e32 vcc, s59, v64
	v_add_u32_e32 v68, 0x40000, v165
	s_nop 0
	v_cndmask_b32_e32 v64, v64, v65, vcc
	v_rsq_f32_e32 v64, v64
	s_nop 0
	v_mul_f32_e32 v65, 0x45800000, v64
	v_cndmask_b32_e32 v64, v64, v65, vcc
	v_pk_mul_f32 v[62:63], v[62:63], v[64:65] op_sel_hi:[1,0]
	v_pk_mul_f32 v[60:61], v[60:61], v[64:65] op_sel_hi:[1,0]
	v_pk_mul_f32 v[58:59], v[58:59], v[64:65] op_sel_hi:[1,0]
	v_pk_mul_f32 v[56:57], v[56:57], v[64:65] op_sel_hi:[1,0]
	v_pk_mul_f32 v[54:55], v[54:55], v[64:65] op_sel_hi:[1,0]
	v_pk_mul_f32 v[52:53], v[52:53], v[64:65] op_sel_hi:[1,0]
	v_pk_mul_f32 v[66:67], v[50:51], v[64:65] op_sel_hi:[1,0]
	v_pk_mul_f32 v[64:65], v[48:49], v[64:65] op_sel_hi:[1,0]
	v_cvt_pk_bf16_f32 v48, v60, v61
	v_cvt_pk_bf16_f32 v49, v62, v63
	v_cvt_pk_bf16_f32 v50, v56, v57
	v_cvt_pk_bf16_f32 v51, v58, v59
	v_cvt_pk_bf16_f32 v52, v52, v53
	v_cvt_pk_bf16_f32 v53, v54, v55
	v_cvt_pk_bf16_f32 v54, v64, v65
	v_cvt_pk_bf16_f32 v55, v66, v67
	buffer_store_dwordx4 v[48:51], v68, s[8:11], 0 offen
	buffer_store_dwordx4 v[52:55], v68, s[8:11], 0 offen offset:256
	global_load_dword v48, v[146:147], off offset:576
	s_waitcnt vmcnt(0)
	v_fmamk_f32 v48, v48, 0x3a800000, v152
	v_mul_f32_e32 v49, 0x4b800000, v48
	v_cmp_gt_f32_e32 vcc, s59, v48
	v_add_u32_e32 v52, 0x48000, v165
	s_nop 0
	v_cndmask_b32_e32 v48, v48, v49, vcc
	v_rsq_f32_e32 v48, v48
	s_nop 0
	v_mul_f32_e32 v49, 0x45800000, v48
	v_cndmask_b32_e32 v48, v48, v49, vcc
	v_pk_mul_f32 v[46:47], v[46:47], v[48:49] op_sel_hi:[1,0]
	v_pk_mul_f32 v[44:45], v[44:45], v[48:49] op_sel_hi:[1,0]
	v_pk_mul_f32 v[42:43], v[42:43], v[48:49] op_sel_hi:[1,0]
	v_pk_mul_f32 v[40:41], v[40:41], v[48:49] op_sel_hi:[1,0]
	v_pk_mul_f32 v[38:39], v[38:39], v[48:49] op_sel_hi:[1,0]
	v_pk_mul_f32 v[36:37], v[36:37], v[48:49] op_sel_hi:[1,0]
	v_pk_mul_f32 v[50:51], v[34:35], v[48:49] op_sel_hi:[1,0]
	v_pk_mul_f32 v[48:49], v[32:33], v[48:49] op_sel_hi:[1,0]
	v_cvt_pk_bf16_f32 v32, v44, v45
	v_cvt_pk_bf16_f32 v33, v46, v47
	v_cvt_pk_bf16_f32 v34, v40, v41
	v_cvt_pk_bf16_f32 v35, v42, v43
	v_cvt_pk_bf16_f32 v36, v36, v37
	v_cvt_pk_bf16_f32 v37, v38, v39
	v_cvt_pk_bf16_f32 v38, v48, v49
	v_cvt_pk_bf16_f32 v39, v50, v51
	buffer_store_dwordx4 v[32:35], v52, s[8:11], 0 offen
	buffer_store_dwordx4 v[36:39], v52, s[8:11], 0 offen offset:256
	global_load_dword v32, v[146:147], off offset:640
	s_waitcnt vmcnt(0)
	v_fmamk_f32 v32, v32, 0x3a800000, v152
	v_mul_f32_e32 v33, 0x4b800000, v32
	v_cmp_gt_f32_e32 vcc, s59, v32
	v_add_u32_e32 v36, 0x50000, v165
	s_nop 0
	v_cndmask_b32_e32 v32, v32, v33, vcc
	v_rsq_f32_e32 v32, v32
	s_nop 0
	v_mul_f32_e32 v33, 0x45800000, v32
	v_cndmask_b32_e32 v32, v32, v33, vcc
	v_pk_mul_f32 v[30:31], v[30:31], v[32:33] op_sel_hi:[1,0]
	v_pk_mul_f32 v[28:29], v[28:29], v[32:33] op_sel_hi:[1,0]
	v_pk_mul_f32 v[26:27], v[26:27], v[32:33] op_sel_hi:[1,0]
	v_pk_mul_f32 v[24:25], v[24:25], v[32:33] op_sel_hi:[1,0]
	v_pk_mul_f32 v[22:23], v[22:23], v[32:33] op_sel_hi:[1,0]
	v_pk_mul_f32 v[20:21], v[20:21], v[32:33] op_sel_hi:[1,0]
	v_pk_mul_f32 v[34:35], v[18:19], v[32:33] op_sel_hi:[1,0]
	v_pk_mul_f32 v[32:33], v[16:17], v[32:33] op_sel_hi:[1,0]
	v_cvt_pk_bf16_f32 v16, v28, v29
	v_cvt_pk_bf16_f32 v17, v30, v31
	v_cvt_pk_bf16_f32 v18, v24, v25
	v_cvt_pk_bf16_f32 v19, v26, v27
	v_cvt_pk_bf16_f32 v20, v20, v21
	v_cvt_pk_bf16_f32 v21, v22, v23
	v_cvt_pk_bf16_f32 v22, v32, v33
	v_cvt_pk_bf16_f32 v23, v34, v35
	buffer_store_dwordx4 v[16:19], v36, s[8:11], 0 offen
	buffer_store_dwordx4 v[20:23], v36, s[8:11], 0 offen offset:256
	global_load_dword v16, v[146:147], off offset:704
	s_andn2_b64 vcc, exec, s[4:5]
	v_add_u32_e32 v20, 0x58000, v165
	s_mov_b64 s[4:5], -1
	s_waitcnt vmcnt(0)
	v_fmamk_f32 v16, v16, 0x3a800000, v152
	v_mul_f32_e32 v17, 0x4b800000, v16
	v_cmp_gt_f32_e64 s[6:7], s59, v16
	s_nop 1
	v_cndmask_b32_e64 v16, v16, v17, s[6:7]
	v_rsq_f32_e32 v16, v16
	s_nop 0
	v_mul_f32_e32 v17, 0x45800000, v16
	v_cndmask_b32_e64 v16, v16, v17, s[6:7]
	v_pk_mul_f32 v[14:15], v[14:15], v[16:17] op_sel_hi:[1,0]
	v_pk_mul_f32 v[12:13], v[12:13], v[16:17] op_sel_hi:[1,0]
	v_pk_mul_f32 v[10:11], v[10:11], v[16:17] op_sel_hi:[1,0]
	v_pk_mul_f32 v[8:9], v[8:9], v[16:17] op_sel_hi:[1,0]
	v_pk_mul_f32 v[6:7], v[6:7], v[16:17] op_sel_hi:[1,0]
	v_pk_mul_f32 v[4:5], v[4:5], v[16:17] op_sel_hi:[1,0]
	v_pk_mul_f32 v[18:19], v[2:3], v[16:17] op_sel_hi:[1,0]
	v_pk_mul_f32 v[16:17], v[0:1], v[16:17] op_sel_hi:[1,0]
	v_cvt_pk_bf16_f32 v0, v12, v13
	v_cvt_pk_bf16_f32 v1, v14, v15
	v_cvt_pk_bf16_f32 v2, v8, v9
	v_cvt_pk_bf16_f32 v3, v10, v11
	v_cvt_pk_bf16_f32 v4, v4, v5
	v_cvt_pk_bf16_f32 v5, v6, v7
	v_cvt_pk_bf16_f32 v6, v16, v17
	v_cvt_pk_bf16_f32 v7, v18, v19
	buffer_store_dwordx4 v[0:3], v20, s[8:11], 0 offen
	buffer_store_dwordx4 v[4:7], v20, s[8:11], 0 offen offset:256
.Lpp7_done:
	s_cbranch_vccnz .LBB0_619
	s_andn2_b64 vcc, exec, s[26:27]
	s_cbranch_vccnz .LBB0_618
	s_barrier
	s_branch .LBB0_618

; #define LAS __attribute__((address_space(3)))
; __device__ __forceinline__ unsigned pk2(float lo, float hi) { return pg8::cvt_pk_bf16(lo, hi); }
; #define MFMA16(a, b, c) __builtin_amdgcn_mfma_f32_16x16x32_bf16((a), (b), (c), 0, 0, 0)
; __device__ __forceinline__ void xattn_softmax(f32x4 (&s)[16], bf16x8 (&pf)[8], float& rinv) {
;     ...
;     rinv = 1.f / sum;
; #pragma unroll
;     for (int kk = 0; kk < 8; ++kk) { u32x4 w; w.x = pk2(s[2 * kk][0], s[2 * kk][1]); w.y = pk2(s[2 * kk][2], s[2 * kk][3]); w.z = pk2(s[2 * kk + 1][0], s[2 * kk + 1][1]); w.w = pk2(s[2 * kk + 1][2], s[2 * kk + 1][3]);
;         pf[kk] = __builtin_bit_cast(bf16x8, w); }
; __device__ __forceinline__ void xattn_pair(LAS unsigned char* lds, int bh, size_t row_base, bf16* QO, const bf16* Kx, const bf16* VTx, int tid, const WsRef& wsr) {
;     ...
;     const u32x4* vg = (const u32x4*)(VTx + (size_t)bh * 65536);
; #pragma unroll 4
;     for (int i = 0; i < 16; ++i) { const int id = tid + 512 * i, r = id >> 5, ch = id & 31; *(LAS u32x4*)(T + r * LDX + ch * 8) = vg[id]; }
;     __syncthreads();
; #pragma unroll
;     for (int nh = 0; nh < 2; ++nh) {
;         f32x4 o0[8], o1[8];
; #pragma unroll
;         for (int n = 0; n < 8; ++n) { o0[n] = (f32x4){0.f, 0.f, 0.f, 0.f}; o1[n] = (f32x4){0.f, 0.f, 0.f, 0.f}; }
; #pragma unroll
;         for (int kk = 0; kk < 8; ++kk)
; #pragma unroll
;             for (int n = 0; n < 8; ++n) { const LAS bf16* vp = T + ((nh * 8 + n) * 16 + fr) * LDX + kk * 32 + 4 * fq;
;                 const u32x2 lo = *(const LAS u32x2*)vp, hi = *(const LAS u32x2*)(vp + 16); u32x4 w; w.x = lo.x; w.y = lo.y; w.z = hi.x; w.w = hi.y; const bf16x8 vf = __builtin_bit_cast(bf16x8, w);
;                 o0[n] = MFMA16(vf, pf0[kk], o0[n]); o1[n] = MFMA16(vf, pf1[kk], o1[n]); }
.LBB0_706:
	v_lshl_add_u64 v[32:33], v[84:85], 0, s[8:9]
	v_add_co_u32_e32 v20, vcc, 0x2300000, v32
	s_add_u32 s8, s8, 0x8000
	s_nop 0
	v_addc_co_u32_e32 v21, vcc, 0, v33, vcc
	v_add_co_u32_e32 v24, vcc, 0x2302000, v32
	s_addc_u32 s9, s9, 0
	s_nop 0
	v_addc_co_u32_e32 v25, vcc, 0, v33, vcc
	v_add_co_u32_e32 v28, vcc, 0x2304000, v32
	global_load_dwordx4 v[20:23], v[20:21], off
	s_nop 0
	global_load_dwordx4 v[24:27], v[24:25], off
	v_addc_co_u32_e32 v29, vcc, 0, v33, vcc
	v_add_co_u32_e32 v32, vcc, 0x2306000, v32
	global_load_dwordx4 v[28:31], v[28:29], off
	s_nop 0
	v_addc_co_u32_e32 v33, vcc, 0, v33, vcc
	global_load_dwordx4 v[32:35], v[32:33], off
	s_cmp_lg_u32 s8, 0x20000
	s_waitcnt vmcnt(3)
	ds_write_b128 v91, v[20:23]
	v_add_u32_e32 v91, 0x8400, v91
	s_waitcnt vmcnt(2)
	ds_write_b128 v90, v[24:27]
	v_add_u32_e32 v90, 0x8400, v90
	s_waitcnt vmcnt(1)
	ds_write_b128 v2, v[28:31]
	v_add_u32_e32 v2, 0x8400, v2
	s_waitcnt vmcnt(0)
	ds_write_b128 v89, v[32:35]
	v_add_u32_e32 v89, 0x8400, v89
	s_cbranch_scc1 .LBB0_706
	v_add_u32_e32 v99, 0, v109
	v_add_u32_e32 v155, v99, v88
	s_waitcnt lgkmcnt(0)
	s_barrier
	ds_read2_b64 v[28:31], v155 offset1:4
	v_cvt_pk_bf16_f32 v20, v165, v168
	v_cvt_pk_bf16_f32 v24, v133, v136
	v_cvt_pk_bf16_f32 v25, v140, v144
	v_cvt_pk_bf16_f32 v26, v149, v150
	v_cvt_pk_bf16_f32 v27, v151, v152
	v_cvt_pk_bf16_f32 v21, v167, v170
	v_cvt_pk_bf16_f32 v22, v173, v174
	v_cvt_pk_bf16_f32 v23, v175, v176
	v_add_u32_e32 v133, 0x2000, v155
	s_waitcnt lgkmcnt(0)
	v_mfma_f32_16x16x32_bf16 v[88:91], v[28:31], v[24:27], 0
	v_add_u32_e32 v136, 0x4000, v155
	v_add_u32_e32 v140, 0x6000, v155
	v_add_u32_e32 v144, 0x8000, v155
	v_mfma_f32_16x16x32_bf16 v[174:177], v[28:31], v[20:23], 0
	ds_read2_b64 v[28:31], v133 offset0:32 offset1:36
	v_add_u32_e32 v149, 0xa000, v155
	v_add_u32_e32 v150, 0xc000, v155
	s_waitcnt lgkmcnt(0)
	v_mfma_f32_16x16x32_bf16 v[178:181], v[28:31], v[24:27], 0
	ds_read2_b64 v[238:241], v155 offset0:8 offset1:12
	v_cvt_pk_bf16_f32 v32, v118, v123
	v_cvt_pk_bf16_f32 v33, v127, v132
	v_mfma_f32_16x16x32_bf16 v[182:185], v[28:31], v[20:23], 0
	ds_read2_b64 v[28:31], v136 offset0:64 offset1:68
	v_cvt_pk_bf16_f32 v34, v139, v143
	v_cvt_pk_bf16_f32 v35, v146, v148
	s_waitcnt lgkmcnt(0)
	v_mfma_f32_16x16x32_bf16 v[186:189], v[28:31], v[24:27], 0
	v_add_u32_e32 v2, 0xe000, v155
	ds_read2_b64 v[230:233], v2 offset0:224 offset1:228
	v_cvt_pk_bf16_f32 v41, v52, v53
	v_mfma_f32_16x16x32_bf16 v[190:193], v[28:31], v[20:23], 0
	ds_read2_b64 v[28:31], v140 offset0:96 offset1:100
	v_cvt_pk_bf16_f32 v42, v55, v163
	v_cvt_pk_bf16_f32 v40, v44, v45
	s_waitcnt lgkmcnt(0)
	v_mfma_f32_16x16x32_bf16 v[194:197], v[28:31], v[24:27], 0
	v_cvt_pk_bf16_f32 v44, v111, v114
	v_cvt_pk_bf16_f32 v45, v117, v122
	v_cvt_pk_bf16_f32 v46, v130, v135
	v_mfma_f32_16x16x32_bf16 v[198:201], v[28:31], v[20:23], 0
	ds_read2_b64 v[28:31], v144 offset0:128 offset1:132
	v_cvt_pk_bf16_f32 v47, v138, v142
	v_cvt_pk_bf16_f32 v43, v164, v43
	s_waitcnt lgkmcnt(0)
	v_mfma_f32_16x16x32_bf16 v[206:209], v[28:31], v[24:27], 0
	v_cvt_pk_bf16_f32 v48, v48, v50
	v_cvt_pk_bf16_f32 v49, v49, v51
	v_cvt_pk_bf16_f32 v50, v60, v61
	v_mfma_f32_16x16x32_bf16 v[210:213], v[28:31], v[20:23], 0
	ds_read2_b64 v[28:31], v149 offset0:160 offset1:164
	v_cvt_pk_bf16_f32 v51, v63, v162
	v_cvt_pk_bf16_f32 v56, v56, v58
	s_waitcnt lgkmcnt(0)
	v_mfma_f32_16x16x32_bf16 v[214:217], v[28:31], v[24:27], 0
	v_cvt_pk_bf16_f32 v57, v57, v59
	v_cvt_pk_bf16_f32 v58, v156, v157
	v_cvt_pk_bf16_f32 v59, v158, v159
	v_mfma_f32_16x16x32_bf16 v[218:221], v[28:31], v[20:23], 0
	ds_read2_b64 v[28:31], v150 offset0:192 offset1:196
	ds_read2_b64 v[156:159], v136 offset0:96 offset1:100
	v_add_f32_e32 v92, v0, v1
	s_waitcnt lgkmcnt(1)
	v_mfma_f32_16x16x32_bf16 v[222:225], v[28:31], v[24:27], 0
	v_cvt_pk_bf16_f32 v0, v4, v5
	v_cvt_pk_bf16_f32 v3, v11, v3
	v_cvt_pk_bf16_f32 v4, v12, v13
	v_mfma_f32_16x16x32_bf16 v[226:229], v[28:31], v[20:23], 0
	v_cvt_pk_bf16_f32 v31, v171, v172
	ds_read2_b64 v[170:173], v133 offset0:40 offset1:44
	v_cvt_pk_bf16_f32 v28, v62, v160
	v_cvt_pk_bf16_f32 v29, v54, v161
	v_cvt_pk_bf16_f32 v30, v166, v169
	v_mfma_f32_16x16x32_bf16 v[234:237], v[230:233], v[24:27], 0
	ds_read2_b64 v[52:55], v133 offset0:48 offset1:52
	ds_read2_b64 v[60:63], v133 offset0:56 offset1:60
	v_cvt_pk_bf16_f32 v1, v6, v7
	v_mfma_f32_16x16x32_bf16 v[166:169], v[238:241], v[28:31], v[174:177]
	v_cvt_pk_bf16_f32 v6, v16, v17
	v_cvt_pk_bf16_f32 v16, v36, v38
	v_cvt_pk_bf16_f32 v17, v37, v39
	s_waitcnt lgkmcnt(2)
	v_mfma_f32_16x16x32_bf16 v[174:177], v[170:173], v[32:35], v[178:181]
	v_cvt_pk_bf16_f32 v38, v77, v79
	v_cvt_pk_bf16_f32 v39, v81, v95
	v_cvt_pk_bf16_f32 v5, v14, v15
	ds_read2_b64 v[178:181], v136 offset0:72 offset1:76
	v_mfma_f32_16x16x32_bf16 v[170:173], v[170:173], v[28:31], v[182:185]
	v_cvt_pk_bf16_f32 v36, v66, v69
	v_cvt_pk_bf16_f32 v37, v71, v72
	v_cvt_pk_bf16_f32 v19, v94, v19
	s_waitcnt lgkmcnt(0)
	v_mfma_f32_16x16x32_bf16 v[182:185], v[178:181], v[32:35], v[186:189]
	s_nop 2
	ds_read2_b64 v[186:189], v140 offset0:104 offset1:108
	v_cvt_pk_bf16_f32 v7, v8, v9
	v_add_u32_e32 v96, v96, v109
	v_mfma_f32_16x16x32_bf16 v[178:181], v[178:181], v[28:31], v[190:193]
	v_add_u32_e32 v98, v98, v109
	s_mov_b32 s88, s84
	v_subrev_u32_e32 v96, s84, v96
	s_waitcnt lgkmcnt(0)
	v_mfma_f32_16x16x32_bf16 v[190:193], v[186:189], v[32:35], v[194:197]
	v_subrev_u32_e32 v98, s84, v98
	s_nop 1
	ds_read2_b64 v[194:197], v144 offset0:136 offset1:140
	v_add_u32_e32 v109, 0x1c0, v99
	v_mfma_f32_16x16x32_bf16 v[186:189], v[186:189], v[28:31], v[198:201]
	s_waitcnt lgkmcnt(0)
; #define LAS __attribute__((address_space(3)))
; #define MFMA16(a, b, c) __builtin_amdgcn_mfma_f32_16x16x32_bf16((a), (b), (c), 0, 0, 0)
; __device__ __forceinline__ void xattn_softmax(f32x4 (&s)[16], bf16x8 (&pf)[8], float& rinv) {
;     ...
;     sum += __shfl_xor(sum, 16); sum += __shfl_xor(sum, 32);
;     rinv = 1.f / sum;
; __device__ __forceinline__ void xattn_pair(LAS unsigned char* lds, int bh, size_t row_base, bf16* QO, const bf16* Kx, const bf16* VTx, int tid, const WsRef& wsr) {
;     ...
;     for (int nh = 0; nh < 2; ++nh) {
;         f32x4 o0[8], o1[8];
; #pragma unroll
;         for (int n = 0; n < 8; ++n) { o0[n] = (f32x4){0.f, 0.f, 0.f, 0.f}; o1[n] = (f32x4){0.f, 0.f, 0.f, 0.f}; }
; #pragma unroll
;         for (int kk = 0; kk < 8; ++kk)
; #pragma unroll
;             for (int n = 0; n < 8; ++n) { const LAS bf16* vp = T + ((nh * 8 + n) * 16 + fr) * LDX + kk * 32 + 4 * fq;
;                 const u32x2 lo = *(const LAS u32x2*)vp, hi = *(const LAS u32x2*)(vp + 16); u32x4 w; w.x = lo.x; w.y = lo.y; w.z = hi.x; w.w = hi.y; const bf16x8 vf = __builtin_bit_cast(bf16x8, w);
;                 o0[n] = MFMA16(vf, pf0[kk], o0[n]); o1[n] = MFMA16(vf, pf1[kk], o1[n]); }
	v_mfma_f32_16x16x32_bf16 v[198:201], v[194:197], v[32:35], v[206:209]
	s_nop 2
	ds_read2_b64 v[206:209], v149 offset0:168 offset1:172
	v_mfma_f32_16x16x32_bf16 v[194:197], v[194:197], v[28:31], v[210:213]
	s_waitcnt lgkmcnt(0)
	v_mfma_f32_16x16x32_bf16 v[210:213], v[206:209], v[32:35], v[214:217]
	s_nop 2
	ds_read2_b64 v[214:217], v150 offset0:200 offset1:204
	v_mfma_f32_16x16x32_bf16 v[206:209], v[206:209], v[28:31], v[218:221]
	s_waitcnt lgkmcnt(0)
	v_mfma_f32_16x16x32_bf16 v[218:221], v[214:217], v[32:35], v[222:225]
	s_nop 2
	ds_read2_b64 v[222:225], v2 offset0:232 offset1:236
	v_mfma_f32_16x16x32_bf16 v[214:217], v[214:217], v[28:31], v[226:229]
	s_waitcnt lgkmcnt(0)
	v_mfma_f32_16x16x32_bf16 v[226:229], v[222:225], v[32:35], v[234:237]
	s_nop 2
	ds_read2_b64 v[234:237], v155 offset0:16 offset1:20
	s_waitcnt lgkmcnt(0)
	v_mfma_f32_16x16x32_bf16 v[164:167], v[234:237], v[40:43], v[166:169]
	v_mfma_f32_16x16x32_bf16 v[174:177], v[52:55], v[44:47], v[174:177]
	v_mfma_f32_16x16x32_bf16 v[168:171], v[52:55], v[40:43], v[170:173]
	ds_read2_b64 v[52:55], v136 offset0:80 offset1:84
	s_waitcnt lgkmcnt(0)
	v_mfma_f32_16x16x32_bf16 v[182:185], v[52:55], v[44:47], v[182:185]
	v_mfma_f32_16x16x32_bf16 v[178:181], v[52:55], v[40:43], v[178:181]
	ds_read2_b64 v[52:55], v140 offset0:112 offset1:116
	s_waitcnt lgkmcnt(0)
	v_mfma_f32_16x16x32_bf16 v[190:193], v[52:55], v[44:47], v[190:193]
	v_mfma_f32_16x16x32_bf16 v[186:189], v[52:55], v[40:43], v[186:189]
	ds_read2_b64 v[52:55], v144 offset0:144 offset1:148
	s_waitcnt lgkmcnt(0)
	v_mfma_f32_16x16x32_bf16 v[198:201], v[52:55], v[44:47], v[198:201]
	v_mfma_f32_16x16x32_bf16 v[194:197], v[52:55], v[40:43], v[194:197]
	ds_read2_b64 v[52:55], v149 offset0:176 offset1:180
	v_mfma_f32_16x16x32_bf16 v[88:91], v[238:241], v[32:35], v[88:91]
	s_waitcnt lgkmcnt(0)
	v_mfma_f32_16x16x32_bf16 v[210:213], v[52:55], v[44:47], v[210:213]
	v_mfma_f32_16x16x32_bf16 v[206:209], v[52:55], v[40:43], v[206:209]
	ds_read2_b64 v[52:55], v150 offset0:208 offset1:212
	v_mfma_f32_16x16x32_bf16 v[88:91], v[234:237], v[44:47], v[88:91]
	ds_read2_b64 v[234:237], v155 offset0:24 offset1:28
	s_waitcnt lgkmcnt(1)
	v_mfma_f32_16x16x32_bf16 v[218:221], v[52:55], v[44:47], v[218:221]
	v_mfma_f32_16x16x32_bf16 v[214:217], v[52:55], v[40:43], v[214:217]
	v_cvt_pk_bf16_f32 v52, v83, v102
	v_cvt_pk_bf16_f32 v53, v110, v113
	v_cvt_pk_bf16_f32 v54, v120, v125
	v_cvt_pk_bf16_f32 v55, v129, v134
	s_waitcnt lgkmcnt(0)
	v_mfma_f32_16x16x32_bf16 v[160:163], v[234:237], v[48:51], v[164:167]
	v_add_f32_e32 v102, v153, v154
	ds_bpermute_b32 v114, v64, v102
	ds_bpermute_b32 v64, v64, v92
	v_mfma_f32_16x16x32_bf16 v[164:167], v[60:63], v[52:55], v[174:177]
	v_add_u32_e32 v129, 64, v99
	s_waitcnt lgkmcnt(1)
	v_add_f32_e32 v102, v102, v114
	v_mfma_f32_16x16x32_bf16 v[168:171], v[60:63], v[48:51], v[168:171]
	ds_read2_b64 v[60:63], v136 offset0:88 offset1:92
	s_waitcnt lgkmcnt(1)
	v_add_f32_e32 v14, v92, v64
	v_div_scale_f32 v15, s[8:9], v14, v14, 1.0
	s_waitcnt lgkmcnt(0)
	v_mfma_f32_16x16x32_bf16 v[172:175], v[60:63], v[52:55], v[182:185]
	v_rcp_f32_e32 v64, v15
	v_div_scale_f32 v72, s[8:9], v102, v102, 1.0
	v_mfma_f32_16x16x32_bf16 v[176:179], v[60:63], v[48:51], v[178:181]
	ds_read2_b64 v[60:63], v140 offset0:120 offset1:124
	v_fma_f32 v8, -v15, v64, 1.0
	v_fmac_f32_e32 v64, v8, v64
	s_waitcnt lgkmcnt(0)
	v_mfma_f32_16x16x32_bf16 v[180:183], v[60:63], v[52:55], v[190:193]
	v_div_scale_f32 v8, vcc, 1.0, v14, 1.0
	v_mul_f32_e32 v9, v8, v64
	v_mfma_f32_16x16x32_bf16 v[184:187], v[60:63], v[48:51], v[186:189]
	ds_read2_b64 v[60:63], v144 offset0:152 offset1:156
	v_rcp_f32_e32 v114, v72
	v_fma_f32 v66, -v15, v9, v8
	s_waitcnt lgkmcnt(0)
	v_mfma_f32_16x16x32_bf16 v[188:191], v[60:63], v[52:55], v[198:201]
	v_fmac_f32_e32 v9, v66, v64
	v_fma_f32 v8, -v15, v9, v8
	v_div_fmas_f32 v8, v8, v64, v9
	v_mfma_f32_16x16x32_bf16 v[192:195], v[60:63], v[48:51], v[194:197]
	ds_read2_b64 v[60:63], v149 offset0:184 offset1:188
	v_cvt_pk_bf16_f32 v15, v73, v75
	v_div_scale_f32 v73, vcc, 1.0, v102, 1.0
	s_waitcnt lgkmcnt(0)
	v_mfma_f32_16x16x32_bf16 v[196:199], v[60:63], v[52:55], v[210:213]
	v_cvt_pk_bf16_f32 v9, v126, v131
	v_mfma_f32_16x16x32_bf16 v[200:203], v[60:63], v[48:51], v[206:209]
	ds_read2_b64 v[60:63], v150 offset0:216 offset1:220
	v_mfma_f32_16x16x32_bf16 v[230:233], v[230:233], v[20:23], 0
	v_mfma_f32_16x16x32_bf16 v[222:225], v[222:225], v[28:31], v[230:233]
	s_waitcnt lgkmcnt(0)
	v_mfma_f32_16x16x32_bf16 v[210:213], v[60:63], v[48:51], v[214:217]
	s_nop 4
	ds_read2_b64 v[230:233], v2 offset0:240 offset1:244
	ds_read2_b64 v[214:217], v2 offset0:248 offset1:252
	s_waitcnt lgkmcnt(1)
	v_mfma_f32_16x16x32_bf16 v[226:229], v[230:233], v[44:47], v[226:229]
	v_cvt_pk_bf16_f32 v2, v10, v18
	ds_read2_b64 v[10:13], v155 offset0:40 offset1:44
	v_cvt_pk_bf16_f32 v18, v86, v87
	v_mfma_f32_16x16x32_bf16 v[206:209], v[60:63], v[52:55], v[218:221]
	v_cvt_pk_bf16_f32 v62, v112, v115
	ds_read2_b64 v[110:113], v133 offset0:64 offset1:68
	v_cvt_pk_bf16_f32 v60, v78, v80
	s_waitcnt lgkmcnt(2)
	v_mfma_f32_16x16x32_bf16 v[218:221], v[214:217], v[52:55], v[226:229]
	v_cvt_pk_bf16_f32 v61, v82, v100
	v_cvt_pk_bf16_f32 v63, v119, v124
	v_add_u32_e32 v115, 0xe800, v155
	ds_read2_b64 v[226:229], v155 offset0:32 offset1:36
	v_mfma_f32_16x16x32_bf16 v[88:91], v[234:237], v[52:55], v[88:91]
	ds_read2_b64 v[78:81], v133 offset0:72 offset1:76
	v_div_fixup_f32 v100, v8, v14, 1.0
	v_cvt_pk_bf16_f32 v8, v116, v121
	s_waitcnt lgkmcnt(2)
	v_mfma_f32_16x16x32_bf16 v[122:125], v[110:113], v[60:63], v[164:167]
	v_cvt_pk_bf16_f32 v14, v74, v76
	s_nop 1
	ds_read2_b64 v[164:167], v140 offset0:128 offset1:132
	s_waitcnt lgkmcnt(2)
; #define LAS __attribute__((address_space(3)))
; __device__ __forceinline__ unsigned pk2(float lo, float hi) { return pg8::cvt_pk_bf16(lo, hi); }
; __device__ __forceinline__ void wt_store8(const WsRef& w, const void* p, u32x2 v) { __builtin_amdgcn_raw_buffer_store_b64(v, w.r, (unsigned)((const unsigned char*)p - w.base), 0, 16); }
; #define MFMA16(a, b, c) __builtin_amdgcn_mfma_f32_16x16x32_bf16((a), (b), (c), 0, 0, 0)
; __device__ __forceinline__ void xattn_pair(LAS unsigned char* lds, int bh, size_t row_base, bf16* QO, const bf16* Kx, const bf16* VTx, int tid, const WsRef& wsr) {
;     ...
;     for (int nh = 0; nh < 2; ++nh) {
;         f32x4 o0[8], o1[8];
; #pragma unroll
;         for (int n = 0; n < 8; ++n) { o0[n] = (f32x4){0.f, 0.f, 0.f, 0.f}; o1[n] = (f32x4){0.f, 0.f, 0.f, 0.f}; }
; #pragma unroll
;         for (int kk = 0; kk < 8; ++kk)
; #pragma unroll
;             for (int n = 0; n < 8; ++n) { const LAS bf16* vp = T + ((nh * 8 + n) * 16 + fr) * LDX + kk * 32 + 4 * fq;
;                 const u32x2 lo = *(const LAS u32x2*)vp, hi = *(const LAS u32x2*)(vp + 16); u32x4 w; w.x = lo.x; w.y = lo.y; w.z = hi.x; w.w = hi.y; const bf16x8 vf = __builtin_bit_cast(bf16x8, w);
;                 o0[n] = MFMA16(vf, pf0[kk], o0[n]); o1[n] = MFMA16(vf, pf1[kk], o1[n]); }
; #pragma unroll
;         for (int n = 0; n < 8; ++n) { const f32x4 v0 = o0[n] * rinv0, v1 = o1[n] * rinv1; u32x2 w0, w1; w0.x = pk2(v0[0], v0[1]); w0.y = pk2(v0[2], v0[3]); w1.x = pk2(v1[0], v1[1]); w1.y = pk2(v1[2], v1[3]);
;             wt_store8(wsr, qp0 + (nh * 8 + n) * 16 + 4 * fq, w0); wt_store8(wsr, qp1 + (nh * 8 + n) * 16 + 4 * fq, w1); }
	v_mfma_f32_16x16x32_bf16 v[82:85], v[226:229], v[60:63], v[88:91]
	v_mfma_f32_16x16x32_bf16 v[88:91], v[226:229], v[56:59], v[160:163]
	v_mfma_f32_16x16x32_bf16 v[160:163], v[156:159], v[60:63], v[172:175]
	s_nop 2
	ds_read2_b64 v[172:175], v144 offset0:160 offset1:164
	v_mfma_f32_16x16x32_bf16 v[110:113], v[110:113], v[56:59], v[168:171]
	s_waitcnt lgkmcnt(1)
	v_mfma_f32_16x16x32_bf16 v[168:171], v[164:167], v[60:63], v[180:183]
	v_mfma_f32_16x16x32_bf16 v[164:167], v[164:167], v[56:59], v[184:187]
	s_nop 1
	ds_read2_b64 v[180:183], v149 offset0:192 offset1:196
	ds_read2_b64 v[184:187], v150 offset0:224 offset1:228
	v_mfma_f32_16x16x32_bf16 v[156:159], v[156:159], v[56:59], v[176:179]
	s_waitcnt lgkmcnt(2)
	v_mfma_f32_16x16x32_bf16 v[176:179], v[172:175], v[60:63], v[188:191]
	v_mfma_f32_16x16x32_bf16 v[172:175], v[172:175], v[56:59], v[192:195]
	s_nop 2
	ds_read2_b64 v[192:195], v115 offset1:4
	v_mfma_f32_16x16x32_bf16 v[222:225], v[230:233], v[40:43], v[222:225]
	v_mfma_f32_16x16x32_bf16 v[214:217], v[214:217], v[48:51], v[222:225]
	s_waitcnt lgkmcnt(2)
	v_mfma_f32_16x16x32_bf16 v[188:191], v[180:183], v[60:63], v[196:199]
	s_waitcnt lgkmcnt(1)
	v_mfma_f32_16x16x32_bf16 v[196:199], v[184:187], v[60:63], v[206:209]
	v_mfma_f32_16x16x32_bf16 v[184:187], v[184:187], v[56:59], v[210:213]
	v_mfma_f32_16x16x32_bf16 v[206:209], v[10:13], v[36:39], v[82:85]
	v_mfma_f32_16x16x32_bf16 v[210:213], v[10:13], v[16:19], v[88:91]
	ds_read2_b64 v[10:13], v136 offset0:104 offset1:108
	s_nop 0
	ds_read2_b64 v[82:85], v144 offset0:168 offset1:172
	v_mfma_f32_16x16x32_bf16 v[180:183], v[180:183], v[56:59], v[200:203]
	s_waitcnt lgkmcnt(2)
	v_mfma_f32_16x16x32_bf16 v[200:203], v[192:195], v[60:63], v[218:221]
	v_mfma_f32_16x16x32_bf16 v[192:195], v[192:195], v[56:59], v[214:217]
	v_mfma_f32_16x16x32_bf16 v[122:125], v[78:81], v[36:39], v[122:125]
	v_mfma_f32_16x16x32_bf16 v[214:217], v[78:81], v[16:19], v[110:113]
	ds_read2_b64 v[78:81], v140 offset0:136 offset1:140
	s_nop 1
	ds_read2_b64 v[110:113], v149 offset0:200 offset1:204
	s_waitcnt lgkmcnt(3)
	v_mfma_f32_16x16x32_bf16 v[160:163], v[10:13], v[36:39], v[160:163]
	v_mfma_f32_16x16x32_bf16 v[156:159], v[10:13], v[16:19], v[156:159]
	v_cvt_pk_bf16_f32 v12, v65, v68
	v_cvt_pk_bf16_f32 v13, v67, v70
	ds_read2_b64 v[64:67], v150 offset0:232 offset1:236
	v_fma_f32 v68, -v72, v114, 1.0
	s_waitcnt lgkmcnt(3)
	v_mfma_f32_16x16x32_bf16 v[88:91], v[82:85], v[16:19], v[172:175]
	v_fmac_f32_e32 v114, v68, v114
	ds_read2_b64 v[68:71], v115 offset0:8 offset1:12
	v_cvt_pk_bf16_f32 v10, v137, v141
	ds_read2_b64 v[172:175], v133 offset0:80 offset1:84
	s_waitcnt lgkmcnt(4)
	v_mfma_f32_16x16x32_bf16 v[116:119], v[78:81], v[16:19], v[164:167]
	v_cvt_pk_bf16_f32 v11, v145, v147
	s_nop 1
	ds_read2_b64 v[164:167], v155 offset0:48 offset1:52
	v_mfma_f32_16x16x32_bf16 v[168:171], v[78:81], v[36:39], v[168:171]
	v_mfma_f32_16x16x32_bf16 v[92:95], v[82:85], v[36:39], v[176:179]
	s_waitcnt lgkmcnt(4)
	v_mfma_f32_16x16x32_bf16 v[80:83], v[110:113], v[36:39], v[188:191]
	v_mfma_f32_16x16x32_bf16 v[84:87], v[110:113], v[16:19], v[180:183]
	v_mul_f32_e32 v110, v73, v114
	v_fma_f32 v74, -v72, v110, v73
	v_fmac_f32_e32 v110, v74, v114
	v_fma_f32 v111, -v72, v110, v73
	s_waitcnt lgkmcnt(3)
	v_mfma_f32_16x16x32_bf16 v[76:79], v[64:67], v[36:39], v[196:199]
	v_add_u32_e32 v113, 0xc0, v99
	v_add_u32_e32 v112, 0x100, v99
	v_mfma_f32_16x16x32_bf16 v[72:75], v[64:67], v[16:19], v[184:187]
	v_div_fmas_f32 v64, v111, v114, v110
	v_div_fixup_f32 v102, v64, v102, 1.0
	ds_read2_b64 v[180:183], v136 offset0:112 offset1:116
	ds_read2_b64 v[184:187], v140 offset0:144 offset1:148
	ds_read2_b64 v[188:191], v144 offset0:176 offset1:180
	s_waitcnt lgkmcnt(5)
	v_mfma_f32_16x16x32_bf16 v[64:67], v[68:71], v[36:39], v[200:203]
	v_add_u32_e32 v114, 0x80, v99
	v_add_u32_e32 v111, 0x140, v99
	v_add_u32_e32 v110, 0x180, v99
	v_mfma_f32_16x16x32_bf16 v[68:71], v[68:71], v[16:19], v[192:195]
	s_waitcnt lgkmcnt(4)
	v_mfma_f32_16x16x32_bf16 v[120:123], v[172:175], v[12:15], v[122:125]
	s_nop 2
	ds_read2_b64 v[124:127], v149 offset0:208 offset1:212
	ds_read2_b64 v[192:195], v150 offset0:240 offset1:244
	ds_read2_b64 v[152:155], v155 offset0:56 offset1:60
	ds_read2_b64 v[130:133], v133 offset0:88 offset1:92
	ds_read2_b64 v[196:199], v115 offset0:16 offset1:20
	s_waitcnt lgkmcnt(8)
	v_mfma_f32_16x16x32_bf16 v[176:179], v[164:167], v[12:15], v[206:209]
	ds_read2_b64 v[134:137], v136 offset0:120 offset1:124
	ds_read2_b64 v[138:141], v140 offset0:152 offset1:156
	ds_read2_b64 v[142:145], v144 offset0:184 offset1:188
	ds_read2_b64 v[146:149], v149 offset0:216 offset1:220
	ds_read2_b64 v[200:203], v150 offset0:248 offset1:252
	ds_read2_b64 v[206:209], v115 offset0:24 offset1:28
	v_mfma_f32_16x16x32_bf16 v[164:167], v[164:167], v[4:7], v[210:213]
	s_waitcnt lgkmcnt(8)
	v_mfma_f32_16x16x32_bf16 v[176:179], v[152:155], v[8:11], v[176:179]
	v_mfma_f32_16x16x32_bf16 v[150:153], v[152:155], v[0:3], v[164:167]
	v_mfma_f32_16x16x32_bf16 v[172:175], v[172:175], v[4:7], v[214:217]
	s_nop 5
	v_mul_f32_e64 v164, v102, v178
	v_mul_f32_e64 v165, v102, v179
	v_pk_mul_f32 v[166:167], v[102:103], v[176:177] op_sel_hi:[0,1]
	v_pk_mul_f32 v[176:177], v[100:101], v[152:153] op_sel_hi:[0,1]
	s_waitcnt lgkmcnt(7)
	v_mfma_f32_16x16x32_bf16 v[120:123], v[130:133], v[8:11], v[120:123]
	v_mul_f32_e64 v150, v100, v150
	v_mul_f32_e64 v151, v100, v151
	v_cvt_pk_bf16_f32 v166, v166, v167
	v_cvt_pk_bf16_f32 v167, v164, v165
	v_cvt_pk_bf16_f32 v150, v150, v151
	v_cvt_pk_bf16_f32 v151, v176, v177
	v_readlane_b32 vcc_lo, v255, 59
	s_mov_b32 vcc_hi, 0
	s_nop 1
	s_mov_b64 vcc, vcc
	s_nop 1
	s_cbranch_vccnz .Lpp8_plain
; #define LAS __attribute__((address_space(3)))
; __device__ __forceinline__ unsigned pk2(float lo, float hi) { return pg8::cvt_pk_bf16(lo, hi); }
; __device__ __forceinline__ void wt_store8(const WsRef& w, const void* p, u32x2 v) { __builtin_amdgcn_raw_buffer_store_b64(v, w.r, (unsigned)((const unsigned char*)p - w.base), 0, 16); }
; #define MFMA16(a, b, c) __builtin_amdgcn_mfma_f32_16x16x32_bf16((a), (b), (c), 0, 0, 0)
; __device__ __forceinline__ void xattn_pair(LAS unsigned char* lds, int bh, size_t row_base, bf16* QO, const bf16* Kx, const bf16* VTx, int tid, const WsRef& wsr) {
;     ...
;     for (int nh = 0; nh < 2; ++nh) {
;         f32x4 o0[8], o1[8];
; #pragma unroll
;         for (int n = 0; n < 8; ++n) { o0[n] = (f32x4){0.f, 0.f, 0.f, 0.f}; o1[n] = (f32x4){0.f, 0.f, 0.f, 0.f}; }
; #pragma unroll
;         for (int kk = 0; kk < 8; ++kk)
; #pragma unroll
;             for (int n = 0; n < 8; ++n) { const LAS bf16* vp = T + ((nh * 8 + n) * 16 + fr) * LDX + kk * 32 + 4 * fq;
;                 const u32x2 lo = *(const LAS u32x2*)vp, hi = *(const LAS u32x2*)(vp + 16); u32x4 w; w.x = lo.x; w.y = lo.y; w.z = hi.x; w.w = hi.y; const bf16x8 vf = __builtin_bit_cast(bf16x8, w);
;                 o0[n] = MFMA16(vf, pf0[kk], o0[n]); o1[n] = MFMA16(vf, pf1[kk], o1[n]); }
; #pragma unroll
;         for (int n = 0; n < 8; ++n) { const f32x4 v0 = o0[n] * rinv0, v1 = o1[n] * rinv1; u32x2 w0, w1; w0.x = pk2(v0[0], v0[1]); w0.y = pk2(v0[2], v0[3]); w1.x = pk2(v1[0], v1[1]); w1.y = pk2(v1[2], v1[3]);
;             wt_store8(wsr, qp0 + (nh * 8 + n) * 16 + 4 * fq, w0); wt_store8(wsr, qp1 + (nh * 8 + n) * 16 + 4 * fq, w1); }
;         __builtin_amdgcn_sched_barrier(0);
	buffer_store_dwordx2 v[166:167], v96, s[88:91], 0 offen sc1
	buffer_store_dwordx2 v[150:151], v98, s[88:91], 0 offen sc1
	v_pk_mul_f32 v[150:151], v[102:103], v[122:123] op_sel_hi:[0,1]
	v_pk_mul_f32 v[164:165], v[102:103], v[120:121] op_sel_hi:[0,1]
	v_mfma_f32_16x16x32_bf16 v[120:123], v[130:133], v[0:3], v[172:175]
	v_cvt_pk_bf16_f32 v130, v164, v165
	v_cvt_pk_bf16_f32 v131, v150, v151
	v_mfma_f32_16x16x32_bf16 v[160:163], v[180:183], v[12:15], v[160:163]
	v_mfma_f32_16x16x32_bf16 v[152:155], v[180:183], v[4:7], v[156:159]
	s_nop 3
	v_mul_f32_e64 v122, v100, v122
	v_mul_f32_e64 v123, v100, v123
	v_pk_mul_f32 v[120:121], v[100:101], v[120:121] op_sel_hi:[0,1]
	v_cvt_pk_bf16_f32 v132, v120, v121
	v_cvt_pk_bf16_f32 v133, v122, v123
	s_waitcnt lgkmcnt(5)
	v_mfma_f32_16x16x32_bf16 v[120:123], v[134:137], v[8:11], v[160:163]
	buffer_store_dwordx2 v[130:131], v96, s[88:91], 0 offen offset:32 sc1
	buffer_store_dwordx2 v[132:133], v98, s[88:91], 0 offen offset:32 sc1
	v_mfma_f32_16x16x32_bf16 v[156:159], v[184:187], v[12:15], v[168:171]
	s_nop 4
	v_mul_f32_e64 v122, v102, v122
	v_mul_f32_e64 v123, v102, v123
	v_pk_mul_f32 v[120:121], v[102:103], v[120:121] op_sel_hi:[0,1]
	v_mfma_f32_16x16x32_bf16 v[116:119], v[184:187], v[4:7], v[116:119]
	v_mfma_f32_16x16x32_bf16 v[92:95], v[188:191], v[12:15], v[92:95]
	v_mfma_f32_16x16x32_bf16 v[88:91], v[188:191], v[4:7], v[88:91]
	v_mfma_f32_16x16x32_bf16 v[80:83], v[124:127], v[12:15], v[80:83]
	v_mfma_f32_16x16x32_bf16 v[130:133], v[134:137], v[0:3], v[152:155]
	v_cvt_pk_bf16_f32 v134, v120, v121
	v_cvt_pk_bf16_f32 v135, v122, v123
	s_waitcnt lgkmcnt(4)
	v_mfma_f32_16x16x32_bf16 v[120:123], v[138:141], v[8:11], v[156:159]
	v_mfma_f32_16x16x32_bf16 v[116:119], v[138:141], v[0:3], v[116:119]
	s_nop 2
	v_mul_f32_e64 v132, v100, v132
	v_mul_f32_e64 v133, v100, v133
	s_nop 1
	v_pk_mul_f32 v[122:123], v[102:103], v[122:123] op_sel_hi:[0,1]
	v_pk_mul_f32 v[120:121], v[102:103], v[120:121] op_sel_hi:[0,1]
	s_waitcnt lgkmcnt(3)
	v_mfma_f32_16x16x32_bf16 v[92:95], v[142:145], v[8:11], v[92:95]
	v_mul_f32_e64 v130, v100, v130
	v_mul_f32_e64 v131, v100, v131
	v_pk_mul_f32 v[118:119], v[100:101], v[118:119] op_sel_hi:[0,1]
	v_pk_mul_f32 v[116:117], v[100:101], v[116:117] op_sel_hi:[0,1]
	v_mfma_f32_16x16x32_bf16 v[88:91], v[142:145], v[0:3], v[88:91]
	v_cvt_pk_bf16_f32 v120, v120, v121
	s_nop 1
	v_pk_mul_f32 v[94:95], v[102:103], v[94:95] op_sel_hi:[0,1]
	v_pk_mul_f32 v[92:93], v[102:103], v[92:93] op_sel_hi:[0,1]
	v_mfma_f32_16x16x32_bf16 v[76:79], v[192:195], v[12:15], v[76:79]
	v_cvt_pk_bf16_f32 v121, v122, v123
	s_nop 0
	v_pk_mul_f32 v[90:91], v[100:101], v[90:91] op_sel_hi:[0,1]
	v_pk_mul_f32 v[88:89], v[100:101], v[88:89] op_sel_hi:[0,1]
	v_mfma_f32_16x16x32_bf16 v[72:75], v[192:195], v[4:7], v[72:75]
	v_cvt_pk_bf16_f32 v116, v116, v117
	v_cvt_pk_bf16_f32 v117, v118, v119
	v_cvt_pk_bf16_f32 v92, v92, v93
	v_mfma_f32_16x16x32_bf16 v[84:87], v[124:127], v[4:7], v[84:87]
	v_cvt_pk_bf16_f32 v93, v94, v95
	v_cvt_pk_bf16_f32 v88, v88, v89
	v_cvt_pk_bf16_f32 v89, v90, v91
	s_waitcnt lgkmcnt(2)
	v_mfma_f32_16x16x32_bf16 v[80:83], v[146:149], v[8:11], v[80:83]
	v_cvt_pk_bf16_f32 v130, v130, v131
	v_cvt_pk_bf16_f32 v131, v132, v133
	buffer_store_dwordx2 v[134:135], v96, s[88:91], 0 offen offset:64 sc1
	buffer_store_dwordx2 v[130:131], v98, s[88:91], 0 offen offset:64 sc1
	v_mfma_f32_16x16x32_bf16 v[64:67], v[196:199], v[12:15], v[64:67]
	buffer_store_dwordx2 v[120:121], v96, s[88:91], 0 offen offset:96 sc1
	buffer_store_dwordx2 v[116:117], v98, s[88:91], 0 offen offset:96 sc1
	buffer_store_dwordx2 v[92:93], v96, s[88:91], 0 offen offset:128 sc1
	buffer_store_dwordx2 v[88:89], v98, s[88:91], 0 offen offset:128 sc1
	s_waitcnt lgkmcnt(1)
	v_mfma_f32_16x16x32_bf16 v[76:79], v[200:203], v[8:11], v[76:79]
	v_mul_f32_e64 v88, v102, v82
	v_mul_f32_e64 v89, v102, v83
	v_pk_mul_f32 v[80:81], v[102:103], v[80:81] op_sel_hi:[0,1]
	v_cvt_pk_bf16_f32 v80, v80, v81
	v_mfma_f32_16x16x32_bf16 v[72:75], v[200:203], v[0:3], v[72:75]
	v_cvt_pk_bf16_f32 v81, v88, v89
	s_nop 1
	v_pk_mul_f32 v[78:79], v[102:103], v[78:79] op_sel_hi:[0,1]
	v_pk_mul_f32 v[76:77], v[102:103], v[76:77] op_sel_hi:[0,1]
	v_mfma_f32_16x16x32_bf16 v[82:85], v[146:149], v[0:3], v[84:87]
	v_cvt_pk_bf16_f32 v76, v76, v77
	s_nop 0
	v_pk_mul_f32 v[74:75], v[100:101], v[74:75] op_sel_hi:[0,1]
	v_pk_mul_f32 v[72:73], v[100:101], v[72:73] op_sel_hi:[0,1]
	v_mfma_f32_16x16x32_bf16 v[68:71], v[196:199], v[4:7], v[68:71]
	v_cvt_pk_bf16_f32 v77, v78, v79
	s_nop 1
	v_pk_mul_f32 v[84:85], v[100:101], v[84:85] op_sel_hi:[0,1]
	v_pk_mul_f32 v[82:83], v[100:101], v[82:83] op_sel_hi:[0,1]
	s_waitcnt lgkmcnt(0)
	v_mfma_f32_16x16x32_bf16 v[64:67], v[206:209], v[8:11], v[64:67]
	v_cvt_pk_bf16_f32 v72, v72, v73
	v_cvt_pk_bf16_f32 v73, v74, v75
	v_cvt_pk_bf16_f32 v82, v82, v83
	v_cvt_pk_bf16_f32 v83, v84, v85
	buffer_store_dwordx2 v[80:81], v96, s[88:91], 0 offen offset:160 sc1
	buffer_store_dwordx2 v[82:83], v98, s[88:91], 0 offen offset:160 sc1
	buffer_store_dwordx2 v[76:77], v96, s[88:91], 0 offen offset:192 sc1
	buffer_store_dwordx2 v[72:73], v98, s[88:91], 0 offen offset:192 sc1
	v_pk_mul_f32 v[72:73], v[102:103], v[66:67] op_sel_hi:[0,1]
	v_pk_mul_f32 v[74:75], v[102:103], v[64:65] op_sel_hi:[0,1]
	v_mfma_f32_16x16x32_bf16 v[64:67], v[206:209], v[0:3], v[68:71]
	s_nop 2
	v_cvt_pk_bf16_f32 v68, v74, v75
	v_cvt_pk_bf16_f32 v69, v72, v73
	s_nop 2
	v_pk_mul_f32 v[66:67], v[100:101], v[66:67] op_sel_hi:[0,1]
	v_pk_mul_f32 v[64:65], v[100:101], v[64:65] op_sel_hi:[0,1]
	v_cvt_pk_bf16_f32 v64, v64, v65
	v_cvt_pk_bf16_f32 v65, v66, v67
	buffer_store_dwordx2 v[68:69], v96, s[88:91], 0 offen offset:224 sc1
	buffer_store_dwordx2 v[64:65], v98, s[88:91], 0 offen offset:224 sc1
	v_add_u32_e32 v115, v99, v107
	ds_read2_b64 v[116:119], v115 offset1:4
	v_add_u32_e32 v115, v99, v105
	v_add_u32_e32 v64, v99, v97
	v_add_u32_e32 v72, v99, v103
	v_add_u32_e32 v80, v99, v106
	v_add_u32_e32 v88, v99, v108
	ds_read2_b64 v[124:127], v115 offset1:4
	v_add_u32_e32 v115, v99, v104
	v_add_u32_e32 v99, v99, v101
	ds_read2_b64 v[64:67], v64 offset1:4
	ds_read2_b64 v[72:75], v72 offset1:4
	ds_read2_b64 v[80:83], v80 offset1:4
	ds_read2_b64 v[88:91], v88 offset1:4
	ds_read2_b64 v[134:137], v115 offset1:4
	ds_read2_b64 v[142:145], v99 offset1:4
	v_add_u32_e32 v99, v129, v97
	s_waitcnt lgkmcnt(5)
; #define LAS __attribute__((address_space(3)))
; #define MFMA16(a, b, c) __builtin_amdgcn_mfma_f32_16x16x32_bf16((a), (b), (c), 0, 0, 0)
; __device__ __forceinline__ void xattn_pair(LAS unsigned char* lds, int bh, size_t row_base, bf16* QO, const bf16* Kx, const bf16* VTx, int tid, const WsRef& wsr) {
;     ...
; #pragma unroll
;         for (int kk = 0; kk < 8; ++kk)
; #pragma unroll
;             for (int n = 0; n < 8; ++n) { const LAS bf16* vp = T + ((nh * 8 + n) * 16 + fr) * LDX + kk * 32 + 4 * fq;
;                 const u32x2 lo = *(const LAS u32x2*)vp, hi = *(const LAS u32x2*)(vp + 16); u32x4 w; w.x = lo.x; w.y = lo.y; w.z = hi.x; w.w = hi.y; const bf16x8 vf = __builtin_bit_cast(bf16x8, w);
;                 o0[n] = MFMA16(vf, pf0[kk], o0[n]); o1[n] = MFMA16(vf, pf1[kk], o1[n]); }
	v_mfma_f32_16x16x32_bf16 v[68:71], v[64:67], v[24:27], 0
	v_mfma_f32_16x16x32_bf16 v[64:67], v[64:67], v[20:23], 0
	s_waitcnt lgkmcnt(4)
	v_mfma_f32_16x16x32_bf16 v[76:79], v[72:75], v[24:27], 0
	v_mfma_f32_16x16x32_bf16 v[72:75], v[72:75], v[20:23], 0
	s_waitcnt lgkmcnt(3)
	v_mfma_f32_16x16x32_bf16 v[84:87], v[80:83], v[24:27], 0
	v_mfma_f32_16x16x32_bf16 v[80:83], v[80:83], v[20:23], 0
	s_waitcnt lgkmcnt(2)
	v_mfma_f32_16x16x32_bf16 v[92:95], v[88:91], v[24:27], 0
	v_mfma_f32_16x16x32_bf16 v[88:91], v[88:91], v[20:23], 0
	v_mfma_f32_16x16x32_bf16 v[120:123], v[116:119], v[24:27], 0
	v_mfma_f32_16x16x32_bf16 v[116:119], v[116:119], v[20:23], 0
	v_mfma_f32_16x16x32_bf16 v[130:133], v[124:127], v[24:27], 0
	v_mfma_f32_16x16x32_bf16 v[124:127], v[124:127], v[20:23], 0
	s_waitcnt lgkmcnt(1)
	v_mfma_f32_16x16x32_bf16 v[138:141], v[134:137], v[24:27], 0
	v_mfma_f32_16x16x32_bf16 v[134:137], v[134:137], v[20:23], 0
	s_waitcnt lgkmcnt(0)
	v_mfma_f32_16x16x32_bf16 v[24:27], v[142:145], v[24:27], 0
	v_mfma_f32_16x16x32_bf16 v[20:23], v[142:145], v[20:23], 0
	ds_read2_b64 v[142:145], v99 offset1:4
	v_add_u32_e32 v99, v129, v103
	s_waitcnt lgkmcnt(0)
	v_mfma_f32_16x16x32_bf16 v[68:71], v[142:145], v[32:35], v[68:71]
	v_mfma_f32_16x16x32_bf16 v[64:67], v[142:145], v[28:31], v[64:67]
	ds_read2_b64 v[142:145], v99 offset1:4
	v_add_u32_e32 v99, v129, v106
	s_waitcnt lgkmcnt(0)
	v_mfma_f32_16x16x32_bf16 v[76:79], v[142:145], v[32:35], v[76:79]
	v_mfma_f32_16x16x32_bf16 v[72:75], v[142:145], v[28:31], v[72:75]
	ds_read2_b64 v[142:145], v99 offset1:4
	v_add_u32_e32 v99, v129, v108
	s_waitcnt lgkmcnt(0)
	v_mfma_f32_16x16x32_bf16 v[84:87], v[142:145], v[32:35], v[84:87]
	v_mfma_f32_16x16x32_bf16 v[80:83], v[142:145], v[28:31], v[80:83]
	ds_read2_b64 v[142:145], v99 offset1:4
	v_add_u32_e32 v99, v129, v107
	s_waitcnt lgkmcnt(0)
	v_mfma_f32_16x16x32_bf16 v[92:95], v[142:145], v[32:35], v[92:95]
	v_mfma_f32_16x16x32_bf16 v[88:91], v[142:145], v[28:31], v[88:91]
	ds_read2_b64 v[142:145], v99 offset1:4
	v_add_u32_e32 v99, v129, v105
	s_waitcnt lgkmcnt(0)
	v_mfma_f32_16x16x32_bf16 v[120:123], v[142:145], v[32:35], v[120:123]
	v_mfma_f32_16x16x32_bf16 v[116:119], v[142:145], v[28:31], v[116:119]
	ds_read2_b64 v[142:145], v99 offset1:4
	v_add_u32_e32 v99, v129, v104
	s_waitcnt lgkmcnt(0)
	v_mfma_f32_16x16x32_bf16 v[130:133], v[142:145], v[32:35], v[130:133]
	v_mfma_f32_16x16x32_bf16 v[124:127], v[142:145], v[28:31], v[124:127]
	ds_read2_b64 v[142:145], v99 offset1:4
	v_add_u32_e32 v99, v129, v101
	s_waitcnt lgkmcnt(0)
	v_mfma_f32_16x16x32_bf16 v[138:141], v[142:145], v[32:35], v[138:141]
	v_mfma_f32_16x16x32_bf16 v[134:137], v[142:145], v[28:31], v[134:137]
	ds_read2_b64 v[142:145], v99 offset1:4
	v_add_u32_e32 v99, v114, v105
	s_waitcnt lgkmcnt(0)
	v_mfma_f32_16x16x32_bf16 v[20:23], v[142:145], v[28:31], v[20:23]
	v_add_u32_e32 v28, v114, v97
	ds_read2_b64 v[28:31], v28 offset1:4
	v_mfma_f32_16x16x32_bf16 v[24:27], v[142:145], v[32:35], v[24:27]
	s_waitcnt lgkmcnt(0)
	v_mfma_f32_16x16x32_bf16 v[32:35], v[28:31], v[44:47], v[68:71]
	v_mfma_f32_16x16x32_bf16 v[28:31], v[28:31], v[40:43], v[64:67]
	s_nop 2
	v_add_u32_e32 v64, v114, v103
	ds_read2_b64 v[64:67], v64 offset1:4
	s_waitcnt lgkmcnt(0)
	v_mfma_f32_16x16x32_bf16 v[68:71], v[64:67], v[44:47], v[76:79]
	v_mfma_f32_16x16x32_bf16 v[64:67], v[64:67], v[40:43], v[72:75]
	s_nop 2
	v_add_u32_e32 v72, v114, v106
	ds_read2_b64 v[72:75], v72 offset1:4
	s_waitcnt lgkmcnt(0)
	v_mfma_f32_16x16x32_bf16 v[76:79], v[72:75], v[44:47], v[84:87]
	v_mfma_f32_16x16x32_bf16 v[72:75], v[72:75], v[40:43], v[80:83]
	s_nop 2
	v_add_u32_e32 v80, v114, v108
	ds_read2_b64 v[80:83], v80 offset1:4
	s_waitcnt lgkmcnt(0)
	v_mfma_f32_16x16x32_bf16 v[84:87], v[80:83], v[44:47], v[92:95]
	v_mfma_f32_16x16x32_bf16 v[80:83], v[80:83], v[40:43], v[88:91]
	s_nop 2
	v_add_u32_e32 v88, v114, v107
	ds_read2_b64 v[88:91], v88 offset1:4
	s_waitcnt lgkmcnt(0)
	v_mfma_f32_16x16x32_bf16 v[92:95], v[88:91], v[44:47], v[120:123]
	v_mfma_f32_16x16x32_bf16 v[88:91], v[88:91], v[40:43], v[116:119]
	s_nop 2
	ds_read2_b64 v[116:119], v99 offset1:4
	v_add_u32_e32 v99, v114, v104
	s_waitcnt lgkmcnt(0)
	v_mfma_f32_16x16x32_bf16 v[120:123], v[116:119], v[44:47], v[130:133]
	v_mfma_f32_16x16x32_bf16 v[116:119], v[116:119], v[40:43], v[124:127]
	s_nop 2
	ds_read2_b64 v[124:127], v99 offset1:4
	v_add_u32_e32 v99, v114, v101
	s_waitcnt lgkmcnt(0)
	v_mfma_f32_16x16x32_bf16 v[130:133], v[124:127], v[44:47], v[138:141]
	v_mfma_f32_16x16x32_bf16 v[124:127], v[124:127], v[40:43], v[134:137]
	s_nop 2
	ds_read2_b64 v[134:137], v99 offset1:4
	s_waitcnt lgkmcnt(0)
	v_mfma_f32_16x16x32_bf16 v[20:23], v[134:137], v[40:43], v[20:23]
	v_add_u32_e32 v40, v113, v97
	ds_read2_b64 v[40:43], v40 offset1:4
	v_add_u32_e32 v99, v113, v104
	s_waitcnt lgkmcnt(0)
	v_mfma_f32_16x16x32_bf16 v[32:35], v[40:43], v[52:55], v[32:35]
	v_mfma_f32_16x16x32_bf16 v[28:31], v[40:43], v[48:51], v[28:31]
	v_add_u32_e32 v40, v113, v103
	ds_read2_b64 v[40:43], v40 offset1:4
	v_mfma_f32_16x16x32_bf16 v[24:27], v[134:137], v[44:47], v[24:27]
	s_waitcnt lgkmcnt(0)
	v_mfma_f32_16x16x32_bf16 v[44:47], v[40:43], v[52:55], v[68:71]
	v_mfma_f32_16x16x32_bf16 v[40:43], v[40:43], v[48:51], v[64:67]
	s_nop 2
	v_add_u32_e32 v64, v113, v106
	ds_read2_b64 v[64:67], v64 offset1:4
	s_waitcnt lgkmcnt(0)
	v_mfma_f32_16x16x32_bf16 v[68:71], v[64:67], v[52:55], v[76:79]
	v_mfma_f32_16x16x32_bf16 v[64:67], v[64:67], v[48:51], v[72:75]
	s_nop 2
	v_add_u32_e32 v72, v113, v108
	ds_read2_b64 v[72:75], v72 offset1:4
	s_waitcnt lgkmcnt(0)
; #define LAS __attribute__((address_space(3)))
; #define MFMA16(a, b, c) __builtin_amdgcn_mfma_f32_16x16x32_bf16((a), (b), (c), 0, 0, 0)
; __device__ __forceinline__ void xattn_pair(LAS unsigned char* lds, int bh, size_t row_base, bf16* QO, const bf16* Kx, const bf16* VTx, int tid, const WsRef& wsr) {
;     ...
; #pragma unroll
;         for (int kk = 0; kk < 8; ++kk)
; #pragma unroll
;             for (int n = 0; n < 8; ++n) { const LAS bf16* vp = T + ((nh * 8 + n) * 16 + fr) * LDX + kk * 32 + 4 * fq;
;                 const u32x2 lo = *(const LAS u32x2*)vp, hi = *(const LAS u32x2*)(vp + 16); u32x4 w; w.x = lo.x; w.y = lo.y; w.z = hi.x; w.w = hi.y; const bf16x8 vf = __builtin_bit_cast(bf16x8, w);
;                 o0[n] = MFMA16(vf, pf0[kk], o0[n]); o1[n] = MFMA16(vf, pf1[kk], o1[n]); }
	v_mfma_f32_16x16x32_bf16 v[76:79], v[72:75], v[52:55], v[84:87]
	v_mfma_f32_16x16x32_bf16 v[72:75], v[72:75], v[48:51], v[80:83]
	s_nop 2
	v_add_u32_e32 v80, v113, v107
	ds_read2_b64 v[80:83], v80 offset1:4
	s_waitcnt lgkmcnt(0)
	v_mfma_f32_16x16x32_bf16 v[84:87], v[80:83], v[52:55], v[92:95]
	v_mfma_f32_16x16x32_bf16 v[80:83], v[80:83], v[48:51], v[88:91]
	s_nop 2
	v_add_u32_e32 v88, v113, v105
	ds_read2_b64 v[88:91], v88 offset1:4
	s_waitcnt lgkmcnt(0)
	v_mfma_f32_16x16x32_bf16 v[92:95], v[88:91], v[52:55], v[120:123]
	v_mfma_f32_16x16x32_bf16 v[88:91], v[88:91], v[48:51], v[116:119]
	s_nop 2
	ds_read2_b64 v[114:117], v99 offset1:4
	v_add_u32_e32 v99, v113, v101
	s_waitcnt lgkmcnt(0)
	v_mfma_f32_16x16x32_bf16 v[118:121], v[114:117], v[52:55], v[130:133]
	v_mfma_f32_16x16x32_bf16 v[114:117], v[114:117], v[48:51], v[124:127]
	s_nop 2
	ds_read2_b64 v[122:125], v99 offset1:4
	s_waitcnt lgkmcnt(0)
	v_mfma_f32_16x16x32_bf16 v[20:23], v[122:125], v[48:51], v[20:23]
	v_add_u32_e32 v48, v112, v97
	ds_read2_b64 v[48:51], v48 offset1:4
	v_add_u32_e32 v99, v112, v101
	s_waitcnt lgkmcnt(0)
	v_mfma_f32_16x16x32_bf16 v[32:35], v[48:51], v[60:63], v[32:35]
	v_mfma_f32_16x16x32_bf16 v[28:31], v[48:51], v[56:59], v[28:31]
	v_add_u32_e32 v48, v112, v103
	ds_read2_b64 v[48:51], v48 offset1:4
	s_waitcnt lgkmcnt(0)
	v_mfma_f32_16x16x32_bf16 v[44:47], v[48:51], v[60:63], v[44:47]
	v_mfma_f32_16x16x32_bf16 v[40:43], v[48:51], v[56:59], v[40:43]
	v_add_u32_e32 v48, v112, v106
	ds_read2_b64 v[48:51], v48 offset1:4
	v_mfma_f32_16x16x32_bf16 v[24:27], v[122:125], v[52:55], v[24:27]
	s_waitcnt lgkmcnt(0)
	v_mfma_f32_16x16x32_bf16 v[52:55], v[48:51], v[60:63], v[68:71]
	v_mfma_f32_16x16x32_bf16 v[48:51], v[48:51], v[56:59], v[64:67]
	s_nop 2
	v_add_u32_e32 v64, v112, v108
	ds_read2_b64 v[64:67], v64 offset1:4
	s_waitcnt lgkmcnt(0)
	v_mfma_f32_16x16x32_bf16 v[68:71], v[64:67], v[60:63], v[76:79]
	v_mfma_f32_16x16x32_bf16 v[64:67], v[64:67], v[56:59], v[72:75]
	s_nop 2
	v_add_u32_e32 v72, v112, v107
	ds_read2_b64 v[72:75], v72 offset1:4
	s_waitcnt lgkmcnt(0)
	v_mfma_f32_16x16x32_bf16 v[76:79], v[72:75], v[60:63], v[84:87]
	v_mfma_f32_16x16x32_bf16 v[72:75], v[72:75], v[56:59], v[80:83]
	s_nop 2
	v_add_u32_e32 v80, v112, v105
	ds_read2_b64 v[80:83], v80 offset1:4
	s_waitcnt lgkmcnt(0)
	v_mfma_f32_16x16x32_bf16 v[84:87], v[80:83], v[60:63], v[92:95]
	v_mfma_f32_16x16x32_bf16 v[80:83], v[80:83], v[56:59], v[88:91]
	s_nop 2
	v_add_u32_e32 v88, v112, v104
	ds_read2_b64 v[88:91], v88 offset1:4
	s_waitcnt lgkmcnt(0)
	v_mfma_f32_16x16x32_bf16 v[92:95], v[88:91], v[60:63], v[118:121]
	v_mfma_f32_16x16x32_bf16 v[88:91], v[88:91], v[56:59], v[114:117]
	s_nop 2
	ds_read2_b64 v[112:115], v99 offset1:4
	s_waitcnt lgkmcnt(0)
	v_mfma_f32_16x16x32_bf16 v[56:59], v[112:115], v[56:59], v[20:23]
	s_nop 2
	v_add_u32_e32 v20, v111, v97
	ds_read2_b64 v[20:23], v20 offset1:4
	v_add_u32_e32 v99, v110, v101
	v_mfma_f32_16x16x32_bf16 v[24:27], v[112:115], v[60:63], v[24:27]
	s_waitcnt lgkmcnt(0)
	v_mfma_f32_16x16x32_bf16 v[60:63], v[20:23], v[36:39], v[32:35]
	v_mfma_f32_16x16x32_bf16 v[112:115], v[20:23], v[16:19], v[28:31]
	v_add_u32_e32 v20, v111, v103
	ds_read2_b64 v[20:23], v20 offset1:4
	s_waitcnt lgkmcnt(0)
	v_mfma_f32_16x16x32_bf16 v[116:119], v[20:23], v[36:39], v[44:47]
	v_add_u32_e32 v28, v111, v105
	v_mfma_f32_16x16x32_bf16 v[120:123], v[20:23], v[16:19], v[40:43]
	v_add_u32_e32 v20, v111, v106
	ds_read2_b64 v[20:23], v20 offset1:4
	s_waitcnt lgkmcnt(0)
	v_mfma_f32_16x16x32_bf16 v[52:55], v[20:23], v[36:39], v[52:55]
	v_mfma_f32_16x16x32_bf16 v[48:51], v[20:23], v[16:19], v[48:51]
	v_add_u32_e32 v20, v111, v108
	ds_read2_b64 v[20:23], v20 offset1:4
	s_waitcnt lgkmcnt(0)
	v_mfma_f32_16x16x32_bf16 v[68:71], v[20:23], v[36:39], v[68:71]
	v_mfma_f32_16x16x32_bf16 v[64:67], v[20:23], v[16:19], v[64:67]
	v_add_u32_e32 v20, v111, v107
	ds_read2_b64 v[20:23], v20 offset1:4
	s_waitcnt lgkmcnt(0)
	v_mfma_f32_16x16x32_bf16 v[76:79], v[20:23], v[36:39], v[76:79]
	v_mfma_f32_16x16x32_bf16 v[44:47], v[20:23], v[16:19], v[72:75]
	ds_read2_b64 v[20:23], v28 offset1:4
	v_add_u32_e32 v28, v111, v104
	s_waitcnt lgkmcnt(0)
	v_mfma_f32_16x16x32_bf16 v[40:43], v[20:23], v[36:39], v[84:87]
	v_add_u32_e32 v72, v111, v101
	ds_read2_b64 v[72:75], v72 offset1:4
	s_nop 0
	v_add_u32_e32 v84, v110, v103
	v_mfma_f32_16x16x32_bf16 v[32:35], v[20:23], v[16:19], v[80:83]
	ds_read2_b64 v[20:23], v28 offset1:4
	ds_read2_b64 v[84:87], v84 offset1:4
	s_nop 0
	v_add_u32_e32 v80, v110, v97
	ds_read2_b64 v[80:83], v80 offset1:4
	v_add_u32_e32 v97, v109, v97
	ds_read2_b64 v[124:127], v97 offset1:4
	s_waitcnt lgkmcnt(3)
	v_mfma_f32_16x16x32_bf16 v[28:31], v[20:23], v[36:39], v[92:95]
	v_add_u32_e32 v97, v109, v103
	ds_read2_b64 v[130:133], v97 offset1:4
	v_add_u32_e32 v97, v109, v106
	v_mfma_f32_16x16x32_bf16 v[20:23], v[20:23], v[16:19], v[88:91]
	v_add_u32_e32 v92, v110, v104
	ds_read2_b64 v[92:95], v92 offset1:4
	s_nop 0
	v_add_u32_e32 v88, v110, v106
	v_mfma_f32_16x16x32_bf16 v[24:27], v[72:75], v[36:39], v[24:27]
	ds_read2_b64 v[36:39], v88 offset1:4
	v_add_u32_e32 v88, v110, v108
	ds_read2_b64 v[88:91], v88 offset1:4
	s_waitcnt lgkmcnt(5)
	v_mfma_f32_16x16x32_bf16 v[60:63], v[80:83], v[12:15], v[60:63]
	v_mfma_f32_16x16x32_bf16 v[80:83], v[80:83], v[4:7], v[112:115]
	s_waitcnt lgkmcnt(4)
; #define LAS __attribute__((address_space(3)))
; __device__ __forceinline__ unsigned pk2(float lo, float hi) { return pg8::cvt_pk_bf16(lo, hi); }
; __device__ __forceinline__ void wt_store8(const WsRef& w, const void* p, u32x2 v) { __builtin_amdgcn_raw_buffer_store_b64(v, w.r, (unsigned)((const unsigned char*)p - w.base), 0, 16); }
; #define MFMA16(a, b, c) __builtin_amdgcn_mfma_f32_16x16x32_bf16((a), (b), (c), 0, 0, 0)
; __device__ __forceinline__ void xattn_pair(LAS unsigned char* lds, int bh, size_t row_base, bf16* QO, const bf16* Kx, const bf16* VTx, int tid, const WsRef& wsr) {
;     ...
; #pragma unroll
;         for (int kk = 0; kk < 8; ++kk)
; #pragma unroll
;             for (int n = 0; n < 8; ++n) { const LAS bf16* vp = T + ((nh * 8 + n) * 16 + fr) * LDX + kk * 32 + 4 * fq;
;                 const u32x2 lo = *(const LAS u32x2*)vp, hi = *(const LAS u32x2*)(vp + 16); u32x4 w; w.x = lo.x; w.y = lo.y; w.z = hi.x; w.w = hi.y; const bf16x8 vf = __builtin_bit_cast(bf16x8, w);
;                 o0[n] = MFMA16(vf, pf0[kk], o0[n]); o1[n] = MFMA16(vf, pf1[kk], o1[n]); }
; #pragma unroll
;         for (int n = 0; n < 8; ++n) { const f32x4 v0 = o0[n] * rinv0, v1 = o1[n] * rinv1; u32x2 w0, w1; w0.x = pk2(v0[0], v0[1]); w0.y = pk2(v0[2], v0[3]); w1.x = pk2(v1[0], v1[1]); w1.y = pk2(v1[2], v1[3]);
;             wt_store8(wsr, qp0 + (nh * 8 + n) * 16 + 4 * fq, w0); wt_store8(wsr, qp1 + (nh * 8 + n) * 16 + 4 * fq, w1); }
;         __builtin_amdgcn_sched_barrier(0);
;     }
;     __syncthreads();
	v_mfma_f32_16x16x32_bf16 v[60:63], v[124:127], v[8:11], v[60:63]
	v_mfma_f32_16x16x32_bf16 v[114:117], v[84:87], v[12:15], v[116:119]
	v_mfma_f32_16x16x32_bf16 v[84:87], v[84:87], v[4:7], v[120:123]
	s_nop 2
	ds_read2_b64 v[118:121], v97 offset1:4
	v_add_u32_e32 v97, v109, v108
	v_mfma_f32_16x16x32_bf16 v[80:83], v[124:127], v[0:3], v[80:83]
	ds_read2_b64 v[134:137], v97 offset1:4
	v_add_u32_e32 v97, v109, v107
	ds_read2_b64 v[138:141], v97 offset1:4
	v_add_u32_e32 v97, v109, v104
	v_mfma_f32_16x16x32_bf16 v[16:19], v[72:75], v[16:19], v[56:59]
	v_add_u32_e32 v72, v110, v105
	v_pk_mul_f32 v[122:123], v[102:103], v[60:61] op_sel_hi:[0,1]
	s_nop 0
	v_pk_mul_f32 v[82:83], v[100:101], v[82:83] op_sel_hi:[0,1]
	v_add_u32_e32 v56, v110, v107
	s_waitcnt lgkmcnt(4)
	v_mfma_f32_16x16x32_bf16 v[52:55], v[36:39], v[12:15], v[52:55]
	ds_read2_b64 v[56:59], v56 offset1:4
	ds_read2_b64 v[72:75], v72 offset1:4
	ds_read2_b64 v[110:113], v99 offset1:4
	v_mfma_f32_16x16x32_bf16 v[36:39], v[36:39], v[4:7], v[48:51]
	s_nop 2
	v_add_u32_e32 v48, v109, v105
	ds_read2_b64 v[104:107], v97 offset1:4
	v_add_u32_e32 v97, v109, v101
	v_pk_mul_f32 v[108:109], v[102:103], v[62:63] op_sel_hi:[0,1]
	s_waitcnt lgkmcnt(7)
	v_mfma_f32_16x16x32_bf16 v[60:63], v[88:91], v[12:15], v[68:71]
	ds_read2_b64 v[48:51], v48 offset1:4
	ds_read2_b64 v[142:145], v97 offset1:4
	s_nop 0
	v_pk_mul_f32 v[68:69], v[100:101], v[80:81] op_sel_hi:[0,1]
	v_cvt_pk_bf16_f32 v70, v122, v123
	v_cvt_pk_bf16_f32 v71, v108, v109
	v_cvt_pk_bf16_f32 v80, v68, v69
	buffer_store_dwordx2 v[70:71], v96, s[88:91], 0 offen offset:256 sc1
	v_mfma_f32_16x16x32_bf16 v[68:71], v[130:133], v[8:11], v[114:117]
	v_cvt_pk_bf16_f32 v81, v82, v83
	buffer_store_dwordx2 v[80:81], v98, s[88:91], 0 offen offset:256 sc1
	s_waitcnt lgkmcnt(8)
	v_mfma_f32_16x16x32_bf16 v[36:39], v[118:121], v[0:3], v[36:39]
	v_mfma_f32_16x16x32_bf16 v[52:55], v[118:121], v[8:11], v[52:55]
	s_nop 2
	v_mul_f32_e64 v80, v102, v70
	v_mul_f32_e64 v81, v102, v71
	v_pk_mul_f32 v[82:83], v[102:103], v[68:69] op_sel_hi:[0,1]
	v_cvt_pk_bf16_f32 v82, v82, v83
	v_mfma_f32_16x16x32_bf16 v[68:71], v[130:133], v[0:3], v[84:87]
	v_cvt_pk_bf16_f32 v83, v80, v81
	v_pk_mul_f32 v[54:55], v[102:103], v[54:55] op_sel_hi:[0,1]
	v_pk_mul_f32 v[52:53], v[102:103], v[52:53] op_sel_hi:[0,1]
	v_cvt_pk_bf16_f32 v52, v52, v53
	v_cvt_pk_bf16_f32 v53, v54, v55
	s_nop 2
	v_pk_mul_f32 v[84:85], v[100:101], v[70:71] op_sel_hi:[0,1]
	v_pk_mul_f32 v[86:87], v[100:101], v[68:69] op_sel_hi:[0,1]
	s_waitcnt lgkmcnt(5)
	v_mfma_f32_16x16x32_bf16 v[68:71], v[56:59], v[12:15], v[76:79]
	s_nop 2
	v_cvt_pk_bf16_f32 v76, v86, v87
	v_cvt_pk_bf16_f32 v77, v84, v85
	buffer_store_dwordx2 v[82:83], v96, s[88:91], 0 offen offset:288 sc1
	buffer_store_dwordx2 v[76:77], v98, s[88:91], 0 offen offset:288 sc1
	v_pk_mul_f32 v[76:77], v[100:101], v[38:39] op_sel_hi:[0,1]
	v_pk_mul_f32 v[78:79], v[100:101], v[36:37] op_sel_hi:[0,1]
	v_mfma_f32_16x16x32_bf16 v[36:39], v[56:59], v[4:7], v[44:47]
	v_cvt_pk_bf16_f32 v54, v78, v79
	v_cvt_pk_bf16_f32 v55, v76, v77
	buffer_store_dwordx2 v[52:53], v96, s[88:91], 0 offen offset:320 sc1
	buffer_store_dwordx2 v[54:55], v98, s[88:91], 0 offen offset:320 sc1
	v_mfma_f32_16x16x32_bf16 v[44:47], v[134:137], v[8:11], v[60:63]
	v_mfma_f32_16x16x32_bf16 v[36:39], v[138:141], v[0:3], v[36:39]
	v_mfma_f32_16x16x32_bf16 v[64:67], v[88:91], v[4:7], v[64:67]
	s_nop 5
	v_mul_f32_e64 v46, v102, v46
	v_mul_f32_e64 v47, v102, v47
	v_pk_mul_f32 v[44:45], v[102:103], v[44:45] op_sel_hi:[0,1]
	v_cvt_pk_bf16_f32 v44, v44, v45
	v_cvt_pk_bf16_f32 v45, v46, v47
	buffer_store_dwordx2 v[44:45], v96, s[88:91], 0 offen offset:352 sc1
	v_mfma_f32_16x16x32_bf16 v[44:47], v[138:141], v[8:11], v[68:71]
	v_mul_f32_e64 v38, v100, v38
	v_mul_f32_e64 v39, v100, v39
	v_pk_mul_f32 v[36:37], v[100:101], v[36:37] op_sel_hi:[0,1]
	s_waitcnt lgkmcnt(4)
	v_mfma_f32_16x16x32_bf16 v[40:43], v[72:75], v[12:15], v[40:43]
	v_mfma_f32_16x16x32_bf16 v[28:31], v[92:95], v[12:15], v[28:31]
	s_nop 1
	v_mul_f32_e64 v46, v102, v46
	v_mul_f32_e64 v47, v102, v47
	v_pk_mul_f32 v[44:45], v[102:103], v[44:45] op_sel_hi:[0,1]
	v_cvt_pk_bf16_f32 v44, v44, v45
	v_mfma_f32_16x16x32_bf16 v[20:23], v[92:95], v[4:7], v[20:23]
	v_cvt_pk_bf16_f32 v45, v46, v47
	v_cvt_pk_bf16_f32 v46, v36, v37
	v_cvt_pk_bf16_f32 v47, v38, v39
	s_waitcnt lgkmcnt(3)
	v_mfma_f32_16x16x32_bf16 v[12:15], v[110:113], v[12:15], v[24:27]
	v_mfma_f32_16x16x32_bf16 v[32:35], v[72:75], v[4:7], v[32:35]
	v_mfma_f32_16x16x32_bf16 v[4:7], v[110:113], v[4:7], v[16:19]
	v_mfma_f32_16x16x32_bf16 v[52:55], v[134:137], v[0:3], v[64:67]
	s_waitcnt lgkmcnt(1)
	v_mfma_f32_16x16x32_bf16 v[36:39], v[48:51], v[8:11], v[40:43]
	v_mfma_f32_16x16x32_bf16 v[28:31], v[104:107], v[8:11], v[28:31]
	s_nop 4
	v_mul_f32_e64 v54, v100, v54
	v_mul_f32_e64 v55, v100, v55
	v_pk_mul_f32 v[52:53], v[100:101], v[52:53] op_sel_hi:[0,1]
	v_pk_mul_f32 v[38:39], v[102:103], v[38:39] op_sel_hi:[0,1]
	v_mfma_f32_16x16x32_bf16 v[20:23], v[104:107], v[0:3], v[20:23]
	v_mul_f32_e64 v36, v102, v36
	v_mul_f32_e64 v37, v102, v37
	v_pk_mul_f32 v[30:31], v[102:103], v[30:31] op_sel_hi:[0,1]
	v_pk_mul_f32 v[28:29], v[102:103], v[28:29] op_sel_hi:[0,1]
	s_waitcnt lgkmcnt(0)
	v_mfma_f32_16x16x32_bf16 v[8:11], v[142:145], v[8:11], v[12:15]
	v_cvt_pk_bf16_f32 v52, v52, v53
	s_nop 0
	v_pk_mul_f32 v[22:23], v[100:101], v[22:23] op_sel_hi:[0,1]
	v_pk_mul_f32 v[20:21], v[100:101], v[20:21] op_sel_hi:[0,1]
	v_mfma_f32_16x16x32_bf16 v[32:35], v[48:51], v[0:3], v[32:35]
	v_cvt_pk_bf16_f32 v53, v54, v55
	s_nop 1
	v_pk_mul_f32 v[10:11], v[102:103], v[10:11] op_sel_hi:[0,1]
	v_pk_mul_f32 v[8:9], v[102:103], v[8:9] op_sel_hi:[0,1]
	v_mfma_f32_16x16x32_bf16 v[0:3], v[142:145], v[0:3], v[4:7]
	v_cvt_pk_bf16_f32 v36, v36, v37
	s_nop 0
	v_pk_mul_f32 v[34:35], v[100:101], v[34:35] op_sel_hi:[0,1]
	v_pk_mul_f32 v[32:33], v[100:101], v[32:33] op_sel_hi:[0,1]
	v_cvt_pk_bf16_f32 v37, v38, v39
	v_cvt_pk_bf16_f32 v24, v28, v29
	v_cvt_pk_bf16_f32 v25, v30, v31
	v_cvt_pk_bf16_f32 v16, v20, v21
	v_cvt_pk_bf16_f32 v17, v22, v23
	v_pk_mul_f32 v[2:3], v[100:101], v[2:3] op_sel_hi:[0,1]
	v_pk_mul_f32 v[0:1], v[100:101], v[0:1] op_sel_hi:[0,1]
	v_cvt_pk_bf16_f32 v4, v8, v9
	v_cvt_pk_bf16_f32 v5, v10, v11
	buffer_store_dwordx2 v[52:53], v98, s[88:91], 0 offen offset:352 sc1
	buffer_store_dwordx2 v[44:45], v96, s[88:91], 0 offen offset:384 sc1
	buffer_store_dwordx2 v[46:47], v98, s[88:91], 0 offen offset:384 sc1
	v_cvt_pk_bf16_f32 v32, v32, v33
	v_cvt_pk_bf16_f32 v33, v34, v35
	buffer_store_dwordx2 v[36:37], v96, s[88:91], 0 offen offset:416 sc1
	buffer_store_dwordx2 v[32:33], v98, s[88:91], 0 offen offset:416 sc1
	buffer_store_dwordx2 v[24:25], v96, s[88:91], 0 offen offset:448 sc1
	buffer_store_dwordx2 v[16:17], v98, s[88:91], 0 offen offset:448 sc1
	v_cvt_pk_bf16_f32 v0, v0, v1
	v_cvt_pk_bf16_f32 v1, v2, v3
	buffer_store_dwordx2 v[4:5], v96, s[88:91], 0 offen offset:480 sc1
	buffer_store_dwordx2 v[0:1], v98, s[88:91], 0 offen offset:480 sc1
	s_branch .Lpp8_done
; #define LAS __attribute__((address_space(3)))
; __device__ __forceinline__ unsigned pk2(float lo, float hi) { return pg8::cvt_pk_bf16(lo, hi); }
; __device__ __forceinline__ void wt_store8(const WsRef& w, const void* p, u32x2 v) { __builtin_amdgcn_raw_buffer_store_b64(v, w.r, (unsigned)((const unsigned char*)p - w.base), 0, 16); }
; #define MFMA16(a, b, c) __builtin_amdgcn_mfma_f32_16x16x32_bf16((a), (b), (c), 0, 0, 0)
; __device__ __forceinline__ void xattn_pair(LAS unsigned char* lds, int bh, size_t row_base, bf16* QO, const bf16* Kx, const bf16* VTx, int tid, const WsRef& wsr) {
;     ...
;     for (int nh = 0; nh < 2; ++nh) {
;         f32x4 o0[8], o1[8];
; #pragma unroll
;         for (int n = 0; n < 8; ++n) { o0[n] = (f32x4){0.f, 0.f, 0.f, 0.f}; o1[n] = (f32x4){0.f, 0.f, 0.f, 0.f}; }
; #pragma unroll
;         for (int kk = 0; kk < 8; ++kk)
; #pragma unroll
;             for (int n = 0; n < 8; ++n) { const LAS bf16* vp = T + ((nh * 8 + n) * 16 + fr) * LDX + kk * 32 + 4 * fq;
;                 const u32x2 lo = *(const LAS u32x2*)vp, hi = *(const LAS u32x2*)(vp + 16); u32x4 w; w.x = lo.x; w.y = lo.y; w.z = hi.x; w.w = hi.y; const bf16x8 vf = __builtin_bit_cast(bf16x8, w);
;                 o0[n] = MFMA16(vf, pf0[kk], o0[n]); o1[n] = MFMA16(vf, pf1[kk], o1[n]); }
; #pragma unroll
;         for (int n = 0; n < 8; ++n) { const f32x4 v0 = o0[n] * rinv0, v1 = o1[n] * rinv1; u32x2 w0, w1; w0.x = pk2(v0[0], v0[1]); w0.y = pk2(v0[2], v0[3]); w1.x = pk2(v1[0], v1[1]); w1.y = pk2(v1[2], v1[3]);
;             wt_store8(wsr, qp0 + (nh * 8 + n) * 16 + 4 * fq, w0); wt_store8(wsr, qp1 + (nh * 8 + n) * 16 + 4 * fq, w1); }
;         __builtin_amdgcn_sched_barrier(0);
.Lpp8_plain:
	buffer_store_dwordx2 v[166:167], v96, s[88:91], 0 offen
	buffer_store_dwordx2 v[150:151], v98, s[88:91], 0 offen
	v_pk_mul_f32 v[150:151], v[102:103], v[122:123] op_sel_hi:[0,1]
	v_pk_mul_f32 v[164:165], v[102:103], v[120:121] op_sel_hi:[0,1]
	v_mfma_f32_16x16x32_bf16 v[120:123], v[130:133], v[0:3], v[172:175]
	v_cvt_pk_bf16_f32 v130, v164, v165
	v_cvt_pk_bf16_f32 v131, v150, v151
	v_mfma_f32_16x16x32_bf16 v[160:163], v[180:183], v[12:15], v[160:163]
	v_mfma_f32_16x16x32_bf16 v[152:155], v[180:183], v[4:7], v[156:159]
	s_nop 3
	v_mul_f32_e64 v122, v100, v122
	v_mul_f32_e64 v123, v100, v123
	v_pk_mul_f32 v[120:121], v[100:101], v[120:121] op_sel_hi:[0,1]
	v_cvt_pk_bf16_f32 v132, v120, v121
	v_cvt_pk_bf16_f32 v133, v122, v123
	s_waitcnt lgkmcnt(5)
	v_mfma_f32_16x16x32_bf16 v[120:123], v[134:137], v[8:11], v[160:163]
	buffer_store_dwordx2 v[130:131], v96, s[88:91], 0 offen offset:32
	buffer_store_dwordx2 v[132:133], v98, s[88:91], 0 offen offset:32
	v_mfma_f32_16x16x32_bf16 v[156:159], v[184:187], v[12:15], v[168:171]
	s_nop 4
	v_mul_f32_e64 v122, v102, v122
	v_mul_f32_e64 v123, v102, v123
	v_pk_mul_f32 v[120:121], v[102:103], v[120:121] op_sel_hi:[0,1]
	v_mfma_f32_16x16x32_bf16 v[116:119], v[184:187], v[4:7], v[116:119]
	v_mfma_f32_16x16x32_bf16 v[92:95], v[188:191], v[12:15], v[92:95]
	v_mfma_f32_16x16x32_bf16 v[88:91], v[188:191], v[4:7], v[88:91]
	v_mfma_f32_16x16x32_bf16 v[80:83], v[124:127], v[12:15], v[80:83]
	v_mfma_f32_16x16x32_bf16 v[130:133], v[134:137], v[0:3], v[152:155]
	v_cvt_pk_bf16_f32 v134, v120, v121
	v_cvt_pk_bf16_f32 v135, v122, v123
	s_waitcnt lgkmcnt(4)
	v_mfma_f32_16x16x32_bf16 v[120:123], v[138:141], v[8:11], v[156:159]
	v_mfma_f32_16x16x32_bf16 v[116:119], v[138:141], v[0:3], v[116:119]
	s_nop 2
	v_mul_f32_e64 v132, v100, v132
	v_mul_f32_e64 v133, v100, v133
	s_nop 1
	v_pk_mul_f32 v[122:123], v[102:103], v[122:123] op_sel_hi:[0,1]
	v_pk_mul_f32 v[120:121], v[102:103], v[120:121] op_sel_hi:[0,1]
	s_waitcnt lgkmcnt(3)
	v_mfma_f32_16x16x32_bf16 v[92:95], v[142:145], v[8:11], v[92:95]
	v_mul_f32_e64 v130, v100, v130
	v_mul_f32_e64 v131, v100, v131
	v_pk_mul_f32 v[118:119], v[100:101], v[118:119] op_sel_hi:[0,1]
	v_pk_mul_f32 v[116:117], v[100:101], v[116:117] op_sel_hi:[0,1]
	v_mfma_f32_16x16x32_bf16 v[88:91], v[142:145], v[0:3], v[88:91]
	v_cvt_pk_bf16_f32 v120, v120, v121
	s_nop 1
	v_pk_mul_f32 v[94:95], v[102:103], v[94:95] op_sel_hi:[0,1]
	v_pk_mul_f32 v[92:93], v[102:103], v[92:93] op_sel_hi:[0,1]
	v_mfma_f32_16x16x32_bf16 v[76:79], v[192:195], v[12:15], v[76:79]
	v_cvt_pk_bf16_f32 v121, v122, v123
	s_nop 0
	v_pk_mul_f32 v[90:91], v[100:101], v[90:91] op_sel_hi:[0,1]
	v_pk_mul_f32 v[88:89], v[100:101], v[88:89] op_sel_hi:[0,1]
	v_mfma_f32_16x16x32_bf16 v[72:75], v[192:195], v[4:7], v[72:75]
	v_cvt_pk_bf16_f32 v116, v116, v117
	v_cvt_pk_bf16_f32 v117, v118, v119
	v_cvt_pk_bf16_f32 v92, v92, v93
	v_mfma_f32_16x16x32_bf16 v[84:87], v[124:127], v[4:7], v[84:87]
	v_cvt_pk_bf16_f32 v93, v94, v95
	v_cvt_pk_bf16_f32 v88, v88, v89
	v_cvt_pk_bf16_f32 v89, v90, v91
	s_waitcnt lgkmcnt(2)
	v_mfma_f32_16x16x32_bf16 v[80:83], v[146:149], v[8:11], v[80:83]
	v_cvt_pk_bf16_f32 v130, v130, v131
	v_cvt_pk_bf16_f32 v131, v132, v133
	buffer_store_dwordx2 v[134:135], v96, s[88:91], 0 offen offset:64
	buffer_store_dwordx2 v[130:131], v98, s[88:91], 0 offen offset:64
	v_mfma_f32_16x16x32_bf16 v[64:67], v[196:199], v[12:15], v[64:67]
	buffer_store_dwordx2 v[120:121], v96, s[88:91], 0 offen offset:96
	buffer_store_dwordx2 v[116:117], v98, s[88:91], 0 offen offset:96
	buffer_store_dwordx2 v[92:93], v96, s[88:91], 0 offen offset:128
	buffer_store_dwordx2 v[88:89], v98, s[88:91], 0 offen offset:128
	s_waitcnt lgkmcnt(1)
	v_mfma_f32_16x16x32_bf16 v[76:79], v[200:203], v[8:11], v[76:79]
	v_mul_f32_e64 v88, v102, v82
	v_mul_f32_e64 v89, v102, v83
	v_pk_mul_f32 v[80:81], v[102:103], v[80:81] op_sel_hi:[0,1]
	v_cvt_pk_bf16_f32 v80, v80, v81
	v_mfma_f32_16x16x32_bf16 v[72:75], v[200:203], v[0:3], v[72:75]
	v_cvt_pk_bf16_f32 v81, v88, v89
	s_nop 1
	v_pk_mul_f32 v[78:79], v[102:103], v[78:79] op_sel_hi:[0,1]
	v_pk_mul_f32 v[76:77], v[102:103], v[76:77] op_sel_hi:[0,1]
	v_mfma_f32_16x16x32_bf16 v[82:85], v[146:149], v[0:3], v[84:87]
	v_cvt_pk_bf16_f32 v76, v76, v77
	s_nop 0
	v_pk_mul_f32 v[74:75], v[100:101], v[74:75] op_sel_hi:[0,1]
	v_pk_mul_f32 v[72:73], v[100:101], v[72:73] op_sel_hi:[0,1]
	v_mfma_f32_16x16x32_bf16 v[68:71], v[196:199], v[4:7], v[68:71]
	v_cvt_pk_bf16_f32 v77, v78, v79
	s_nop 1
	v_pk_mul_f32 v[84:85], v[100:101], v[84:85] op_sel_hi:[0,1]
	v_pk_mul_f32 v[82:83], v[100:101], v[82:83] op_sel_hi:[0,1]
	s_waitcnt lgkmcnt(0)
	v_mfma_f32_16x16x32_bf16 v[64:67], v[206:209], v[8:11], v[64:67]
	v_cvt_pk_bf16_f32 v72, v72, v73
	v_cvt_pk_bf16_f32 v73, v74, v75
	v_cvt_pk_bf16_f32 v82, v82, v83
	v_cvt_pk_bf16_f32 v83, v84, v85
	buffer_store_dwordx2 v[80:81], v96, s[88:91], 0 offen offset:160
	buffer_store_dwordx2 v[82:83], v98, s[88:91], 0 offen offset:160
	buffer_store_dwordx2 v[76:77], v96, s[88:91], 0 offen offset:192
	buffer_store_dwordx2 v[72:73], v98, s[88:91], 0 offen offset:192
	v_pk_mul_f32 v[72:73], v[102:103], v[66:67] op_sel_hi:[0,1]
	v_pk_mul_f32 v[74:75], v[102:103], v[64:65] op_sel_hi:[0,1]
	v_mfma_f32_16x16x32_bf16 v[64:67], v[206:209], v[0:3], v[68:71]
	s_nop 2
	v_cvt_pk_bf16_f32 v68, v74, v75
	v_cvt_pk_bf16_f32 v69, v72, v73
	s_nop 2
	v_pk_mul_f32 v[66:67], v[100:101], v[66:67] op_sel_hi:[0,1]
	v_pk_mul_f32 v[64:65], v[100:101], v[64:65] op_sel_hi:[0,1]
	v_cvt_pk_bf16_f32 v64, v64, v65
	v_cvt_pk_bf16_f32 v65, v66, v67
	buffer_store_dwordx2 v[68:69], v96, s[88:91], 0 offen offset:224
	buffer_store_dwordx2 v[64:65], v98, s[88:91], 0 offen offset:224
	v_add_u32_e32 v115, v99, v107
	ds_read2_b64 v[116:119], v115 offset1:4
	v_add_u32_e32 v115, v99, v105
	v_add_u32_e32 v64, v99, v97
	v_add_u32_e32 v72, v99, v103
	v_add_u32_e32 v80, v99, v106
	v_add_u32_e32 v88, v99, v108
	ds_read2_b64 v[124:127], v115 offset1:4
	v_add_u32_e32 v115, v99, v104
	v_add_u32_e32 v99, v99, v101
	ds_read2_b64 v[64:67], v64 offset1:4
	ds_read2_b64 v[72:75], v72 offset1:4
	ds_read2_b64 v[80:83], v80 offset1:4
	ds_read2_b64 v[88:91], v88 offset1:4
	ds_read2_b64 v[134:137], v115 offset1:4
	ds_read2_b64 v[142:145], v99 offset1:4
	v_add_u32_e32 v99, v129, v97
	s_waitcnt lgkmcnt(5)
; #define LAS __attribute__((address_space(3)))
; #define MFMA16(a, b, c) __builtin_amdgcn_mfma_f32_16x16x32_bf16((a), (b), (c), 0, 0, 0)
; __device__ __forceinline__ void xattn_pair(LAS unsigned char* lds, int bh, size_t row_base, bf16* QO, const bf16* Kx, const bf16* VTx, int tid, const WsRef& wsr) {
;     ...
; #pragma unroll
;         for (int kk = 0; kk < 8; ++kk)
; #pragma unroll
;             for (int n = 0; n < 8; ++n) { const LAS bf16* vp = T + ((nh * 8 + n) * 16 + fr) * LDX + kk * 32 + 4 * fq;
;                 const u32x2 lo = *(const LAS u32x2*)vp, hi = *(const LAS u32x2*)(vp + 16); u32x4 w; w.x = lo.x; w.y = lo.y; w.z = hi.x; w.w = hi.y; const bf16x8 vf = __builtin_bit_cast(bf16x8, w);
;                 o0[n] = MFMA16(vf, pf0[kk], o0[n]); o1[n] = MFMA16(vf, pf1[kk], o1[n]); }
	v_mfma_f32_16x16x32_bf16 v[68:71], v[64:67], v[24:27], 0
	v_mfma_f32_16x16x32_bf16 v[64:67], v[64:67], v[20:23], 0
	s_waitcnt lgkmcnt(4)
	v_mfma_f32_16x16x32_bf16 v[76:79], v[72:75], v[24:27], 0
	v_mfma_f32_16x16x32_bf16 v[72:75], v[72:75], v[20:23], 0
	s_waitcnt lgkmcnt(3)
	v_mfma_f32_16x16x32_bf16 v[84:87], v[80:83], v[24:27], 0
	v_mfma_f32_16x16x32_bf16 v[80:83], v[80:83], v[20:23], 0
	s_waitcnt lgkmcnt(2)
	v_mfma_f32_16x16x32_bf16 v[92:95], v[88:91], v[24:27], 0
	v_mfma_f32_16x16x32_bf16 v[88:91], v[88:91], v[20:23], 0
	v_mfma_f32_16x16x32_bf16 v[120:123], v[116:119], v[24:27], 0
	v_mfma_f32_16x16x32_bf16 v[116:119], v[116:119], v[20:23], 0
	v_mfma_f32_16x16x32_bf16 v[130:133], v[124:127], v[24:27], 0
	v_mfma_f32_16x16x32_bf16 v[124:127], v[124:127], v[20:23], 0
	s_waitcnt lgkmcnt(1)
	v_mfma_f32_16x16x32_bf16 v[138:141], v[134:137], v[24:27], 0
	v_mfma_f32_16x16x32_bf16 v[134:137], v[134:137], v[20:23], 0
	s_waitcnt lgkmcnt(0)
	v_mfma_f32_16x16x32_bf16 v[24:27], v[142:145], v[24:27], 0
	v_mfma_f32_16x16x32_bf16 v[20:23], v[142:145], v[20:23], 0
	ds_read2_b64 v[142:145], v99 offset1:4
	v_add_u32_e32 v99, v129, v103
	s_waitcnt lgkmcnt(0)
	v_mfma_f32_16x16x32_bf16 v[68:71], v[142:145], v[32:35], v[68:71]
	v_mfma_f32_16x16x32_bf16 v[64:67], v[142:145], v[28:31], v[64:67]
	ds_read2_b64 v[142:145], v99 offset1:4
	v_add_u32_e32 v99, v129, v106
	s_waitcnt lgkmcnt(0)
	v_mfma_f32_16x16x32_bf16 v[76:79], v[142:145], v[32:35], v[76:79]
	v_mfma_f32_16x16x32_bf16 v[72:75], v[142:145], v[28:31], v[72:75]
	ds_read2_b64 v[142:145], v99 offset1:4
	v_add_u32_e32 v99, v129, v108
	s_waitcnt lgkmcnt(0)
	v_mfma_f32_16x16x32_bf16 v[84:87], v[142:145], v[32:35], v[84:87]
	v_mfma_f32_16x16x32_bf16 v[80:83], v[142:145], v[28:31], v[80:83]
	ds_read2_b64 v[142:145], v99 offset1:4
	v_add_u32_e32 v99, v129, v107
	s_waitcnt lgkmcnt(0)
	v_mfma_f32_16x16x32_bf16 v[92:95], v[142:145], v[32:35], v[92:95]
	v_mfma_f32_16x16x32_bf16 v[88:91], v[142:145], v[28:31], v[88:91]
	ds_read2_b64 v[142:145], v99 offset1:4
	v_add_u32_e32 v99, v129, v105
	s_waitcnt lgkmcnt(0)
	v_mfma_f32_16x16x32_bf16 v[120:123], v[142:145], v[32:35], v[120:123]
	v_mfma_f32_16x16x32_bf16 v[116:119], v[142:145], v[28:31], v[116:119]
	ds_read2_b64 v[142:145], v99 offset1:4
	v_add_u32_e32 v99, v129, v104
	s_waitcnt lgkmcnt(0)
	v_mfma_f32_16x16x32_bf16 v[130:133], v[142:145], v[32:35], v[130:133]
	v_mfma_f32_16x16x32_bf16 v[124:127], v[142:145], v[28:31], v[124:127]
	ds_read2_b64 v[142:145], v99 offset1:4
	v_add_u32_e32 v99, v129, v101
	s_waitcnt lgkmcnt(0)
	v_mfma_f32_16x16x32_bf16 v[138:141], v[142:145], v[32:35], v[138:141]
	v_mfma_f32_16x16x32_bf16 v[134:137], v[142:145], v[28:31], v[134:137]
	ds_read2_b64 v[142:145], v99 offset1:4
	v_add_u32_e32 v99, v114, v105
	s_waitcnt lgkmcnt(0)
	v_mfma_f32_16x16x32_bf16 v[20:23], v[142:145], v[28:31], v[20:23]
	v_add_u32_e32 v28, v114, v97
	ds_read2_b64 v[28:31], v28 offset1:4
	v_mfma_f32_16x16x32_bf16 v[24:27], v[142:145], v[32:35], v[24:27]
	s_waitcnt lgkmcnt(0)
	v_mfma_f32_16x16x32_bf16 v[32:35], v[28:31], v[44:47], v[68:71]
	v_mfma_f32_16x16x32_bf16 v[28:31], v[28:31], v[40:43], v[64:67]
	s_nop 2
	v_add_u32_e32 v64, v114, v103
	ds_read2_b64 v[64:67], v64 offset1:4
	s_waitcnt lgkmcnt(0)
	v_mfma_f32_16x16x32_bf16 v[68:71], v[64:67], v[44:47], v[76:79]
	v_mfma_f32_16x16x32_bf16 v[64:67], v[64:67], v[40:43], v[72:75]
	s_nop 2
	v_add_u32_e32 v72, v114, v106
	ds_read2_b64 v[72:75], v72 offset1:4
	s_waitcnt lgkmcnt(0)
	v_mfma_f32_16x16x32_bf16 v[76:79], v[72:75], v[44:47], v[84:87]
	v_mfma_f32_16x16x32_bf16 v[72:75], v[72:75], v[40:43], v[80:83]
	s_nop 2
	v_add_u32_e32 v80, v114, v108
	ds_read2_b64 v[80:83], v80 offset1:4
	s_waitcnt lgkmcnt(0)
	v_mfma_f32_16x16x32_bf16 v[84:87], v[80:83], v[44:47], v[92:95]
	v_mfma_f32_16x16x32_bf16 v[80:83], v[80:83], v[40:43], v[88:91]
	s_nop 2
	v_add_u32_e32 v88, v114, v107
	ds_read2_b64 v[88:91], v88 offset1:4
	s_waitcnt lgkmcnt(0)
	v_mfma_f32_16x16x32_bf16 v[92:95], v[88:91], v[44:47], v[120:123]
	v_mfma_f32_16x16x32_bf16 v[88:91], v[88:91], v[40:43], v[116:119]
	s_nop 2
	ds_read2_b64 v[116:119], v99 offset1:4
	v_add_u32_e32 v99, v114, v104
	s_waitcnt lgkmcnt(0)
	v_mfma_f32_16x16x32_bf16 v[120:123], v[116:119], v[44:47], v[130:133]
	v_mfma_f32_16x16x32_bf16 v[116:119], v[116:119], v[40:43], v[124:127]
	s_nop 2
	ds_read2_b64 v[124:127], v99 offset1:4
	v_add_u32_e32 v99, v114, v101
	s_waitcnt lgkmcnt(0)
	v_mfma_f32_16x16x32_bf16 v[130:133], v[124:127], v[44:47], v[138:141]
	v_mfma_f32_16x16x32_bf16 v[124:127], v[124:127], v[40:43], v[134:137]
	s_nop 2
	ds_read2_b64 v[134:137], v99 offset1:4
	s_waitcnt lgkmcnt(0)
	v_mfma_f32_16x16x32_bf16 v[20:23], v[134:137], v[40:43], v[20:23]
	v_add_u32_e32 v40, v113, v97
	ds_read2_b64 v[40:43], v40 offset1:4
	v_add_u32_e32 v99, v113, v104
	s_waitcnt lgkmcnt(0)
	v_mfma_f32_16x16x32_bf16 v[32:35], v[40:43], v[52:55], v[32:35]
	v_mfma_f32_16x16x32_bf16 v[28:31], v[40:43], v[48:51], v[28:31]
	v_add_u32_e32 v40, v113, v103
	ds_read2_b64 v[40:43], v40 offset1:4
	v_mfma_f32_16x16x32_bf16 v[24:27], v[134:137], v[44:47], v[24:27]
	s_waitcnt lgkmcnt(0)
	v_mfma_f32_16x16x32_bf16 v[44:47], v[40:43], v[52:55], v[68:71]
	v_mfma_f32_16x16x32_bf16 v[40:43], v[40:43], v[48:51], v[64:67]
	s_nop 2
	v_add_u32_e32 v64, v113, v106
	ds_read2_b64 v[64:67], v64 offset1:4
	s_waitcnt lgkmcnt(0)
	v_mfma_f32_16x16x32_bf16 v[68:71], v[64:67], v[52:55], v[76:79]
	v_mfma_f32_16x16x32_bf16 v[64:67], v[64:67], v[48:51], v[72:75]
	s_nop 2
	v_add_u32_e32 v72, v113, v108
	ds_read2_b64 v[72:75], v72 offset1:4
	s_waitcnt lgkmcnt(0)
; #define LAS __attribute__((address_space(3)))
; #define MFMA16(a, b, c) __builtin_amdgcn_mfma_f32_16x16x32_bf16((a), (b), (c), 0, 0, 0)
; __device__ __forceinline__ void xattn_pair(LAS unsigned char* lds, int bh, size_t row_base, bf16* QO, const bf16* Kx, const bf16* VTx, int tid, const WsRef& wsr) {
;     ...
; #pragma unroll
;         for (int kk = 0; kk < 8; ++kk)
; #pragma unroll
;             for (int n = 0; n < 8; ++n) { const LAS bf16* vp = T + ((nh * 8 + n) * 16 + fr) * LDX + kk * 32 + 4 * fq;
;                 const u32x2 lo = *(const LAS u32x2*)vp, hi = *(const LAS u32x2*)(vp + 16); u32x4 w; w.x = lo.x; w.y = lo.y; w.z = hi.x; w.w = hi.y; const bf16x8 vf = __builtin_bit_cast(bf16x8, w);
;                 o0[n] = MFMA16(vf, pf0[kk], o0[n]); o1[n] = MFMA16(vf, pf1[kk], o1[n]); }
	v_mfma_f32_16x16x32_bf16 v[76:79], v[72:75], v[52:55], v[84:87]
	v_mfma_f32_16x16x32_bf16 v[72:75], v[72:75], v[48:51], v[80:83]
	s_nop 2
	v_add_u32_e32 v80, v113, v107
	ds_read2_b64 v[80:83], v80 offset1:4
	s_waitcnt lgkmcnt(0)
	v_mfma_f32_16x16x32_bf16 v[84:87], v[80:83], v[52:55], v[92:95]
	v_mfma_f32_16x16x32_bf16 v[80:83], v[80:83], v[48:51], v[88:91]
	s_nop 2
	v_add_u32_e32 v88, v113, v105
	ds_read2_b64 v[88:91], v88 offset1:4
	s_waitcnt lgkmcnt(0)
	v_mfma_f32_16x16x32_bf16 v[92:95], v[88:91], v[52:55], v[120:123]
	v_mfma_f32_16x16x32_bf16 v[88:91], v[88:91], v[48:51], v[116:119]
	s_nop 2
	ds_read2_b64 v[114:117], v99 offset1:4
	v_add_u32_e32 v99, v113, v101
	s_waitcnt lgkmcnt(0)
	v_mfma_f32_16x16x32_bf16 v[118:121], v[114:117], v[52:55], v[130:133]
	v_mfma_f32_16x16x32_bf16 v[114:117], v[114:117], v[48:51], v[124:127]
	s_nop 2
	ds_read2_b64 v[122:125], v99 offset1:4
	s_waitcnt lgkmcnt(0)
	v_mfma_f32_16x16x32_bf16 v[20:23], v[122:125], v[48:51], v[20:23]
	v_add_u32_e32 v48, v112, v97
	ds_read2_b64 v[48:51], v48 offset1:4
	v_add_u32_e32 v99, v112, v101
	s_waitcnt lgkmcnt(0)
	v_mfma_f32_16x16x32_bf16 v[32:35], v[48:51], v[60:63], v[32:35]
	v_mfma_f32_16x16x32_bf16 v[28:31], v[48:51], v[56:59], v[28:31]
	v_add_u32_e32 v48, v112, v103
	ds_read2_b64 v[48:51], v48 offset1:4
	s_waitcnt lgkmcnt(0)
	v_mfma_f32_16x16x32_bf16 v[44:47], v[48:51], v[60:63], v[44:47]
	v_mfma_f32_16x16x32_bf16 v[40:43], v[48:51], v[56:59], v[40:43]
	v_add_u32_e32 v48, v112, v106
	ds_read2_b64 v[48:51], v48 offset1:4
	v_mfma_f32_16x16x32_bf16 v[24:27], v[122:125], v[52:55], v[24:27]
	s_waitcnt lgkmcnt(0)
	v_mfma_f32_16x16x32_bf16 v[52:55], v[48:51], v[60:63], v[68:71]
	v_mfma_f32_16x16x32_bf16 v[48:51], v[48:51], v[56:59], v[64:67]
	s_nop 2
	v_add_u32_e32 v64, v112, v108
	ds_read2_b64 v[64:67], v64 offset1:4
	s_waitcnt lgkmcnt(0)
	v_mfma_f32_16x16x32_bf16 v[68:71], v[64:67], v[60:63], v[76:79]
	v_mfma_f32_16x16x32_bf16 v[64:67], v[64:67], v[56:59], v[72:75]
	s_nop 2
	v_add_u32_e32 v72, v112, v107
	ds_read2_b64 v[72:75], v72 offset1:4
	s_waitcnt lgkmcnt(0)
	v_mfma_f32_16x16x32_bf16 v[76:79], v[72:75], v[60:63], v[84:87]
	v_mfma_f32_16x16x32_bf16 v[72:75], v[72:75], v[56:59], v[80:83]
	s_nop 2
	v_add_u32_e32 v80, v112, v105
	ds_read2_b64 v[80:83], v80 offset1:4
	s_waitcnt lgkmcnt(0)
	v_mfma_f32_16x16x32_bf16 v[84:87], v[80:83], v[60:63], v[92:95]
	v_mfma_f32_16x16x32_bf16 v[80:83], v[80:83], v[56:59], v[88:91]
	s_nop 2
	v_add_u32_e32 v88, v112, v104
	ds_read2_b64 v[88:91], v88 offset1:4
	s_waitcnt lgkmcnt(0)
	v_mfma_f32_16x16x32_bf16 v[92:95], v[88:91], v[60:63], v[118:121]
	v_mfma_f32_16x16x32_bf16 v[88:91], v[88:91], v[56:59], v[114:117]
	s_nop 2
	ds_read2_b64 v[112:115], v99 offset1:4
	s_waitcnt lgkmcnt(0)
	v_mfma_f32_16x16x32_bf16 v[56:59], v[112:115], v[56:59], v[20:23]
	s_nop 2
	v_add_u32_e32 v20, v111, v97
	ds_read2_b64 v[20:23], v20 offset1:4
	v_add_u32_e32 v99, v110, v101
	v_mfma_f32_16x16x32_bf16 v[24:27], v[112:115], v[60:63], v[24:27]
	s_waitcnt lgkmcnt(0)
	v_mfma_f32_16x16x32_bf16 v[60:63], v[20:23], v[36:39], v[32:35]
	v_mfma_f32_16x16x32_bf16 v[112:115], v[20:23], v[16:19], v[28:31]
	v_add_u32_e32 v20, v111, v103
	ds_read2_b64 v[20:23], v20 offset1:4
	s_waitcnt lgkmcnt(0)
	v_mfma_f32_16x16x32_bf16 v[116:119], v[20:23], v[36:39], v[44:47]
	v_add_u32_e32 v28, v111, v105
	v_mfma_f32_16x16x32_bf16 v[120:123], v[20:23], v[16:19], v[40:43]
	v_add_u32_e32 v20, v111, v106
	ds_read2_b64 v[20:23], v20 offset1:4
	s_waitcnt lgkmcnt(0)
	v_mfma_f32_16x16x32_bf16 v[52:55], v[20:23], v[36:39], v[52:55]
	v_mfma_f32_16x16x32_bf16 v[48:51], v[20:23], v[16:19], v[48:51]
	v_add_u32_e32 v20, v111, v108
	ds_read2_b64 v[20:23], v20 offset1:4
	s_waitcnt lgkmcnt(0)
	v_mfma_f32_16x16x32_bf16 v[68:71], v[20:23], v[36:39], v[68:71]
	v_mfma_f32_16x16x32_bf16 v[64:67], v[20:23], v[16:19], v[64:67]
	v_add_u32_e32 v20, v111, v107
	ds_read2_b64 v[20:23], v20 offset1:4
	s_waitcnt lgkmcnt(0)
	v_mfma_f32_16x16x32_bf16 v[76:79], v[20:23], v[36:39], v[76:79]
	v_mfma_f32_16x16x32_bf16 v[44:47], v[20:23], v[16:19], v[72:75]
	ds_read2_b64 v[20:23], v28 offset1:4
	v_add_u32_e32 v28, v111, v104
	s_waitcnt lgkmcnt(0)
	v_mfma_f32_16x16x32_bf16 v[40:43], v[20:23], v[36:39], v[84:87]
	v_add_u32_e32 v72, v111, v101
	ds_read2_b64 v[72:75], v72 offset1:4
	s_nop 0
	v_add_u32_e32 v84, v110, v103
	v_mfma_f32_16x16x32_bf16 v[32:35], v[20:23], v[16:19], v[80:83]
	ds_read2_b64 v[20:23], v28 offset1:4
	ds_read2_b64 v[84:87], v84 offset1:4
	s_nop 0
	v_add_u32_e32 v80, v110, v97
	ds_read2_b64 v[80:83], v80 offset1:4
	v_add_u32_e32 v97, v109, v97
	ds_read2_b64 v[124:127], v97 offset1:4
	s_waitcnt lgkmcnt(3)
	v_mfma_f32_16x16x32_bf16 v[28:31], v[20:23], v[36:39], v[92:95]
	v_add_u32_e32 v97, v109, v103
	ds_read2_b64 v[130:133], v97 offset1:4
	v_add_u32_e32 v97, v109, v106
	v_mfma_f32_16x16x32_bf16 v[20:23], v[20:23], v[16:19], v[88:91]
	v_add_u32_e32 v92, v110, v104
	ds_read2_b64 v[92:95], v92 offset1:4
	s_nop 0
	v_add_u32_e32 v88, v110, v106
	v_mfma_f32_16x16x32_bf16 v[24:27], v[72:75], v[36:39], v[24:27]
	ds_read2_b64 v[36:39], v88 offset1:4
	v_add_u32_e32 v88, v110, v108
	ds_read2_b64 v[88:91], v88 offset1:4
	s_waitcnt lgkmcnt(5)
	v_mfma_f32_16x16x32_bf16 v[60:63], v[80:83], v[12:15], v[60:63]
	v_mfma_f32_16x16x32_bf16 v[80:83], v[80:83], v[4:7], v[112:115]
	s_waitcnt lgkmcnt(4)
; #define LAS __attribute__((address_space(3)))
; __device__ __forceinline__ unsigned pk2(float lo, float hi) { return pg8::cvt_pk_bf16(lo, hi); }
; __device__ __forceinline__ void wt_store8(const WsRef& w, const void* p, u32x2 v) { __builtin_amdgcn_raw_buffer_store_b64(v, w.r, (unsigned)((const unsigned char*)p - w.base), 0, 16); }
; #define MFMA16(a, b, c) __builtin_amdgcn_mfma_f32_16x16x32_bf16((a), (b), (c), 0, 0, 0)
; __device__ __forceinline__ void xattn_pair(LAS unsigned char* lds, int bh, size_t row_base, bf16* QO, const bf16* Kx, const bf16* VTx, int tid, const WsRef& wsr) {
;     ...
; #pragma unroll
;         for (int kk = 0; kk < 8; ++kk)
; #pragma unroll
;             for (int n = 0; n < 8; ++n) { const LAS bf16* vp = T + ((nh * 8 + n) * 16 + fr) * LDX + kk * 32 + 4 * fq;
;                 const u32x2 lo = *(const LAS u32x2*)vp, hi = *(const LAS u32x2*)(vp + 16); u32x4 w; w.x = lo.x; w.y = lo.y; w.z = hi.x; w.w = hi.y; const bf16x8 vf = __builtin_bit_cast(bf16x8, w);
;                 o0[n] = MFMA16(vf, pf0[kk], o0[n]); o1[n] = MFMA16(vf, pf1[kk], o1[n]); }
; #pragma unroll
;         for (int n = 0; n < 8; ++n) { const f32x4 v0 = o0[n] * rinv0, v1 = o1[n] * rinv1; u32x2 w0, w1; w0.x = pk2(v0[0], v0[1]); w0.y = pk2(v0[2], v0[3]); w1.x = pk2(v1[0], v1[1]); w1.y = pk2(v1[2], v1[3]);
;             wt_store8(wsr, qp0 + (nh * 8 + n) * 16 + 4 * fq, w0); wt_store8(wsr, qp1 + (nh * 8 + n) * 16 + 4 * fq, w1); }
;         __builtin_amdgcn_sched_barrier(0);
;     }
;     __syncthreads();
	v_mfma_f32_16x16x32_bf16 v[60:63], v[124:127], v[8:11], v[60:63]
	v_mfma_f32_16x16x32_bf16 v[114:117], v[84:87], v[12:15], v[116:119]
	v_mfma_f32_16x16x32_bf16 v[84:87], v[84:87], v[4:7], v[120:123]
	s_nop 2
	ds_read2_b64 v[118:121], v97 offset1:4
	v_add_u32_e32 v97, v109, v108
	v_mfma_f32_16x16x32_bf16 v[80:83], v[124:127], v[0:3], v[80:83]
	ds_read2_b64 v[134:137], v97 offset1:4
	v_add_u32_e32 v97, v109, v107
	ds_read2_b64 v[138:141], v97 offset1:4
	v_add_u32_e32 v97, v109, v104
	v_mfma_f32_16x16x32_bf16 v[16:19], v[72:75], v[16:19], v[56:59]
	v_add_u32_e32 v72, v110, v105
	v_pk_mul_f32 v[122:123], v[102:103], v[60:61] op_sel_hi:[0,1]
	s_nop 0
	v_pk_mul_f32 v[82:83], v[100:101], v[82:83] op_sel_hi:[0,1]
	v_add_u32_e32 v56, v110, v107
	s_waitcnt lgkmcnt(4)
	v_mfma_f32_16x16x32_bf16 v[52:55], v[36:39], v[12:15], v[52:55]
	ds_read2_b64 v[56:59], v56 offset1:4
	ds_read2_b64 v[72:75], v72 offset1:4
	ds_read2_b64 v[110:113], v99 offset1:4
	v_mfma_f32_16x16x32_bf16 v[36:39], v[36:39], v[4:7], v[48:51]
	s_nop 2
	v_add_u32_e32 v48, v109, v105
	ds_read2_b64 v[104:107], v97 offset1:4
	v_add_u32_e32 v97, v109, v101
	v_pk_mul_f32 v[108:109], v[102:103], v[62:63] op_sel_hi:[0,1]
	s_waitcnt lgkmcnt(7)
	v_mfma_f32_16x16x32_bf16 v[60:63], v[88:91], v[12:15], v[68:71]
	ds_read2_b64 v[48:51], v48 offset1:4
	ds_read2_b64 v[142:145], v97 offset1:4
	s_nop 0
	v_pk_mul_f32 v[68:69], v[100:101], v[80:81] op_sel_hi:[0,1]
	v_cvt_pk_bf16_f32 v70, v122, v123
	v_cvt_pk_bf16_f32 v71, v108, v109
	v_cvt_pk_bf16_f32 v80, v68, v69
	buffer_store_dwordx2 v[70:71], v96, s[88:91], 0 offen offset:256
	v_mfma_f32_16x16x32_bf16 v[68:71], v[130:133], v[8:11], v[114:117]
	v_cvt_pk_bf16_f32 v81, v82, v83
	buffer_store_dwordx2 v[80:81], v98, s[88:91], 0 offen offset:256
	s_waitcnt lgkmcnt(8)
	v_mfma_f32_16x16x32_bf16 v[36:39], v[118:121], v[0:3], v[36:39]
	v_mfma_f32_16x16x32_bf16 v[52:55], v[118:121], v[8:11], v[52:55]
	s_nop 2
	v_mul_f32_e64 v80, v102, v70
	v_mul_f32_e64 v81, v102, v71
	v_pk_mul_f32 v[82:83], v[102:103], v[68:69] op_sel_hi:[0,1]
	v_cvt_pk_bf16_f32 v82, v82, v83
	v_mfma_f32_16x16x32_bf16 v[68:71], v[130:133], v[0:3], v[84:87]
	v_cvt_pk_bf16_f32 v83, v80, v81
	v_pk_mul_f32 v[54:55], v[102:103], v[54:55] op_sel_hi:[0,1]
	v_pk_mul_f32 v[52:53], v[102:103], v[52:53] op_sel_hi:[0,1]
	v_cvt_pk_bf16_f32 v52, v52, v53
	v_cvt_pk_bf16_f32 v53, v54, v55
	s_nop 2
	v_pk_mul_f32 v[84:85], v[100:101], v[70:71] op_sel_hi:[0,1]
	v_pk_mul_f32 v[86:87], v[100:101], v[68:69] op_sel_hi:[0,1]
	s_waitcnt lgkmcnt(5)
	v_mfma_f32_16x16x32_bf16 v[68:71], v[56:59], v[12:15], v[76:79]
	s_nop 2
	v_cvt_pk_bf16_f32 v76, v86, v87
	v_cvt_pk_bf16_f32 v77, v84, v85
	buffer_store_dwordx2 v[82:83], v96, s[88:91], 0 offen offset:288
	buffer_store_dwordx2 v[76:77], v98, s[88:91], 0 offen offset:288
	v_pk_mul_f32 v[76:77], v[100:101], v[38:39] op_sel_hi:[0,1]
	v_pk_mul_f32 v[78:79], v[100:101], v[36:37] op_sel_hi:[0,1]
	v_mfma_f32_16x16x32_bf16 v[36:39], v[56:59], v[4:7], v[44:47]
	v_cvt_pk_bf16_f32 v54, v78, v79
	v_cvt_pk_bf16_f32 v55, v76, v77
	buffer_store_dwordx2 v[52:53], v96, s[88:91], 0 offen offset:320
	buffer_store_dwordx2 v[54:55], v98, s[88:91], 0 offen offset:320
	v_mfma_f32_16x16x32_bf16 v[44:47], v[134:137], v[8:11], v[60:63]
	v_mfma_f32_16x16x32_bf16 v[36:39], v[138:141], v[0:3], v[36:39]
	v_mfma_f32_16x16x32_bf16 v[64:67], v[88:91], v[4:7], v[64:67]
	s_nop 5
	v_mul_f32_e64 v46, v102, v46
	v_mul_f32_e64 v47, v102, v47
	v_pk_mul_f32 v[44:45], v[102:103], v[44:45] op_sel_hi:[0,1]
	v_cvt_pk_bf16_f32 v44, v44, v45
	v_cvt_pk_bf16_f32 v45, v46, v47
	buffer_store_dwordx2 v[44:45], v96, s[88:91], 0 offen offset:352
	v_mfma_f32_16x16x32_bf16 v[44:47], v[138:141], v[8:11], v[68:71]
	v_mul_f32_e64 v38, v100, v38
	v_mul_f32_e64 v39, v100, v39
	v_pk_mul_f32 v[36:37], v[100:101], v[36:37] op_sel_hi:[0,1]
	s_waitcnt lgkmcnt(4)
	v_mfma_f32_16x16x32_bf16 v[40:43], v[72:75], v[12:15], v[40:43]
	v_mfma_f32_16x16x32_bf16 v[28:31], v[92:95], v[12:15], v[28:31]
	s_nop 1
	v_mul_f32_e64 v46, v102, v46
	v_mul_f32_e64 v47, v102, v47
	v_pk_mul_f32 v[44:45], v[102:103], v[44:45] op_sel_hi:[0,1]
	v_cvt_pk_bf16_f32 v44, v44, v45
	v_mfma_f32_16x16x32_bf16 v[20:23], v[92:95], v[4:7], v[20:23]
	v_cvt_pk_bf16_f32 v45, v46, v47
	v_cvt_pk_bf16_f32 v46, v36, v37
	v_cvt_pk_bf16_f32 v47, v38, v39
	s_waitcnt lgkmcnt(3)
	v_mfma_f32_16x16x32_bf16 v[12:15], v[110:113], v[12:15], v[24:27]
	v_mfma_f32_16x16x32_bf16 v[32:35], v[72:75], v[4:7], v[32:35]
	v_mfma_f32_16x16x32_bf16 v[4:7], v[110:113], v[4:7], v[16:19]
	v_mfma_f32_16x16x32_bf16 v[52:55], v[134:137], v[0:3], v[64:67]
	s_waitcnt lgkmcnt(1)
	v_mfma_f32_16x16x32_bf16 v[36:39], v[48:51], v[8:11], v[40:43]
	v_mfma_f32_16x16x32_bf16 v[28:31], v[104:107], v[8:11], v[28:31]
	s_nop 4
	v_mul_f32_e64 v54, v100, v54
	v_mul_f32_e64 v55, v100, v55
	v_pk_mul_f32 v[52:53], v[100:101], v[52:53] op_sel_hi:[0,1]
	v_pk_mul_f32 v[38:39], v[102:103], v[38:39] op_sel_hi:[0,1]
	v_mfma_f32_16x16x32_bf16 v[20:23], v[104:107], v[0:3], v[20:23]
	v_mul_f32_e64 v36, v102, v36
	v_mul_f32_e64 v37, v102, v37
	v_pk_mul_f32 v[30:31], v[102:103], v[30:31] op_sel_hi:[0,1]
	v_pk_mul_f32 v[28:29], v[102:103], v[28:29] op_sel_hi:[0,1]
	s_waitcnt lgkmcnt(0)
	v_mfma_f32_16x16x32_bf16 v[8:11], v[142:145], v[8:11], v[12:15]
	v_cvt_pk_bf16_f32 v52, v52, v53
	s_nop 0
	v_pk_mul_f32 v[22:23], v[100:101], v[22:23] op_sel_hi:[0,1]
	v_pk_mul_f32 v[20:21], v[100:101], v[20:21] op_sel_hi:[0,1]
	v_mfma_f32_16x16x32_bf16 v[32:35], v[48:51], v[0:3], v[32:35]
	v_cvt_pk_bf16_f32 v53, v54, v55
	s_nop 1
	v_pk_mul_f32 v[10:11], v[102:103], v[10:11] op_sel_hi:[0,1]
	v_pk_mul_f32 v[8:9], v[102:103], v[8:9] op_sel_hi:[0,1]
	v_mfma_f32_16x16x32_bf16 v[0:3], v[142:145], v[0:3], v[4:7]
	v_cvt_pk_bf16_f32 v36, v36, v37
	s_nop 0
	v_pk_mul_f32 v[34:35], v[100:101], v[34:35] op_sel_hi:[0,1]
	v_pk_mul_f32 v[32:33], v[100:101], v[32:33] op_sel_hi:[0,1]
	v_cvt_pk_bf16_f32 v37, v38, v39
	v_cvt_pk_bf16_f32 v24, v28, v29
	v_cvt_pk_bf16_f32 v25, v30, v31
	v_cvt_pk_bf16_f32 v16, v20, v21
	v_cvt_pk_bf16_f32 v17, v22, v23
	v_pk_mul_f32 v[2:3], v[100:101], v[2:3] op_sel_hi:[0,1]
	v_pk_mul_f32 v[0:1], v[100:101], v[0:1] op_sel_hi:[0,1]
	v_cvt_pk_bf16_f32 v4, v8, v9
	v_cvt_pk_bf16_f32 v5, v10, v11
	buffer_store_dwordx2 v[52:53], v98, s[88:91], 0 offen offset:352
	buffer_store_dwordx2 v[44:45], v96, s[88:91], 0 offen offset:384
	buffer_store_dwordx2 v[46:47], v98, s[88:91], 0 offen offset:384
	v_cvt_pk_bf16_f32 v32, v32, v33
	v_cvt_pk_bf16_f32 v33, v34, v35
	buffer_store_dwordx2 v[36:37], v96, s[88:91], 0 offen offset:416
	buffer_store_dwordx2 v[32:33], v98, s[88:91], 0 offen offset:416
	buffer_store_dwordx2 v[24:25], v96, s[88:91], 0 offen offset:448
	buffer_store_dwordx2 v[16:17], v98, s[88:91], 0 offen offset:448
	v_cvt_pk_bf16_f32 v0, v0, v1
	v_cvt_pk_bf16_f32 v1, v2, v3
	buffer_store_dwordx2 v[4:5], v96, s[88:91], 0 offen offset:480
	buffer_store_dwordx2 v[0:1], v98, s[88:91], 0 offen offset:480
.Lpp8_done:
	s_barrier

; __device__ __forceinline__ unsigned cvt_pk_bf16(float lo, float hi) { f32x2_t v = {lo, hi}; bf16x2_t b = __builtin_convertvector(v, bf16x2_t); return __builtin_bit_cast(unsigned, b); }
;     __device__ __forceinline__ void operator()(const f32x4 (&acc)[2][2][4][2], const Unit& u, int wr, int wc, int fr, int fq) const {
;     ...
;             for (int m = 0; m < 4; ++m) { const int row = u.pm * BM + ai * HALF + wr * 64 + m * 16 + fr; const size_t off = (size_t)row * ldc + col0; float ss = 0.f;
; #pragma unroll
;                 for (int bj = 0; bj < 2; ++bj) { const size_t o2 = off + bj * HALF; f32x4 b0, b1;
;                     if (MODE == 0) { b0 = *(const f32x4*)(basef + o2); b1 = *(const f32x4*)(basef + o2 + 4); }
;                     else { const u32x4 w = *(const u32x4*)(xb + o2);
;                         b0 = (f32x4){__uint_as_float(w.x << 16), __uint_as_float(w.x & 0xffff0000u), __uint_as_float(w.y << 16), __uint_as_float(w.y & 0xffff0000u)};
;                         b1 = (f32x4){__uint_as_float(w.z << 16), __uint_as_float(w.z & 0xffff0000u), __uint_as_float(w.w << 16), __uint_as_float(w.w & 0xffff0000u)}; }
;                     const f32x4 v0 = b0 + acc[ai][bj][m][0], v1 = b1 + acc[ai][bj][m][1];
;                     if (MODE == 2) { *(f32x4*)(outf + o2) = v0; *(f32x4*)(outf + o2 + 4) = v1; }
;                     else { ss += (v0[0] * v0[0] + v0[1] * v0[1]) + (v0[2] * v0[2] + v0[3] * v0[3]) + (v1[0] * v1[0] + v1[1] * v1[1]) + (v1[2] * v1[2] + v1[3] * v1[3]);
;                         u32x4 w; w.x = cvt_pk_bf16(v0[0], v0[1]); w.y = cvt_pk_bf16(v0[2], v0[3]); w.z = cvt_pk_bf16(v1[0], v1[1]); w.w = cvt_pk_bf16(v1[2], v1[3]);
;                         __builtin_amdgcn_raw_buffer_store_b128(w, rsrc, (unsigned)(o2 * 2), 0, 16); } }
;                 if (MODE != 2) { ss += __shfl_xor(ss, 16); ss += __shfl_xor(ss, 32); if (fq == 0) atomicAdd(rowsq + row, ss); } }
.LBB0_801:
	v_readlane_b32 vcc_lo, v255, 59
	s_mov_b32 vcc_hi, 0
	s_nop 1
	s_mov_b64 vcc, vcc
	s_nop 1
	s_cbranch_vccnz .Lpp9_plain
	v_lshl_add_u32 v148, s40, 8, v129
	v_lshl_or_b32 v146, s42, 8, v151
	v_ashrrev_i32_e32 v149, 31, v148
	v_ashrrev_i32_e32 v147, 31, v146
	v_lshlrev_b64 v[156:157], 10, v[148:149]
	v_lshl_add_u64 v[160:161], v[156:157], 0, v[146:147]
	v_lshl_add_u64 v[156:157], v[160:161], 1, s[96:97]
	global_load_dwordx4 v[156:159], v[156:157], off
	v_lshlrev_b32_e32 v168, 1, v160
	v_or_b32_e32 v160, 0x80, v160
	v_lshl_add_u64 v[162:163], v[160:161], 1, s[96:97]
	v_xor_b32_e32 v161, 32, v155
	s_waitcnt vmcnt(0)
	v_lshlrev_b32_e32 v164, 16, v156
	v_and_b32_e32 v165, 0xffff0000, v156
	v_lshlrev_b32_e32 v156, 16, v157
	v_and_b32_e32 v157, 0xffff0000, v157
	v_lshlrev_b32_e32 v166, 16, v158
	v_and_b32_e32 v167, 0xffff0000, v158
	v_lshlrev_b32_e32 v158, 16, v159
	v_and_b32_e32 v159, 0xffff0000, v159
	v_pk_add_f32 v[126:127], v[126:127], v[156:157]
	v_pk_add_f32 v[156:157], v[124:125], v[164:165]
	v_pk_add_f32 v[158:159], v[122:123], v[158:159]
	v_pk_add_f32 v[164:165], v[120:121], v[166:167]
	v_cvt_pk_bf16_f32 v120, v156, v157
	v_cvt_pk_bf16_f32 v121, v126, v127
	v_cvt_pk_bf16_f32 v122, v164, v165
	v_cvt_pk_bf16_f32 v123, v158, v159
	buffer_store_dwordx4 v[120:123], v168, s[12:15], 0 offen sc1
	global_load_dwordx4 v[122:125], v[162:163], off
	v_mul_f32_e32 v157, v157, v157
	v_mul_f32_e32 v127, v127, v127
	v_mul_f32_e32 v162, v165, v165
	v_fmac_f32_e32 v157, v156, v156
	v_fmac_f32_e32 v127, v126, v126
	v_mul_f32_e32 v159, v159, v159
	v_fmac_f32_e32 v162, v164, v164
	v_add_f32_e32 v126, v157, v127
	v_fmac_f32_e32 v159, v158, v158
	v_add_f32_e32 v126, v162, v126
	v_add_f32_e32 v158, v159, v126
	v_and_b32_e32 v121, 64, v155
	v_xor_b32_e32 v120, 16, v155
	v_add_u32_e32 v121, 64, v121
	v_cmp_lt_i32_e32 vcc, v120, v121
	s_waitcnt vmcnt(0)
	v_lshlrev_b32_e32 v126, 16, v122
	v_and_b32_e32 v127, 0xffff0000, v122
	v_lshlrev_b32_e32 v122, 16, v123
	v_and_b32_e32 v123, 0xffff0000, v123
	v_lshlrev_b32_e32 v156, 16, v124
	v_and_b32_e32 v157, 0xffff0000, v124
	v_lshlrev_b32_e32 v124, 16, v125
	v_and_b32_e32 v125, 0xffff0000, v125
	v_pk_add_f32 v[118:119], v[118:119], v[122:123]
	v_pk_add_f32 v[116:117], v[116:117], v[126:127]
	v_pk_add_f32 v[122:123], v[114:115], v[124:125]
	v_pk_add_f32 v[124:125], v[112:113], v[156:157]
	v_mul_f32_e32 v112, v117, v117
	v_mul_f32_e32 v113, v119, v119
	v_mul_f32_e32 v114, v125, v125
	v_fmac_f32_e32 v112, v116, v116
	v_fmac_f32_e32 v113, v118, v118
	v_mul_f32_e32 v115, v123, v123
	v_fmac_f32_e32 v114, v124, v124
	v_add_f32_e32 v112, v112, v113
	v_fmac_f32_e32 v115, v122, v122
	v_add_f32_e32 v112, v114, v112
	v_cndmask_b32_e32 v120, v155, v120, vcc
	v_add_f32_e32 v112, v115, v112
	v_lshlrev_b32_e32 v120, 2, v120
	v_add_f32_e32 v112, v158, v112
	ds_bpermute_b32 v113, v120, v112
	v_cmp_lt_i32_e32 vcc, v161, v121
	v_cvt_pk_bf16_f32 v116, v116, v117
	v_cvt_pk_bf16_f32 v117, v118, v119
	v_cndmask_b32_e32 v114, v155, v161, vcc
	v_lshlrev_b32_e32 v114, 2, v114
	s_waitcnt lgkmcnt(0)
	v_add_f32_e32 v112, v112, v113
	ds_bpermute_b32 v113, v114, v112
	v_cvt_pk_bf16_f32 v118, v124, v125
	v_cvt_pk_bf16_f32 v119, v122, v123
	v_lshlrev_b32_e32 v115, 1, v160
	buffer_store_dwordx4 v[116:119], v115, s[12:15], 0 offen sc1
	s_and_saveexec_b64 s[40:41], s[6:7]
	s_cbranch_execz .LBB0_803
	v_lshl_add_u64 v[116:117], v[148:149], 2, s[10:11]
	s_waitcnt lgkmcnt(0)
	v_add_f32_e32 v112, v112, v113
	global_atomic_add_f32 v[116:117], v112, off

; __device__ __forceinline__ unsigned cvt_pk_bf16(float lo, float hi) { f32x2_t v = {lo, hi}; bf16x2_t b = __builtin_convertvector(v, bf16x2_t); return __builtin_bit_cast(unsigned, b); }
;     __device__ __forceinline__ void operator()(const f32x4 (&acc)[2][2][4][2], const Unit& u, int wr, int wc, int fr, int fq) const {
;     ...
;             for (int m = 0; m < 4; ++m) { const int row = u.pm * BM + ai * HALF + wr * 64 + m * 16 + fr; const size_t off = (size_t)row * ldc + col0; float ss = 0.f;
; #pragma unroll
;                 for (int bj = 0; bj < 2; ++bj) { const size_t o2 = off + bj * HALF; f32x4 b0, b1;
;                     if (MODE == 0) { b0 = *(const f32x4*)(basef + o2); b1 = *(const f32x4*)(basef + o2 + 4); }
;                     else { const u32x4 w = *(const u32x4*)(xb + o2);
;                         b0 = (f32x4){__uint_as_float(w.x << 16), __uint_as_float(w.x & 0xffff0000u), __uint_as_float(w.y << 16), __uint_as_float(w.y & 0xffff0000u)};
;                         b1 = (f32x4){__uint_as_float(w.z << 16), __uint_as_float(w.z & 0xffff0000u), __uint_as_float(w.w << 16), __uint_as_float(w.w & 0xffff0000u)}; }
;                     const f32x4 v0 = b0 + acc[ai][bj][m][0], v1 = b1 + acc[ai][bj][m][1];
;                     if (MODE == 2) { *(f32x4*)(outf + o2) = v0; *(f32x4*)(outf + o2 + 4) = v1; }
;                     else { ss += (v0[0] * v0[0] + v0[1] * v0[1]) + (v0[2] * v0[2] + v0[3] * v0[3]) + (v1[0] * v1[0] + v1[1] * v1[1]) + (v1[2] * v1[2] + v1[3] * v1[3]);
;                         u32x4 w; w.x = cvt_pk_bf16(v0[0], v0[1]); w.y = cvt_pk_bf16(v0[2], v0[3]); w.z = cvt_pk_bf16(v1[0], v1[1]); w.w = cvt_pk_bf16(v1[2], v1[3]);
;                         __builtin_amdgcn_raw_buffer_store_b128(w, rsrc, (unsigned)(o2 * 2), 0, 16); } }
;                 if (MODE != 2) { ss += __shfl_xor(ss, 16); ss += __shfl_xor(ss, 32); if (fq == 0) atomicAdd(rowsq + row, ss); } }
.Lpp9_plain:
	v_lshl_add_u32 v148, s40, 8, v129
	v_lshl_or_b32 v146, s42, 8, v151
	v_ashrrev_i32_e32 v149, 31, v148
	v_ashrrev_i32_e32 v147, 31, v146
	v_lshlrev_b64 v[156:157], 10, v[148:149]
	v_lshl_add_u64 v[160:161], v[156:157], 0, v[146:147]
	v_lshl_add_u64 v[156:157], v[160:161], 1, s[96:97]
	global_load_dwordx4 v[156:159], v[156:157], off
	v_lshlrev_b32_e32 v168, 1, v160
	v_or_b32_e32 v160, 0x80, v160
	v_lshl_add_u64 v[162:163], v[160:161], 1, s[96:97]
	v_xor_b32_e32 v161, 32, v155
	s_waitcnt vmcnt(0)
	v_lshlrev_b32_e32 v164, 16, v156
	v_and_b32_e32 v165, 0xffff0000, v156
	v_lshlrev_b32_e32 v156, 16, v157
	v_and_b32_e32 v157, 0xffff0000, v157
	v_lshlrev_b32_e32 v166, 16, v158
	v_and_b32_e32 v167, 0xffff0000, v158
	v_lshlrev_b32_e32 v158, 16, v159
	v_and_b32_e32 v159, 0xffff0000, v159
	v_pk_add_f32 v[126:127], v[126:127], v[156:157]
	v_pk_add_f32 v[156:157], v[124:125], v[164:165]
	v_pk_add_f32 v[158:159], v[122:123], v[158:159]
	v_pk_add_f32 v[164:165], v[120:121], v[166:167]
	v_cvt_pk_bf16_f32 v120, v156, v157
	v_cvt_pk_bf16_f32 v121, v126, v127
	v_cvt_pk_bf16_f32 v122, v164, v165
	v_cvt_pk_bf16_f32 v123, v158, v159
	buffer_store_dwordx4 v[120:123], v168, s[12:15], 0 offen
	global_load_dwordx4 v[122:125], v[162:163], off
	v_mul_f32_e32 v157, v157, v157
	v_mul_f32_e32 v127, v127, v127
	v_mul_f32_e32 v162, v165, v165
	v_fmac_f32_e32 v157, v156, v156
	v_fmac_f32_e32 v127, v126, v126
	v_mul_f32_e32 v159, v159, v159
	v_fmac_f32_e32 v162, v164, v164
	v_add_f32_e32 v126, v157, v127
	v_fmac_f32_e32 v159, v158, v158
	v_add_f32_e32 v126, v162, v126
	v_add_f32_e32 v158, v159, v126
	v_and_b32_e32 v121, 64, v155
	v_xor_b32_e32 v120, 16, v155
	v_add_u32_e32 v121, 64, v121
	v_cmp_lt_i32_e32 vcc, v120, v121
	s_waitcnt vmcnt(0)
	v_lshlrev_b32_e32 v126, 16, v122
	v_and_b32_e32 v127, 0xffff0000, v122
	v_lshlrev_b32_e32 v122, 16, v123
	v_and_b32_e32 v123, 0xffff0000, v123
	v_lshlrev_b32_e32 v156, 16, v124
	v_and_b32_e32 v157, 0xffff0000, v124
	v_lshlrev_b32_e32 v124, 16, v125
	v_and_b32_e32 v125, 0xffff0000, v125
	v_pk_add_f32 v[118:119], v[118:119], v[122:123]
	v_pk_add_f32 v[116:117], v[116:117], v[126:127]
	v_pk_add_f32 v[122:123], v[114:115], v[124:125]
	v_pk_add_f32 v[124:125], v[112:113], v[156:157]
	v_mul_f32_e32 v112, v117, v117
	v_mul_f32_e32 v113, v119, v119
	v_mul_f32_e32 v114, v125, v125
	v_fmac_f32_e32 v112, v116, v116
	v_fmac_f32_e32 v113, v118, v118
	v_mul_f32_e32 v115, v123, v123
	v_fmac_f32_e32 v114, v124, v124
	v_add_f32_e32 v112, v112, v113
	v_fmac_f32_e32 v115, v122, v122
	v_add_f32_e32 v112, v114, v112
	v_cndmask_b32_e32 v120, v155, v120, vcc
	v_add_f32_e32 v112, v115, v112
	v_lshlrev_b32_e32 v120, 2, v120
	v_add_f32_e32 v112, v158, v112
	ds_bpermute_b32 v113, v120, v112
	v_cmp_lt_i32_e32 vcc, v161, v121
	v_cvt_pk_bf16_f32 v116, v116, v117
	v_cvt_pk_bf16_f32 v117, v118, v119
	v_cndmask_b32_e32 v114, v155, v161, vcc
	v_lshlrev_b32_e32 v114, 2, v114
	s_waitcnt lgkmcnt(0)
	v_add_f32_e32 v112, v112, v113
	ds_bpermute_b32 v113, v114, v112
	v_cvt_pk_bf16_f32 v118, v124, v125
	v_cvt_pk_bf16_f32 v119, v122, v123
	v_lshlrev_b32_e32 v115, 1, v160
	buffer_store_dwordx4 v[116:119], v115, s[12:15], 0 offen
	s_and_saveexec_b64 s[40:41], s[6:7]
	s_cbranch_execz .Lpp9_803
	v_lshl_add_u64 v[116:117], v[148:149], 2, s[10:11]
	s_waitcnt lgkmcnt(0)
	v_add_f32_e32 v112, v112, v113
	global_atomic_add_f32 v[116:117], v112, off
.Lpp9_803:
	s_or_b64 exec, exec, s[40:41]
	v_or_b32_e32 v112, 16, v148
	s_waitcnt lgkmcnt(0)
	v_ashrrev_i32_e32 v113, 31, v112
	v_lshlrev_b64 v[116:117], 10, v[112:113]
	v_lshl_add_u64 v[122:123], v[116:117], 0, v[146:147]
	v_lshl_add_u64 v[116:117], v[122:123], 1, s[96:97]
	global_load_dwordx4 v[116:119], v[116:117], off
	v_lshlrev_b32_e32 v115, 1, v122
	v_or_b32_e32 v122, 0x80, v122
	v_lshl_add_u64 v[124:125], v[122:123], 1, s[96:97]
	s_waitcnt vmcnt(0)
	v_lshlrev_b32_e32 v126, 16, v116
	v_and_b32_e32 v127, 0xffff0000, v116
	v_lshlrev_b32_e32 v116, 16, v117
	v_and_b32_e32 v117, 0xffff0000, v117
	v_lshlrev_b32_e32 v156, 16, v118
	v_and_b32_e32 v157, 0xffff0000, v118
	v_lshlrev_b32_e32 v118, 16, v119
	v_and_b32_e32 v119, 0xffff0000, v119
	v_pk_add_f32 v[110:111], v[110:111], v[116:117]
	v_pk_add_f32 v[108:109], v[108:109], v[126:127]
	v_pk_add_f32 v[116:117], v[106:107], v[118:119]
	v_pk_add_f32 v[118:119], v[104:105], v[156:157]
	v_cvt_pk_bf16_f32 v104, v108, v109
	v_cvt_pk_bf16_f32 v105, v110, v111
	v_cvt_pk_bf16_f32 v106, v118, v119
	v_cvt_pk_bf16_f32 v107, v116, v117
	buffer_store_dwordx4 v[104:107], v115, s[12:15], 0 offen
	global_load_dwordx4 v[104:107], v[124:125], off
	v_mul_f32_e32 v109, v109, v109
	v_mul_f32_e32 v111, v111, v111
	v_mul_f32_e32 v115, v119, v119
	v_fmac_f32_e32 v109, v108, v108
	v_fmac_f32_e32 v111, v110, v110
	v_mul_f32_e32 v117, v117, v117
	v_fmac_f32_e32 v115, v118, v118
	v_add_f32_e32 v108, v109, v111
	v_fmac_f32_e32 v117, v116, v116
	v_add_f32_e32 v108, v115, v108
	v_add_f32_e32 v115, v117, v108
	s_waitcnt vmcnt(0)
	v_lshlrev_b32_e32 v108, 16, v104
	v_and_b32_e32 v109, 0xffff0000, v104
	v_lshlrev_b32_e32 v104, 16, v105
	v_and_b32_e32 v105, 0xffff0000, v105
	v_lshlrev_b32_e32 v110, 16, v106
	v_and_b32_e32 v111, 0xffff0000, v106
	v_lshlrev_b32_e32 v106, 16, v107
	v_and_b32_e32 v107, 0xffff0000, v107
	v_pk_add_f32 v[102:103], v[102:103], v[104:105]
	v_pk_add_f32 v[100:101], v[100:101], v[108:109]
	v_pk_add_f32 v[104:105], v[98:99], v[106:107]
	v_pk_add_f32 v[106:107], v[96:97], v[110:111]
	v_mul_f32_e32 v96, v101, v101
	v_mul_f32_e32 v97, v103, v103
	v_mul_f32_e32 v98, v107, v107
	v_fmac_f32_e32 v96, v100, v100
	v_fmac_f32_e32 v97, v102, v102
	v_mul_f32_e32 v99, v105, v105
	v_fmac_f32_e32 v98, v106, v106
	v_add_f32_e32 v96, v96, v97
	v_add_f32_e32 v96, v98, v96
	v_fmac_f32_e32 v99, v104, v104
	v_add_f32_e32 v96, v99, v96
	v_add_f32_e32 v96, v115, v96
	ds_bpermute_b32 v97, v120, v96
	v_cvt_pk_bf16_f32 v98, v100, v101
	v_cvt_pk_bf16_f32 v99, v102, v103
	v_cvt_pk_bf16_f32 v100, v106, v107
	v_cvt_pk_bf16_f32 v101, v104, v105
	s_waitcnt lgkmcnt(0)
	v_add_f32_e32 v96, v96, v97
	ds_bpermute_b32 v97, v114, v96
	v_lshlrev_b32_e32 v102, 1, v122
	buffer_store_dwordx4 v[98:101], v102, s[12:15], 0 offen
	s_and_saveexec_b64 s[40:41], s[6:7]
	s_cbranch_execz .Lpp9_805
	v_lshl_add_u64 v[98:99], v[112:113], 2, s[10:11]
	s_waitcnt lgkmcnt(0)
	v_add_f32_e32 v96, v96, v97
	global_atomic_add_f32 v[98:99], v96, off
; __device__ __forceinline__ unsigned cvt_pk_bf16(float lo, float hi) { f32x2_t v = {lo, hi}; bf16x2_t b = __builtin_convertvector(v, bf16x2_t); return __builtin_bit_cast(unsigned, b); }
;     __device__ __forceinline__ void operator()(const f32x4 (&acc)[2][2][4][2], const Unit& u, int wr, int wc, int fr, int fq) const {
;     ...
;             for (int m = 0; m < 4; ++m) { const int row = u.pm * BM + ai * HALF + wr * 64 + m * 16 + fr; const size_t off = (size_t)row * ldc + col0; float ss = 0.f;
; #pragma unroll
;                 for (int bj = 0; bj < 2; ++bj) { const size_t o2 = off + bj * HALF; f32x4 b0, b1;
;                     if (MODE == 0) { b0 = *(const f32x4*)(basef + o2); b1 = *(const f32x4*)(basef + o2 + 4); }
;                     else { const u32x4 w = *(const u32x4*)(xb + o2);
;                         b0 = (f32x4){__uint_as_float(w.x << 16), __uint_as_float(w.x & 0xffff0000u), __uint_as_float(w.y << 16), __uint_as_float(w.y & 0xffff0000u)};
;                         b1 = (f32x4){__uint_as_float(w.z << 16), __uint_as_float(w.z & 0xffff0000u), __uint_as_float(w.w << 16), __uint_as_float(w.w & 0xffff0000u)}; }
;                     const f32x4 v0 = b0 + acc[ai][bj][m][0], v1 = b1 + acc[ai][bj][m][1];
;                     if (MODE == 2) { *(f32x4*)(outf + o2) = v0; *(f32x4*)(outf + o2 + 4) = v1; }
;                     else { ss += (v0[0] * v0[0] + v0[1] * v0[1]) + (v0[2] * v0[2] + v0[3] * v0[3]) + (v1[0] * v1[0] + v1[1] * v1[1]) + (v1[2] * v1[2] + v1[3] * v1[3]);
;                         u32x4 w; w.x = cvt_pk_bf16(v0[0], v0[1]); w.y = cvt_pk_bf16(v0[2], v0[3]); w.z = cvt_pk_bf16(v1[0], v1[1]); w.w = cvt_pk_bf16(v1[2], v1[3]);
;                         __builtin_amdgcn_raw_buffer_store_b128(w, rsrc, (unsigned)(o2 * 2), 0, 16); } }
;                 if (MODE != 2) { ss += __shfl_xor(ss, 16); ss += __shfl_xor(ss, 32); if (fq == 0) atomicAdd(rowsq + row, ss); } }
.Lpp9_805:
	s_or_b64 exec, exec, s[40:41]
	v_or_b32_e32 v96, 32, v148
	s_waitcnt lgkmcnt(0)
	v_ashrrev_i32_e32 v97, 31, v96
	v_lshlrev_b64 v[98:99], 10, v[96:97]
	v_lshl_add_u64 v[102:103], v[98:99], 0, v[146:147]
	v_lshl_add_u64 v[98:99], v[102:103], 1, s[96:97]
	global_load_dwordx4 v[98:101], v[98:99], off
	v_lshlrev_b32_e32 v110, 1, v102
	v_or_b32_e32 v102, 0x80, v102
	v_lshl_add_u64 v[104:105], v[102:103], 1, s[96:97]
	s_waitcnt vmcnt(0)
	v_lshlrev_b32_e32 v106, 16, v98
	v_and_b32_e32 v107, 0xffff0000, v98
	v_lshlrev_b32_e32 v98, 16, v99
	v_and_b32_e32 v99, 0xffff0000, v99
	v_lshlrev_b32_e32 v108, 16, v100
	v_and_b32_e32 v109, 0xffff0000, v100
	v_lshlrev_b32_e32 v100, 16, v101
	v_and_b32_e32 v101, 0xffff0000, v101
	v_pk_add_f32 v[94:95], v[94:95], v[98:99]
	v_pk_add_f32 v[92:93], v[92:93], v[106:107]
	v_pk_add_f32 v[98:99], v[90:91], v[100:101]
	v_pk_add_f32 v[100:101], v[88:89], v[108:109]
	v_cvt_pk_bf16_f32 v88, v92, v93
	v_cvt_pk_bf16_f32 v89, v94, v95
	v_cvt_pk_bf16_f32 v90, v100, v101
	v_cvt_pk_bf16_f32 v91, v98, v99
	buffer_store_dwordx4 v[88:91], v110, s[12:15], 0 offen
	global_load_dwordx4 v[88:91], v[104:105], off
	v_mul_f32_e32 v93, v93, v93
	v_mul_f32_e32 v95, v95, v95
	v_mul_f32_e32 v101, v101, v101
	v_fmac_f32_e32 v93, v92, v92
	v_fmac_f32_e32 v95, v94, v94
	v_mul_f32_e32 v99, v99, v99
	v_fmac_f32_e32 v101, v100, v100
	v_add_f32_e32 v92, v93, v95
	v_fmac_f32_e32 v99, v98, v98
	v_add_f32_e32 v92, v101, v92
	v_add_f32_e32 v98, v99, v92
	s_waitcnt vmcnt(0)
	v_lshlrev_b32_e32 v92, 16, v88
	v_and_b32_e32 v93, 0xffff0000, v88
	v_lshlrev_b32_e32 v88, 16, v89
	v_and_b32_e32 v89, 0xffff0000, v89
	v_lshlrev_b32_e32 v94, 16, v90
	v_and_b32_e32 v95, 0xffff0000, v90
	v_lshlrev_b32_e32 v90, 16, v91
	v_and_b32_e32 v91, 0xffff0000, v91
	v_pk_add_f32 v[86:87], v[86:87], v[88:89]
	v_pk_add_f32 v[84:85], v[84:85], v[92:93]
	v_pk_add_f32 v[88:89], v[82:83], v[90:91]
	v_pk_add_f32 v[90:91], v[80:81], v[94:95]
	v_mul_f32_e32 v80, v85, v85
	v_mul_f32_e32 v81, v87, v87
	v_mul_f32_e32 v82, v91, v91
	v_fmac_f32_e32 v80, v84, v84
	v_fmac_f32_e32 v81, v86, v86
	v_mul_f32_e32 v83, v89, v89
	v_fmac_f32_e32 v82, v90, v90
	v_add_f32_e32 v80, v80, v81
	v_add_f32_e32 v80, v82, v80
	v_fmac_f32_e32 v83, v88, v88
	v_add_f32_e32 v80, v83, v80
	v_add_f32_e32 v80, v98, v80
	ds_bpermute_b32 v81, v120, v80
	v_cvt_pk_bf16_f32 v82, v84, v85
	v_cvt_pk_bf16_f32 v83, v86, v87
	v_cvt_pk_bf16_f32 v84, v90, v91
	v_cvt_pk_bf16_f32 v85, v88, v89
	s_waitcnt lgkmcnt(0)
	v_add_f32_e32 v80, v80, v81
	ds_bpermute_b32 v81, v114, v80
	v_lshlrev_b32_e32 v86, 1, v102
	buffer_store_dwordx4 v[82:85], v86, s[12:15], 0 offen
	s_and_saveexec_b64 s[40:41], s[6:7]
	s_cbranch_execz .Lpp9_807
	v_lshl_add_u64 v[82:83], v[96:97], 2, s[10:11]
	s_waitcnt lgkmcnt(0)
	v_add_f32_e32 v80, v80, v81
	global_atomic_add_f32 v[82:83], v80, off
.Lpp9_807:
	s_or_b64 exec, exec, s[40:41]
	v_or_b32_e32 v80, 48, v148
	s_waitcnt lgkmcnt(0)
	v_ashrrev_i32_e32 v81, 31, v80
	v_lshlrev_b64 v[82:83], 10, v[80:81]
	v_lshl_add_u64 v[86:87], v[82:83], 0, v[146:147]
	v_lshl_add_u64 v[82:83], v[86:87], 1, s[96:97]
	global_load_dwordx4 v[82:85], v[82:83], off
	v_lshlrev_b32_e32 v94, 1, v86
	v_or_b32_e32 v86, 0x80, v86
	v_lshl_add_u64 v[88:89], v[86:87], 1, s[96:97]
	s_waitcnt vmcnt(0)
	v_lshlrev_b32_e32 v90, 16, v82
	v_and_b32_e32 v91, 0xffff0000, v82
	v_lshlrev_b32_e32 v82, 16, v83
	v_and_b32_e32 v83, 0xffff0000, v83
	v_lshlrev_b32_e32 v92, 16, v84
	v_and_b32_e32 v93, 0xffff0000, v84
	v_lshlrev_b32_e32 v84, 16, v85
	v_and_b32_e32 v85, 0xffff0000, v85
	v_pk_add_f32 v[78:79], v[78:79], v[82:83]
	v_pk_add_f32 v[76:77], v[76:77], v[90:91]
	v_pk_add_f32 v[82:83], v[74:75], v[84:85]
	v_pk_add_f32 v[84:85], v[72:73], v[92:93]
	v_cvt_pk_bf16_f32 v72, v76, v77
	v_cvt_pk_bf16_f32 v73, v78, v79
	v_cvt_pk_bf16_f32 v74, v84, v85
	v_cvt_pk_bf16_f32 v75, v82, v83
	buffer_store_dwordx4 v[72:75], v94, s[12:15], 0 offen
	global_load_dwordx4 v[72:75], v[88:89], off
	v_mul_f32_e32 v77, v77, v77
	v_mul_f32_e32 v79, v79, v79
	v_mul_f32_e32 v85, v85, v85
	v_fmac_f32_e32 v77, v76, v76
	v_fmac_f32_e32 v79, v78, v78
	v_mul_f32_e32 v83, v83, v83
	v_fmac_f32_e32 v85, v84, v84
	v_add_f32_e32 v76, v77, v79
	v_fmac_f32_e32 v83, v82, v82
	v_add_f32_e32 v76, v85, v76
	v_add_f32_e32 v82, v83, v76
	s_waitcnt vmcnt(0)
	v_lshlrev_b32_e32 v76, 16, v72
	v_and_b32_e32 v77, 0xffff0000, v72
	v_lshlrev_b32_e32 v72, 16, v73
	v_and_b32_e32 v73, 0xffff0000, v73
	v_lshlrev_b32_e32 v78, 16, v74
	v_and_b32_e32 v79, 0xffff0000, v74
	v_lshlrev_b32_e32 v74, 16, v75
	v_and_b32_e32 v75, 0xffff0000, v75
	v_pk_add_f32 v[70:71], v[70:71], v[72:73]
	v_pk_add_f32 v[68:69], v[68:69], v[76:77]
	v_pk_add_f32 v[72:73], v[66:67], v[74:75]
	v_pk_add_f32 v[74:75], v[64:65], v[78:79]
	v_mul_f32_e32 v64, v69, v69
	v_mul_f32_e32 v65, v71, v71
	v_mul_f32_e32 v66, v75, v75
	v_fmac_f32_e32 v64, v68, v68
	v_fmac_f32_e32 v65, v70, v70
	v_mul_f32_e32 v67, v73, v73
	v_fmac_f32_e32 v66, v74, v74
	v_add_f32_e32 v64, v64, v65
	v_add_f32_e32 v64, v66, v64
	v_fmac_f32_e32 v67, v72, v72
	v_add_f32_e32 v64, v67, v64
	v_add_f32_e32 v64, v82, v64
	ds_bpermute_b32 v65, v120, v64
	v_cvt_pk_bf16_f32 v66, v68, v69
	v_cvt_pk_bf16_f32 v67, v70, v71
	v_cvt_pk_bf16_f32 v68, v74, v75
	v_cvt_pk_bf16_f32 v69, v72, v73
	s_waitcnt lgkmcnt(0)
	v_add_f32_e32 v64, v64, v65
	ds_bpermute_b32 v65, v114, v64
	v_lshlrev_b32_e32 v70, 1, v86
	buffer_store_dwordx4 v[66:69], v70, s[12:15], 0 offen
	s_and_saveexec_b64 s[40:41], s[6:7]
	s_cbranch_execz .Lpp9_809
	v_lshl_add_u64 v[66:67], v[80:81], 2, s[10:11]
	s_waitcnt lgkmcnt(0)
	v_add_f32_e32 v64, v64, v65
	global_atomic_add_f32 v[66:67], v64, off
; __device__ __forceinline__ unsigned cvt_pk_bf16(float lo, float hi) { f32x2_t v = {lo, hi}; bf16x2_t b = __builtin_convertvector(v, bf16x2_t); return __builtin_bit_cast(unsigned, b); }
;     __device__ __forceinline__ void operator()(const f32x4 (&acc)[2][2][4][2], const Unit& u, int wr, int wc, int fr, int fq) const {
;     ...
;             for (int m = 0; m < 4; ++m) { const int row = u.pm * BM + ai * HALF + wr * 64 + m * 16 + fr; const size_t off = (size_t)row * ldc + col0; float ss = 0.f;
; #pragma unroll
;                 for (int bj = 0; bj < 2; ++bj) { const size_t o2 = off + bj * HALF; f32x4 b0, b1;
;                     if (MODE == 0) { b0 = *(const f32x4*)(basef + o2); b1 = *(const f32x4*)(basef + o2 + 4); }
;                     else { const u32x4 w = *(const u32x4*)(xb + o2);
;                         b0 = (f32x4){__uint_as_float(w.x << 16), __uint_as_float(w.x & 0xffff0000u), __uint_as_float(w.y << 16), __uint_as_float(w.y & 0xffff0000u)};
;                         b1 = (f32x4){__uint_as_float(w.z << 16), __uint_as_float(w.z & 0xffff0000u), __uint_as_float(w.w << 16), __uint_as_float(w.w & 0xffff0000u)}; }
;                     const f32x4 v0 = b0 + acc[ai][bj][m][0], v1 = b1 + acc[ai][bj][m][1];
;                     if (MODE == 2) { *(f32x4*)(outf + o2) = v0; *(f32x4*)(outf + o2 + 4) = v1; }
;                     else { ss += (v0[0] * v0[0] + v0[1] * v0[1]) + (v0[2] * v0[2] + v0[3] * v0[3]) + (v1[0] * v1[0] + v1[1] * v1[1]) + (v1[2] * v1[2] + v1[3] * v1[3]);
;                         u32x4 w; w.x = cvt_pk_bf16(v0[0], v0[1]); w.y = cvt_pk_bf16(v0[2], v0[3]); w.z = cvt_pk_bf16(v1[0], v1[1]); w.w = cvt_pk_bf16(v1[2], v1[3]);
;                         __builtin_amdgcn_raw_buffer_store_b128(w, rsrc, (unsigned)(o2 * 2), 0, 16); } }
;                 if (MODE != 2) { ss += __shfl_xor(ss, 16); ss += __shfl_xor(ss, 32); if (fq == 0) atomicAdd(rowsq + row, ss); } }
.Lpp9_809:
	s_or_b64 exec, exec, s[40:41]
	v_add_u32_e32 v64, 0x80, v148
	s_waitcnt lgkmcnt(0)
	v_ashrrev_i32_e32 v65, 31, v64
	v_lshlrev_b64 v[66:67], 10, v[64:65]
	v_lshl_add_u64 v[70:71], v[66:67], 0, v[146:147]
	v_lshl_add_u64 v[66:67], v[70:71], 1, s[96:97]
	global_load_dwordx4 v[66:69], v[66:67], off
	v_lshlrev_b32_e32 v78, 1, v70
	v_or_b32_e32 v70, 0x80, v70
	v_lshl_add_u64 v[72:73], v[70:71], 1, s[96:97]
	s_waitcnt vmcnt(0)
	v_lshlrev_b32_e32 v74, 16, v66
	v_and_b32_e32 v75, 0xffff0000, v66
	v_lshlrev_b32_e32 v66, 16, v67
	v_and_b32_e32 v67, 0xffff0000, v67
	v_lshlrev_b32_e32 v76, 16, v68
	v_and_b32_e32 v77, 0xffff0000, v68
	v_lshlrev_b32_e32 v68, 16, v69
	v_and_b32_e32 v69, 0xffff0000, v69
	v_pk_add_f32 v[62:63], v[62:63], v[66:67]
	v_pk_add_f32 v[60:61], v[60:61], v[74:75]
	v_pk_add_f32 v[66:67], v[58:59], v[68:69]
	v_pk_add_f32 v[68:69], v[56:57], v[76:77]
	v_cvt_pk_bf16_f32 v56, v60, v61
	v_cvt_pk_bf16_f32 v57, v62, v63
	v_cvt_pk_bf16_f32 v58, v68, v69
	v_cvt_pk_bf16_f32 v59, v66, v67
	buffer_store_dwordx4 v[56:59], v78, s[12:15], 0 offen
	global_load_dwordx4 v[56:59], v[72:73], off
	v_mul_f32_e32 v61, v61, v61
	v_mul_f32_e32 v63, v63, v63
	v_mul_f32_e32 v69, v69, v69
	v_fmac_f32_e32 v61, v60, v60
	v_fmac_f32_e32 v63, v62, v62
	v_mul_f32_e32 v67, v67, v67
	v_fmac_f32_e32 v69, v68, v68
	v_add_f32_e32 v60, v61, v63
	v_fmac_f32_e32 v67, v66, v66
	v_add_f32_e32 v60, v69, v60
	v_add_f32_e32 v66, v67, v60
	s_waitcnt vmcnt(0)
	v_lshlrev_b32_e32 v60, 16, v56
	v_and_b32_e32 v61, 0xffff0000, v56
	v_lshlrev_b32_e32 v56, 16, v57
	v_and_b32_e32 v57, 0xffff0000, v57
	v_lshlrev_b32_e32 v62, 16, v58
	v_and_b32_e32 v63, 0xffff0000, v58
	v_lshlrev_b32_e32 v58, 16, v59
	v_and_b32_e32 v59, 0xffff0000, v59
	v_pk_add_f32 v[54:55], v[54:55], v[56:57]
	v_pk_add_f32 v[52:53], v[52:53], v[60:61]
	v_pk_add_f32 v[56:57], v[50:51], v[58:59]
	v_pk_add_f32 v[58:59], v[48:49], v[62:63]
	v_mul_f32_e32 v48, v53, v53
	v_mul_f32_e32 v49, v55, v55
	v_mul_f32_e32 v50, v59, v59
	v_fmac_f32_e32 v48, v52, v52
	v_fmac_f32_e32 v49, v54, v54
	v_mul_f32_e32 v51, v57, v57
	v_fmac_f32_e32 v50, v58, v58
	v_add_f32_e32 v48, v48, v49
	v_add_f32_e32 v48, v50, v48
	v_fmac_f32_e32 v51, v56, v56
	v_add_f32_e32 v48, v51, v48
	v_add_f32_e32 v48, v66, v48
	ds_bpermute_b32 v49, v120, v48
	v_cvt_pk_bf16_f32 v50, v52, v53
	v_cvt_pk_bf16_f32 v51, v54, v55
	v_cvt_pk_bf16_f32 v52, v58, v59
	v_cvt_pk_bf16_f32 v53, v56, v57
	s_waitcnt lgkmcnt(0)
	v_add_f32_e32 v48, v48, v49
	ds_bpermute_b32 v49, v114, v48
	v_lshlrev_b32_e32 v54, 1, v70
	buffer_store_dwordx4 v[50:53], v54, s[12:15], 0 offen
	s_and_saveexec_b64 s[40:41], s[6:7]
	s_cbranch_execz .Lpp9_811
	v_lshl_add_u64 v[50:51], v[64:65], 2, s[10:11]
	s_waitcnt lgkmcnt(0)
	v_add_f32_e32 v48, v48, v49
	global_atomic_add_f32 v[50:51], v48, off
.Lpp9_811:
	s_or_b64 exec, exec, s[40:41]
	v_add_u32_e32 v48, 0x90, v148
	s_waitcnt lgkmcnt(0)
	v_ashrrev_i32_e32 v49, 31, v48
	v_lshlrev_b64 v[50:51], 10, v[48:49]
	v_lshl_add_u64 v[54:55], v[50:51], 0, v[146:147]
	v_lshl_add_u64 v[50:51], v[54:55], 1, s[96:97]
	global_load_dwordx4 v[50:53], v[50:51], off
	v_lshlrev_b32_e32 v62, 1, v54
	v_or_b32_e32 v54, 0x80, v54
	v_lshl_add_u64 v[56:57], v[54:55], 1, s[96:97]
	s_waitcnt vmcnt(0)
	v_lshlrev_b32_e32 v58, 16, v50
	v_and_b32_e32 v59, 0xffff0000, v50
	v_lshlrev_b32_e32 v50, 16, v51
	v_and_b32_e32 v51, 0xffff0000, v51
	v_lshlrev_b32_e32 v60, 16, v52
	v_and_b32_e32 v61, 0xffff0000, v52
	v_lshlrev_b32_e32 v52, 16, v53
	v_and_b32_e32 v53, 0xffff0000, v53
	v_pk_add_f32 v[46:47], v[46:47], v[50:51]
	v_pk_add_f32 v[44:45], v[44:45], v[58:59]
	v_pk_add_f32 v[50:51], v[42:43], v[52:53]
	v_pk_add_f32 v[52:53], v[40:41], v[60:61]
	v_cvt_pk_bf16_f32 v40, v44, v45
	v_cvt_pk_bf16_f32 v41, v46, v47
	v_cvt_pk_bf16_f32 v42, v52, v53
	v_cvt_pk_bf16_f32 v43, v50, v51
	buffer_store_dwordx4 v[40:43], v62, s[12:15], 0 offen
	global_load_dwordx4 v[40:43], v[56:57], off
	v_mul_f32_e32 v45, v45, v45
	v_mul_f32_e32 v47, v47, v47
	v_mul_f32_e32 v53, v53, v53
	v_fmac_f32_e32 v45, v44, v44
	v_fmac_f32_e32 v47, v46, v46
	v_mul_f32_e32 v51, v51, v51
	v_fmac_f32_e32 v53, v52, v52
	v_add_f32_e32 v44, v45, v47
	v_fmac_f32_e32 v51, v50, v50
	v_add_f32_e32 v44, v53, v44
	v_add_f32_e32 v50, v51, v44
	s_waitcnt vmcnt(0)
	v_lshlrev_b32_e32 v44, 16, v40
	v_and_b32_e32 v45, 0xffff0000, v40
	v_lshlrev_b32_e32 v40, 16, v41
	v_and_b32_e32 v41, 0xffff0000, v41
	v_lshlrev_b32_e32 v46, 16, v42
	v_and_b32_e32 v47, 0xffff0000, v42
	v_lshlrev_b32_e32 v42, 16, v43
	v_and_b32_e32 v43, 0xffff0000, v43
	v_pk_add_f32 v[38:39], v[38:39], v[40:41]
	v_pk_add_f32 v[36:37], v[36:37], v[44:45]
	v_pk_add_f32 v[40:41], v[34:35], v[42:43]
	v_pk_add_f32 v[42:43], v[32:33], v[46:47]
	v_mul_f32_e32 v32, v37, v37
	v_mul_f32_e32 v33, v39, v39
	v_mul_f32_e32 v34, v43, v43
	v_fmac_f32_e32 v32, v36, v36
	v_fmac_f32_e32 v33, v38, v38
	v_mul_f32_e32 v35, v41, v41
	v_fmac_f32_e32 v34, v42, v42
	v_add_f32_e32 v32, v32, v33
	v_add_f32_e32 v32, v34, v32
	v_fmac_f32_e32 v35, v40, v40
	v_add_f32_e32 v32, v35, v32
	v_add_f32_e32 v32, v50, v32
	ds_bpermute_b32 v33, v120, v32
	v_cvt_pk_bf16_f32 v34, v36, v37
	v_cvt_pk_bf16_f32 v35, v38, v39
	v_cvt_pk_bf16_f32 v36, v42, v43
	v_cvt_pk_bf16_f32 v37, v40, v41
	s_waitcnt lgkmcnt(0)
	v_add_f32_e32 v32, v32, v33
	ds_bpermute_b32 v33, v114, v32
	v_lshlrev_b32_e32 v38, 1, v54
	buffer_store_dwordx4 v[34:37], v38, s[12:15], 0 offen
	s_and_saveexec_b64 s[40:41], s[6:7]
	s_cbranch_execz .Lpp9_813
	v_lshl_add_u64 v[34:35], v[48:49], 2, s[10:11]
	s_waitcnt lgkmcnt(0)
	v_add_f32_e32 v32, v32, v33
	global_atomic_add_f32 v[34:35], v32, off
; __device__ __forceinline__ unsigned cvt_pk_bf16(float lo, float hi) { f32x2_t v = {lo, hi}; bf16x2_t b = __builtin_convertvector(v, bf16x2_t); return __builtin_bit_cast(unsigned, b); }
;     __device__ __forceinline__ void operator()(const f32x4 (&acc)[2][2][4][2], const Unit& u, int wr, int wc, int fr, int fq) const {
;     ...
;             for (int m = 0; m < 4; ++m) { const int row = u.pm * BM + ai * HALF + wr * 64 + m * 16 + fr; const size_t off = (size_t)row * ldc + col0; float ss = 0.f;
; #pragma unroll
;                 for (int bj = 0; bj < 2; ++bj) { const size_t o2 = off + bj * HALF; f32x4 b0, b1;
;                     if (MODE == 0) { b0 = *(const f32x4*)(basef + o2); b1 = *(const f32x4*)(basef + o2 + 4); }
;                     else { const u32x4 w = *(const u32x4*)(xb + o2);
;                         b0 = (f32x4){__uint_as_float(w.x << 16), __uint_as_float(w.x & 0xffff0000u), __uint_as_float(w.y << 16), __uint_as_float(w.y & 0xffff0000u)};
;                         b1 = (f32x4){__uint_as_float(w.z << 16), __uint_as_float(w.z & 0xffff0000u), __uint_as_float(w.w << 16), __uint_as_float(w.w & 0xffff0000u)}; }
;                     const f32x4 v0 = b0 + acc[ai][bj][m][0], v1 = b1 + acc[ai][bj][m][1];
;                     if (MODE == 2) { *(f32x4*)(outf + o2) = v0; *(f32x4*)(outf + o2 + 4) = v1; }
;                     else { ss += (v0[0] * v0[0] + v0[1] * v0[1]) + (v0[2] * v0[2] + v0[3] * v0[3]) + (v1[0] * v1[0] + v1[1] * v1[1]) + (v1[2] * v1[2] + v1[3] * v1[3]);
;                         u32x4 w; w.x = cvt_pk_bf16(v0[0], v0[1]); w.y = cvt_pk_bf16(v0[2], v0[3]); w.z = cvt_pk_bf16(v1[0], v1[1]); w.w = cvt_pk_bf16(v1[2], v1[3]);
;                         __builtin_amdgcn_raw_buffer_store_b128(w, rsrc, (unsigned)(o2 * 2), 0, 16); } }
;                 if (MODE != 2) { ss += __shfl_xor(ss, 16); ss += __shfl_xor(ss, 32); if (fq == 0) atomicAdd(rowsq + row, ss); } }
.Lpp9_813:
	s_or_b64 exec, exec, s[40:41]
	v_add_u32_e32 v32, 0xa0, v148
	s_waitcnt lgkmcnt(0)
	v_ashrrev_i32_e32 v33, 31, v32
	v_lshlrev_b64 v[34:35], 10, v[32:33]
	v_lshl_add_u64 v[38:39], v[34:35], 0, v[146:147]
	v_lshl_add_u64 v[34:35], v[38:39], 1, s[96:97]
	global_load_dwordx4 v[34:37], v[34:35], off
	v_lshlrev_b32_e32 v46, 1, v38
	v_or_b32_e32 v38, 0x80, v38
	v_lshl_add_u64 v[40:41], v[38:39], 1, s[96:97]
	s_waitcnt vmcnt(0)
	v_lshlrev_b32_e32 v42, 16, v34
	v_and_b32_e32 v43, 0xffff0000, v34
	v_lshlrev_b32_e32 v34, 16, v35
	v_and_b32_e32 v35, 0xffff0000, v35
	v_lshlrev_b32_e32 v44, 16, v36
	v_and_b32_e32 v45, 0xffff0000, v36
	v_lshlrev_b32_e32 v36, 16, v37
	v_and_b32_e32 v37, 0xffff0000, v37
	v_pk_add_f32 v[30:31], v[30:31], v[34:35]
	v_pk_add_f32 v[28:29], v[28:29], v[42:43]
	v_pk_add_f32 v[34:35], v[26:27], v[36:37]
	v_pk_add_f32 v[36:37], v[24:25], v[44:45]
	v_cvt_pk_bf16_f32 v24, v28, v29
	v_cvt_pk_bf16_f32 v25, v30, v31
	v_cvt_pk_bf16_f32 v26, v36, v37
	v_cvt_pk_bf16_f32 v27, v34, v35
	buffer_store_dwordx4 v[24:27], v46, s[12:15], 0 offen
	global_load_dwordx4 v[24:27], v[40:41], off
	v_mul_f32_e32 v29, v29, v29
	v_mul_f32_e32 v31, v31, v31
	v_mul_f32_e32 v37, v37, v37
	v_fmac_f32_e32 v29, v28, v28
	v_fmac_f32_e32 v31, v30, v30
	v_mul_f32_e32 v35, v35, v35
	v_fmac_f32_e32 v37, v36, v36
	v_add_f32_e32 v28, v29, v31
	v_fmac_f32_e32 v35, v34, v34
	v_add_f32_e32 v28, v37, v28
	v_add_f32_e32 v34, v35, v28
	s_waitcnt vmcnt(0)
	v_lshlrev_b32_e32 v28, 16, v24
	v_and_b32_e32 v29, 0xffff0000, v24
	v_lshlrev_b32_e32 v24, 16, v25
	v_and_b32_e32 v25, 0xffff0000, v25
	v_lshlrev_b32_e32 v30, 16, v26
	v_and_b32_e32 v31, 0xffff0000, v26
	v_lshlrev_b32_e32 v26, 16, v27
	v_and_b32_e32 v27, 0xffff0000, v27
	v_pk_add_f32 v[22:23], v[22:23], v[24:25]
	v_pk_add_f32 v[20:21], v[20:21], v[28:29]
	v_pk_add_f32 v[24:25], v[18:19], v[26:27]
	v_pk_add_f32 v[26:27], v[16:17], v[30:31]
	v_mul_f32_e32 v16, v21, v21
	v_mul_f32_e32 v17, v23, v23
	v_mul_f32_e32 v18, v27, v27
	v_fmac_f32_e32 v16, v20, v20
	v_fmac_f32_e32 v17, v22, v22
	v_mul_f32_e32 v19, v25, v25
	v_fmac_f32_e32 v18, v26, v26
	v_add_f32_e32 v16, v16, v17
	v_add_f32_e32 v16, v18, v16
	v_fmac_f32_e32 v19, v24, v24
	v_add_f32_e32 v16, v19, v16
	v_add_f32_e32 v16, v34, v16
	ds_bpermute_b32 v17, v120, v16
	v_cvt_pk_bf16_f32 v18, v20, v21
	v_cvt_pk_bf16_f32 v19, v22, v23
	v_cvt_pk_bf16_f32 v20, v26, v27
	v_cvt_pk_bf16_f32 v21, v24, v25
	s_waitcnt lgkmcnt(0)
	v_add_f32_e32 v16, v16, v17
	ds_bpermute_b32 v17, v114, v16
	v_lshlrev_b32_e32 v22, 1, v38
	buffer_store_dwordx4 v[18:21], v22, s[12:15], 0 offen
	s_and_saveexec_b64 s[40:41], s[6:7]
	s_cbranch_execz .Lpp9_815
	v_lshl_add_u64 v[18:19], v[32:33], 2, s[10:11]
	s_waitcnt lgkmcnt(0)
	v_add_f32_e32 v16, v16, v17
	global_atomic_add_f32 v[18:19], v16, off
.Lpp9_815:
	s_or_b64 exec, exec, s[40:41]
	v_add_u32_e32 v16, 0xb0, v148
	s_waitcnt lgkmcnt(0)
	v_ashrrev_i32_e32 v17, 31, v16
	v_lshlrev_b64 v[18:19], 10, v[16:17]
	v_lshl_add_u64 v[22:23], v[18:19], 0, v[146:147]
	v_lshl_add_u64 v[18:19], v[22:23], 1, s[96:97]
	global_load_dwordx4 v[18:21], v[18:19], off
	v_lshlrev_b32_e32 v30, 1, v22
	v_or_b32_e32 v22, 0x80, v22
	v_lshl_add_u64 v[24:25], v[22:23], 1, s[96:97]
	s_waitcnt vmcnt(0)
	v_lshlrev_b32_e32 v26, 16, v18
	v_and_b32_e32 v27, 0xffff0000, v18
	v_lshlrev_b32_e32 v18, 16, v19
	v_and_b32_e32 v19, 0xffff0000, v19
	v_lshlrev_b32_e32 v28, 16, v20
	v_and_b32_e32 v29, 0xffff0000, v20
	v_lshlrev_b32_e32 v20, 16, v21
	v_and_b32_e32 v21, 0xffff0000, v21
	v_pk_add_f32 v[14:15], v[14:15], v[18:19]
	v_pk_add_f32 v[12:13], v[12:13], v[26:27]
	v_pk_add_f32 v[18:19], v[10:11], v[20:21]
	v_pk_add_f32 v[20:21], v[8:9], v[28:29]
	v_cvt_pk_bf16_f32 v8, v12, v13
	v_cvt_pk_bf16_f32 v9, v14, v15
	v_cvt_pk_bf16_f32 v10, v20, v21
	v_cvt_pk_bf16_f32 v11, v18, v19
	buffer_store_dwordx4 v[8:11], v30, s[12:15], 0 offen
	global_load_dwordx4 v[8:11], v[24:25], off
	v_mul_f32_e32 v13, v13, v13
	v_mul_f32_e32 v15, v15, v15
	v_mul_f32_e32 v21, v21, v21
	v_fmac_f32_e32 v13, v12, v12
	v_fmac_f32_e32 v15, v14, v14
	v_mul_f32_e32 v19, v19, v19
	v_fmac_f32_e32 v21, v20, v20
	v_add_f32_e32 v12, v13, v15
	v_fmac_f32_e32 v19, v18, v18
	v_add_f32_e32 v12, v21, v12
	v_add_f32_e32 v18, v19, v12
	s_waitcnt vmcnt(0)
	v_lshlrev_b32_e32 v12, 16, v8
	v_and_b32_e32 v13, 0xffff0000, v8
	v_lshlrev_b32_e32 v8, 16, v9
	v_and_b32_e32 v9, 0xffff0000, v9
	v_lshlrev_b32_e32 v14, 16, v10
	v_and_b32_e32 v15, 0xffff0000, v10
	v_lshlrev_b32_e32 v10, 16, v11
	v_and_b32_e32 v11, 0xffff0000, v11
	v_pk_add_f32 v[6:7], v[6:7], v[8:9]
	v_pk_add_f32 v[4:5], v[4:5], v[12:13]
	v_pk_add_f32 v[8:9], v[2:3], v[10:11]
	v_pk_add_f32 v[10:11], v[0:1], v[14:15]
	v_mul_f32_e32 v0, v5, v5
	v_mul_f32_e32 v1, v7, v7
	v_mul_f32_e32 v2, v11, v11
	v_fmac_f32_e32 v0, v4, v4
	v_fmac_f32_e32 v1, v6, v6
	v_mul_f32_e32 v3, v9, v9
	v_fmac_f32_e32 v2, v10, v10
	v_add_f32_e32 v0, v0, v1
	v_add_f32_e32 v0, v2, v0
	v_fmac_f32_e32 v3, v8, v8
	v_add_f32_e32 v0, v3, v0
	v_add_f32_e32 v0, v18, v0
	ds_bpermute_b32 v1, v120, v0
	v_cvt_pk_bf16_f32 v2, v4, v5
	v_cvt_pk_bf16_f32 v3, v6, v7
	v_cvt_pk_bf16_f32 v4, v10, v11
	v_cvt_pk_bf16_f32 v5, v8, v9
	s_waitcnt lgkmcnt(0)
	v_add_f32_e32 v0, v0, v1
	ds_bpermute_b32 v1, v114, v0
	v_lshlrev_b32_e32 v6, 1, v22
	buffer_store_dwordx4 v[2:5], v6, s[12:15], 0 offen
	s_and_saveexec_b64 s[40:41], s[6:7]
	s_cbranch_execz .Lpp9_817
	v_lshl_add_u64 v[2:3], v[16:17], 2, s[10:11]
	s_waitcnt lgkmcnt(0)
	v_add_f32_e32 v0, v0, v1
	global_atomic_add_f32 v[2:3], v0, off

; #define PG8_BAR __builtin_amdgcn_s_barrier()
; template <class Epi, class Sched, bool ALIGN_EPI = false, bool SP2 = false>
; __device__ __forceinline__ void gemm_phase(PG8_LAS unsigned char* lds, const Gemm g, const Sched& S, const Epi& E) {
;     ...
;         if constexpr (ALIGN_EPI) { if (wr == 0) PG8_BAR; }
;         if constexpr (!Epi::AFTER_DRAIN) { E(acc, cur, wr, wc, fr, fq); S.done(cur); }
;         if (!has_next) break;
; #pragma unroll
;         for (int a = 0; a < 2; ++a)
; #pragma unroll
;             for (int b = 0; b < 2; ++b)
; #pragma unroll
;                 for (int m = 0; m < 4; ++m)
; #pragma unroll
;                     for (int n = 0; n < 2; ++n) acc[a][b][m][n] = (f32x4){0.f, 0.f, 0.f, 0.f};
;         cur = nxt; cA = nA; cB = nB; ++ui;
;         if constexpr (ALIGN_EPI) { if (wr == 1) PG8_BAR; }
;     }
.Lpp9_done:
	s_andn2_b64 vcc, exec, s[8:9]
	s_mov_b64 s[8:9], -1
	s_cbranch_vccnz .LBB0_790
	s_andn2_b64 vcc, exec, s[24:25]
	s_cbranch_vccnz .LBB0_789
	s_barrier
	s_branch .LBB0_789

; __device__ __forceinline__ unsigned cvt_pk_bf16(float lo, float hi) { f32x2_t v = {lo, hi}; bf16x2_t b = __builtin_convertvector(v, bf16x2_t); return __builtin_bit_cast(unsigned, b); }
;     __device__ __forceinline__ void operator()(const f32x4 (&acc)[2][2][4][2], const Unit& u, int wr, int wc, int fr, int fq) const {
;     ...
;             for (int m = 0; m < 4; ++m) { const int row = row0 + ai * HALF + m * 16;
;                 const float rs = rowsq ? rsqrtf(rowsq[row] * (1.0f / 1024.0f) + 1e-6f) : 1.0f;
; #pragma unroll
;                 for (int bj = 0; bj < 2; ++bj) { f32x4 v0 = acc[ai][bj][m][0] * rs, v1 = acc[ai][bj][m][1] * rs;
;                     if (ACT == 1) {
; #pragma unroll
;                         for (int e = 0; e < 4; ++e) { const float a0 = fmaxf(v0[e], 0.f), a1 = fmaxf(v1[e], 0.f); v0[e] = a0 * a0; v1[e] = a1 * a1; } }
;                     u32x4 w; w.x = cvt_pk_bf16(v0[0], v0[1]); w.y = cvt_pk_bf16(v0[2], v0[3]); w.z = cvt_pk_bf16(v1[0], v1[1]); w.w = cvt_pk_bf16(v1[2], v1[3]);
;                     __builtin_amdgcn_raw_buffer_store_b128(w, rsrc, (unsigned)(((size_t)row * ldc + col0 + bj * HALF) * 2), 0,   16); } }
.LBB0_908:
	v_readlane_b32 vcc_lo, v255, 59
	s_mov_b32 vcc_hi, 0
	s_nop 1
	s_mov_b64 vcc, vcc
	s_nop 1
	s_cbranch_vccnz .Lpp11_plain
	v_lshl_add_u32 v148, s8, 8, v129
	v_ashrrev_i32_e32 v149, 31, v148
	v_lshl_add_u64 v[146:147], v[148:149], 2, s[10:11]
	global_load_dword v156, v[146:147], off
	v_lshl_or_b32 v164, s9, 9, v155
	v_lshl_add_u32 v149, v148, 13, v164
	s_waitcnt vmcnt(0)
	v_fmamk_f32 v156, v156, 0x3a800000, v154
	v_mul_f32_e32 v157, 0x4b800000, v156
	v_cmp_gt_f32_e32 vcc, s57, v156
	s_nop 1
	v_cndmask_b32_e32 v156, v156, v157, vcc
	v_rsq_f32_e32 v160, v156
	v_or_b32_e32 v156, 16, v148
	v_ashrrev_i32_e32 v157, 31, v156
	v_lshl_add_u64 v[158:159], v[156:157], 2, s[10:11]
	v_mul_f32_e32 v157, 0x45800000, v160
	v_cndmask_b32_e32 v160, v160, v157, vcc
	v_pk_mul_f32 v[126:127], v[126:127], v[160:161] op_sel_hi:[1,0]
	v_pk_mul_f32 v[124:125], v[124:125], v[160:161] op_sel_hi:[1,0]
	v_pk_mul_f32 v[122:123], v[122:123], v[160:161] op_sel_hi:[1,0]
	v_pk_mul_f32 v[120:121], v[120:121], v[160:161] op_sel_hi:[1,0]
	v_pk_mul_f32 v[118:119], v[118:119], v[160:161] op_sel_hi:[1,0]
	v_pk_mul_f32 v[116:117], v[116:117], v[160:161] op_sel_hi:[1,0]
	v_pk_mul_f32 v[114:115], v[114:115], v[160:161] op_sel_hi:[1,0]
	v_pk_mul_f32 v[112:113], v[112:113], v[160:161] op_sel_hi:[1,0]
	v_max_f32_e32 v124, 0, v124
	v_max_f32_e32 v120, 0, v120
	v_max_f32_e32 v125, 0, v125
	v_max_f32_e32 v121, 0, v121
	v_max_f32_e32 v126, 0, v126
	v_max_f32_e32 v122, 0, v122
	v_max_f32_e32 v127, 0, v127
	v_max_f32_e32 v123, 0, v123
	v_max_f32_e32 v116, 0, v116
	v_max_f32_e32 v112, 0, v112
	v_max_f32_e32 v117, 0, v117
	v_max_f32_e32 v113, 0, v113
	v_max_f32_e32 v118, 0, v118
	v_max_f32_e32 v114, 0, v114
	v_max_f32_e32 v119, 0, v119
	v_max_f32_e32 v115, 0, v115
	v_pk_mul_f32 v[124:125], v[124:125], v[124:125]
	v_pk_mul_f32 v[120:121], v[120:121], v[120:121]
	v_pk_mul_f32 v[126:127], v[126:127], v[126:127]
	v_pk_mul_f32 v[122:123], v[122:123], v[122:123]
	v_pk_mul_f32 v[116:117], v[116:117], v[116:117]
	v_pk_mul_f32 v[160:161], v[112:113], v[112:113]
	v_pk_mul_f32 v[118:119], v[118:119], v[118:119]
	v_pk_mul_f32 v[162:163], v[114:115], v[114:115]
	v_cvt_pk_bf16_f32 v112, v124, v125
	v_cvt_pk_bf16_f32 v113, v126, v127
	v_cvt_pk_bf16_f32 v114, v120, v121
	v_cvt_pk_bf16_f32 v115, v122, v123
	v_cvt_pk_bf16_f32 v116, v116, v117
	v_cvt_pk_bf16_f32 v117, v118, v119
	v_cvt_pk_bf16_f32 v118, v160, v161
	v_cvt_pk_bf16_f32 v119, v162, v163
	buffer_store_dwordx4 v[112:115], v149, s[12:15], 0 offen sc1
	buffer_store_dwordx4 v[116:119], v149, s[12:15], 0 offen offset:256 sc1
	global_load_dword v113, v[158:159], off
	v_or_b32_e32 v112, 32, v148
	v_lshl_add_u32 v120, v156, 13, v164
	s_waitcnt vmcnt(0)
	v_fmamk_f32 v113, v113, 0x3a800000, v154
	v_mul_f32_e32 v114, 0x4b800000, v113
	v_cmp_gt_f32_e32 vcc, s57, v113
	s_nop 1
	v_cndmask_b32_e32 v113, v113, v114, vcc
	v_rsq_f32_e32 v116, v113
	v_ashrrev_i32_e32 v113, 31, v112
	v_lshl_add_u64 v[114:115], v[112:113], 2, s[10:11]
	v_mul_f32_e32 v113, 0x45800000, v116
	v_cndmask_b32_e32 v116, v116, v113, vcc
	v_pk_mul_f32 v[110:111], v[110:111], v[116:117] op_sel_hi:[1,0]
	v_pk_mul_f32 v[108:109], v[108:109], v[116:117] op_sel_hi:[1,0]
	v_pk_mul_f32 v[106:107], v[106:107], v[116:117] op_sel_hi:[1,0]
	v_pk_mul_f32 v[104:105], v[104:105], v[116:117] op_sel_hi:[1,0]
	v_pk_mul_f32 v[102:103], v[102:103], v[116:117] op_sel_hi:[1,0]
	v_pk_mul_f32 v[100:101], v[100:101], v[116:117] op_sel_hi:[1,0]
	v_pk_mul_f32 v[98:99], v[98:99], v[116:117] op_sel_hi:[1,0]
	v_pk_mul_f32 v[96:97], v[96:97], v[116:117] op_sel_hi:[1,0]
	v_max_f32_e32 v108, 0, v108
	v_max_f32_e32 v104, 0, v104
	v_max_f32_e32 v109, 0, v109
	v_max_f32_e32 v105, 0, v105
	v_max_f32_e32 v110, 0, v110
	v_max_f32_e32 v106, 0, v106
	v_max_f32_e32 v111, 0, v111
	v_max_f32_e32 v107, 0, v107
	v_max_f32_e32 v100, 0, v100
	v_max_f32_e32 v96, 0, v96
	v_max_f32_e32 v101, 0, v101
	v_max_f32_e32 v97, 0, v97
	v_max_f32_e32 v102, 0, v102
	v_max_f32_e32 v98, 0, v98
	v_max_f32_e32 v103, 0, v103
	v_max_f32_e32 v99, 0, v99
	v_pk_mul_f32 v[108:109], v[108:109], v[108:109]
	v_pk_mul_f32 v[104:105], v[104:105], v[104:105]
	v_pk_mul_f32 v[110:111], v[110:111], v[110:111]
	v_pk_mul_f32 v[106:107], v[106:107], v[106:107]
	v_pk_mul_f32 v[100:101], v[100:101], v[100:101]
	v_pk_mul_f32 v[116:117], v[96:97], v[96:97]
	v_pk_mul_f32 v[102:103], v[102:103], v[102:103]
	v_pk_mul_f32 v[118:119], v[98:99], v[98:99]
	v_cvt_pk_bf16_f32 v96, v108, v109
	v_cvt_pk_bf16_f32 v97, v110, v111
	v_cvt_pk_bf16_f32 v98, v104, v105
	v_cvt_pk_bf16_f32 v99, v106, v107
	v_cvt_pk_bf16_f32 v100, v100, v101
	v_cvt_pk_bf16_f32 v101, v102, v103
	v_cvt_pk_bf16_f32 v102, v116, v117
	v_cvt_pk_bf16_f32 v103, v118, v119
	buffer_store_dwordx4 v[96:99], v120, s[12:15], 0 offen sc1
	buffer_store_dwordx4 v[100:103], v120, s[12:15], 0 offen offset:256 sc1
	global_load_dword v97, v[114:115], off
	v_or_b32_e32 v96, 48, v148
	v_lshl_add_u32 v104, v112, 13, v164
	s_waitcnt vmcnt(0)
; __device__ __forceinline__ unsigned cvt_pk_bf16(float lo, float hi) { f32x2_t v = {lo, hi}; bf16x2_t b = __builtin_convertvector(v, bf16x2_t); return __builtin_bit_cast(unsigned, b); }
;     __device__ __forceinline__ void operator()(const f32x4 (&acc)[2][2][4][2], const Unit& u, int wr, int wc, int fr, int fq) const {
;     ...
;             for (int m = 0; m < 4; ++m) { const int row = row0 + ai * HALF + m * 16;
;                 const float rs = rowsq ? rsqrtf(rowsq[row] * (1.0f / 1024.0f) + 1e-6f) : 1.0f;
; #pragma unroll
;                 for (int bj = 0; bj < 2; ++bj) { f32x4 v0 = acc[ai][bj][m][0] * rs, v1 = acc[ai][bj][m][1] * rs;
;                     if (ACT == 1) {
; #pragma unroll
;                         for (int e = 0; e < 4; ++e) { const float a0 = fmaxf(v0[e], 0.f), a1 = fmaxf(v1[e], 0.f); v0[e] = a0 * a0; v1[e] = a1 * a1; } }
;                     u32x4 w; w.x = cvt_pk_bf16(v0[0], v0[1]); w.y = cvt_pk_bf16(v0[2], v0[3]); w.z = cvt_pk_bf16(v1[0], v1[1]); w.w = cvt_pk_bf16(v1[2], v1[3]);
;                     __builtin_amdgcn_raw_buffer_store_b128(w, rsrc, (unsigned)(((size_t)row * ldc + col0 + bj * HALF) * 2), 0,   16); } }
	v_fmamk_f32 v97, v97, 0x3a800000, v154
	v_mul_f32_e32 v98, 0x4b800000, v97
	v_cmp_gt_f32_e32 vcc, s57, v97
	s_nop 1
	v_cndmask_b32_e32 v97, v97, v98, vcc
	v_rsq_f32_e32 v100, v97
	v_ashrrev_i32_e32 v97, 31, v96
	v_lshl_add_u64 v[98:99], v[96:97], 2, s[10:11]
	v_mul_f32_e32 v97, 0x45800000, v100
	v_cndmask_b32_e32 v100, v100, v97, vcc
	v_pk_mul_f32 v[94:95], v[94:95], v[100:101] op_sel_hi:[1,0]
	v_pk_mul_f32 v[92:93], v[92:93], v[100:101] op_sel_hi:[1,0]
	v_pk_mul_f32 v[90:91], v[90:91], v[100:101] op_sel_hi:[1,0]
	v_pk_mul_f32 v[88:89], v[88:89], v[100:101] op_sel_hi:[1,0]
	v_pk_mul_f32 v[86:87], v[86:87], v[100:101] op_sel_hi:[1,0]
	v_pk_mul_f32 v[84:85], v[84:85], v[100:101] op_sel_hi:[1,0]
	v_pk_mul_f32 v[82:83], v[82:83], v[100:101] op_sel_hi:[1,0]
	v_pk_mul_f32 v[80:81], v[80:81], v[100:101] op_sel_hi:[1,0]
	v_max_f32_e32 v92, 0, v92
	v_max_f32_e32 v88, 0, v88
	v_max_f32_e32 v93, 0, v93
	v_max_f32_e32 v89, 0, v89
	v_max_f32_e32 v94, 0, v94
	v_max_f32_e32 v90, 0, v90
	v_max_f32_e32 v95, 0, v95
	v_max_f32_e32 v91, 0, v91
	v_max_f32_e32 v84, 0, v84
	v_max_f32_e32 v80, 0, v80
	v_max_f32_e32 v85, 0, v85
	v_max_f32_e32 v81, 0, v81
	v_max_f32_e32 v86, 0, v86
	v_max_f32_e32 v82, 0, v82
	v_max_f32_e32 v87, 0, v87
	v_max_f32_e32 v83, 0, v83
	v_pk_mul_f32 v[92:93], v[92:93], v[92:93]
	v_pk_mul_f32 v[88:89], v[88:89], v[88:89]
	v_pk_mul_f32 v[94:95], v[94:95], v[94:95]
	v_pk_mul_f32 v[90:91], v[90:91], v[90:91]
	v_pk_mul_f32 v[84:85], v[84:85], v[84:85]
	v_pk_mul_f32 v[100:101], v[80:81], v[80:81]
	v_pk_mul_f32 v[86:87], v[86:87], v[86:87]
	v_pk_mul_f32 v[102:103], v[82:83], v[82:83]
	v_cvt_pk_bf16_f32 v80, v92, v93
	v_cvt_pk_bf16_f32 v81, v94, v95
	v_cvt_pk_bf16_f32 v82, v88, v89
	v_cvt_pk_bf16_f32 v83, v90, v91
	v_cvt_pk_bf16_f32 v84, v84, v85
	v_cvt_pk_bf16_f32 v85, v86, v87
	v_cvt_pk_bf16_f32 v86, v100, v101
	v_cvt_pk_bf16_f32 v87, v102, v103
	buffer_store_dwordx4 v[80:83], v104, s[12:15], 0 offen sc1
	buffer_store_dwordx4 v[84:87], v104, s[12:15], 0 offen offset:256 sc1
	global_load_dword v80, v[98:99], off
	s_waitcnt vmcnt(0)
	v_fmamk_f32 v80, v80, 0x3a800000, v154
	v_mul_f32_e32 v81, 0x4b800000, v80
	v_cmp_gt_f32_e32 vcc, s57, v80
	v_lshl_add_u32 v84, v96, 13, v164
	s_nop 0
	v_cndmask_b32_e32 v80, v80, v81, vcc
	v_rsq_f32_e32 v80, v80
	s_nop 0
	v_mul_f32_e32 v81, 0x45800000, v80
	v_cndmask_b32_e32 v80, v80, v81, vcc
	v_pk_mul_f32 v[78:79], v[78:79], v[80:81] op_sel_hi:[1,0]
	v_pk_mul_f32 v[76:77], v[76:77], v[80:81] op_sel_hi:[1,0]
	v_pk_mul_f32 v[74:75], v[74:75], v[80:81] op_sel_hi:[1,0]
	v_pk_mul_f32 v[72:73], v[72:73], v[80:81] op_sel_hi:[1,0]
	v_pk_mul_f32 v[70:71], v[70:71], v[80:81] op_sel_hi:[1,0]
	v_pk_mul_f32 v[68:69], v[68:69], v[80:81] op_sel_hi:[1,0]
	v_pk_mul_f32 v[66:67], v[66:67], v[80:81] op_sel_hi:[1,0]
	v_pk_mul_f32 v[64:65], v[64:65], v[80:81] op_sel_hi:[1,0]
	v_max_f32_e32 v76, 0, v76
	v_max_f32_e32 v72, 0, v72
	v_max_f32_e32 v77, 0, v77
	v_max_f32_e32 v73, 0, v73
	v_max_f32_e32 v78, 0, v78
	v_max_f32_e32 v74, 0, v74
	v_max_f32_e32 v79, 0, v79
	v_max_f32_e32 v75, 0, v75
	v_max_f32_e32 v68, 0, v68
	v_max_f32_e32 v64, 0, v64
	v_max_f32_e32 v69, 0, v69
	v_max_f32_e32 v65, 0, v65
	v_max_f32_e32 v70, 0, v70
	v_max_f32_e32 v66, 0, v66
	v_max_f32_e32 v71, 0, v71
	v_max_f32_e32 v67, 0, v67
	v_pk_mul_f32 v[76:77], v[76:77], v[76:77]
	v_pk_mul_f32 v[72:73], v[72:73], v[72:73]
	v_pk_mul_f32 v[78:79], v[78:79], v[78:79]
	v_pk_mul_f32 v[74:75], v[74:75], v[74:75]
	v_pk_mul_f32 v[68:69], v[68:69], v[68:69]
	v_pk_mul_f32 v[80:81], v[64:65], v[64:65]
	v_pk_mul_f32 v[70:71], v[70:71], v[70:71]
	v_pk_mul_f32 v[82:83], v[66:67], v[66:67]
	v_cvt_pk_bf16_f32 v64, v76, v77
	v_cvt_pk_bf16_f32 v65, v78, v79
	v_cvt_pk_bf16_f32 v66, v72, v73
	v_cvt_pk_bf16_f32 v67, v74, v75
	v_cvt_pk_bf16_f32 v68, v68, v69
	v_cvt_pk_bf16_f32 v69, v70, v71
	v_cvt_pk_bf16_f32 v70, v80, v81
	v_cvt_pk_bf16_f32 v71, v82, v83
	buffer_store_dwordx4 v[64:67], v84, s[12:15], 0 offen sc1
	buffer_store_dwordx4 v[68:71], v84, s[12:15], 0 offen offset:256 sc1
	global_load_dword v64, v[146:147], off offset:512
	s_waitcnt vmcnt(0)
	v_fmamk_f32 v64, v64, 0x3a800000, v154
	v_mul_f32_e32 v65, 0x4b800000, v64
	v_cmp_gt_f32_e32 vcc, s57, v64
	v_add_u32_e32 v68, 0x100000, v149
	s_nop 0
	v_cndmask_b32_e32 v64, v64, v65, vcc
	v_rsq_f32_e32 v64, v64
	s_nop 0
	v_mul_f32_e32 v65, 0x45800000, v64
	v_cndmask_b32_e32 v64, v64, v65, vcc
	v_pk_mul_f32 v[62:63], v[62:63], v[64:65] op_sel_hi:[1,0]
	v_pk_mul_f32 v[60:61], v[60:61], v[64:65] op_sel_hi:[1,0]
	v_pk_mul_f32 v[58:59], v[58:59], v[64:65] op_sel_hi:[1,0]
	v_pk_mul_f32 v[56:57], v[56:57], v[64:65] op_sel_hi:[1,0]
	v_pk_mul_f32 v[54:55], v[54:55], v[64:65] op_sel_hi:[1,0]
	v_pk_mul_f32 v[52:53], v[52:53], v[64:65] op_sel_hi:[1,0]
	v_pk_mul_f32 v[50:51], v[50:51], v[64:65] op_sel_hi:[1,0]
	v_pk_mul_f32 v[48:49], v[48:49], v[64:65] op_sel_hi:[1,0]
	v_max_f32_e32 v60, 0, v60
	v_max_f32_e32 v56, 0, v56
	v_max_f32_e32 v61, 0, v61
	v_max_f32_e32 v57, 0, v57
	v_max_f32_e32 v62, 0, v62
	v_max_f32_e32 v58, 0, v58
	v_max_f32_e32 v63, 0, v63
	v_max_f32_e32 v59, 0, v59
	v_max_f32_e32 v52, 0, v52
	v_max_f32_e32 v48, 0, v48
	v_max_f32_e32 v53, 0, v53
	v_max_f32_e32 v49, 0, v49
	v_max_f32_e32 v54, 0, v54
	v_max_f32_e32 v50, 0, v50
	v_max_f32_e32 v55, 0, v55
	v_max_f32_e32 v51, 0, v51
	v_pk_mul_f32 v[60:61], v[60:61], v[60:61]
	v_pk_mul_f32 v[56:57], v[56:57], v[56:57]
	v_pk_mul_f32 v[62:63], v[62:63], v[62:63]
	v_pk_mul_f32 v[58:59], v[58:59], v[58:59]
	v_pk_mul_f32 v[52:53], v[52:53], v[52:53]
	v_pk_mul_f32 v[64:65], v[48:49], v[48:49]
	v_pk_mul_f32 v[54:55], v[54:55], v[54:55]
	v_pk_mul_f32 v[66:67], v[50:51], v[50:51]
	v_cvt_pk_bf16_f32 v48, v60, v61
	v_cvt_pk_bf16_f32 v49, v62, v63
	v_cvt_pk_bf16_f32 v50, v56, v57
	v_cvt_pk_bf16_f32 v51, v58, v59
	v_cvt_pk_bf16_f32 v52, v52, v53
	v_cvt_pk_bf16_f32 v53, v54, v55
	v_cvt_pk_bf16_f32 v54, v64, v65
	v_cvt_pk_bf16_f32 v55, v66, v67
	buffer_store_dwordx4 v[48:51], v68, s[12:15], 0 offen sc1
	buffer_store_dwordx4 v[52:55], v68, s[12:15], 0 offen offset:256 sc1
	global_load_dword v48, v[146:147], off offset:576
	s_waitcnt vmcnt(0)
; __device__ __forceinline__ unsigned cvt_pk_bf16(float lo, float hi) { f32x2_t v = {lo, hi}; bf16x2_t b = __builtin_convertvector(v, bf16x2_t); return __builtin_bit_cast(unsigned, b); }
;     __device__ __forceinline__ void operator()(const f32x4 (&acc)[2][2][4][2], const Unit& u, int wr, int wc, int fr, int fq) const {
;     ...
;             for (int m = 0; m < 4; ++m) { const int row = row0 + ai * HALF + m * 16;
;                 const float rs = rowsq ? rsqrtf(rowsq[row] * (1.0f / 1024.0f) + 1e-6f) : 1.0f;
; #pragma unroll
;                 for (int bj = 0; bj < 2; ++bj) { f32x4 v0 = acc[ai][bj][m][0] * rs, v1 = acc[ai][bj][m][1] * rs;
;                     if (ACT == 1) {
; #pragma unroll
;                         for (int e = 0; e < 4; ++e) { const float a0 = fmaxf(v0[e], 0.f), a1 = fmaxf(v1[e], 0.f); v0[e] = a0 * a0; v1[e] = a1 * a1; } }
;                     u32x4 w; w.x = cvt_pk_bf16(v0[0], v0[1]); w.y = cvt_pk_bf16(v0[2], v0[3]); w.z = cvt_pk_bf16(v1[0], v1[1]); w.w = cvt_pk_bf16(v1[2], v1[3]);
;                     __builtin_amdgcn_raw_buffer_store_b128(w, rsrc, (unsigned)(((size_t)row * ldc + col0 + bj * HALF) * 2), 0,   16); } }
	v_fmamk_f32 v48, v48, 0x3a800000, v154
	v_mul_f32_e32 v49, 0x4b800000, v48
	v_cmp_gt_f32_e32 vcc, s57, v48
	v_add_u32_e32 v52, 0x120000, v149
	s_nop 0
	v_cndmask_b32_e32 v48, v48, v49, vcc
	v_rsq_f32_e32 v48, v48
	s_nop 0
	v_mul_f32_e32 v49, 0x45800000, v48
	v_cndmask_b32_e32 v48, v48, v49, vcc
	v_pk_mul_f32 v[46:47], v[46:47], v[48:49] op_sel_hi:[1,0]
	v_pk_mul_f32 v[44:45], v[44:45], v[48:49] op_sel_hi:[1,0]
	v_pk_mul_f32 v[42:43], v[42:43], v[48:49] op_sel_hi:[1,0]
	v_pk_mul_f32 v[40:41], v[40:41], v[48:49] op_sel_hi:[1,0]
	v_pk_mul_f32 v[38:39], v[38:39], v[48:49] op_sel_hi:[1,0]
	v_pk_mul_f32 v[36:37], v[36:37], v[48:49] op_sel_hi:[1,0]
	v_pk_mul_f32 v[34:35], v[34:35], v[48:49] op_sel_hi:[1,0]
	v_pk_mul_f32 v[32:33], v[32:33], v[48:49] op_sel_hi:[1,0]
	v_max_f32_e32 v44, 0, v44
	v_max_f32_e32 v40, 0, v40
	v_max_f32_e32 v45, 0, v45
	v_max_f32_e32 v41, 0, v41
	v_max_f32_e32 v46, 0, v46
	v_max_f32_e32 v42, 0, v42
	v_max_f32_e32 v47, 0, v47
	v_max_f32_e32 v43, 0, v43
	v_max_f32_e32 v36, 0, v36
	v_max_f32_e32 v32, 0, v32
	v_max_f32_e32 v37, 0, v37
	v_max_f32_e32 v33, 0, v33
	v_max_f32_e32 v38, 0, v38
	v_max_f32_e32 v34, 0, v34
	v_max_f32_e32 v39, 0, v39
	v_max_f32_e32 v35, 0, v35
	v_pk_mul_f32 v[44:45], v[44:45], v[44:45]
	v_pk_mul_f32 v[40:41], v[40:41], v[40:41]
	v_pk_mul_f32 v[46:47], v[46:47], v[46:47]
	v_pk_mul_f32 v[42:43], v[42:43], v[42:43]
	v_pk_mul_f32 v[36:37], v[36:37], v[36:37]
	v_pk_mul_f32 v[48:49], v[32:33], v[32:33]
	v_pk_mul_f32 v[38:39], v[38:39], v[38:39]
	v_pk_mul_f32 v[50:51], v[34:35], v[34:35]
	v_cvt_pk_bf16_f32 v32, v44, v45
	v_cvt_pk_bf16_f32 v33, v46, v47
	v_cvt_pk_bf16_f32 v34, v40, v41
	v_cvt_pk_bf16_f32 v35, v42, v43
	v_cvt_pk_bf16_f32 v36, v36, v37
	v_cvt_pk_bf16_f32 v37, v38, v39
	v_cvt_pk_bf16_f32 v38, v48, v49
	v_cvt_pk_bf16_f32 v39, v50, v51
	buffer_store_dwordx4 v[32:35], v52, s[12:15], 0 offen sc1
	buffer_store_dwordx4 v[36:39], v52, s[12:15], 0 offen offset:256 sc1
	global_load_dword v32, v[146:147], off offset:640
	s_waitcnt vmcnt(0)
	v_fmamk_f32 v32, v32, 0x3a800000, v154
	v_mul_f32_e32 v33, 0x4b800000, v32
	v_cmp_gt_f32_e32 vcc, s57, v32
	v_add_u32_e32 v36, 0x140000, v149
	s_nop 0
	v_cndmask_b32_e32 v32, v32, v33, vcc
	v_rsq_f32_e32 v32, v32
	s_nop 0
	v_mul_f32_e32 v33, 0x45800000, v32
	v_cndmask_b32_e32 v32, v32, v33, vcc
	v_pk_mul_f32 v[30:31], v[30:31], v[32:33] op_sel_hi:[1,0]
	v_pk_mul_f32 v[28:29], v[28:29], v[32:33] op_sel_hi:[1,0]
	v_pk_mul_f32 v[26:27], v[26:27], v[32:33] op_sel_hi:[1,0]
	v_pk_mul_f32 v[24:25], v[24:25], v[32:33] op_sel_hi:[1,0]
	v_pk_mul_f32 v[22:23], v[22:23], v[32:33] op_sel_hi:[1,0]
	v_pk_mul_f32 v[20:21], v[20:21], v[32:33] op_sel_hi:[1,0]
	v_pk_mul_f32 v[18:19], v[18:19], v[32:33] op_sel_hi:[1,0]
	v_pk_mul_f32 v[16:17], v[16:17], v[32:33] op_sel_hi:[1,0]
	v_max_f32_e32 v28, 0, v28
	v_max_f32_e32 v24, 0, v24
	v_max_f32_e32 v29, 0, v29
	v_max_f32_e32 v25, 0, v25
	v_max_f32_e32 v30, 0, v30
	v_max_f32_e32 v26, 0, v26
	v_max_f32_e32 v31, 0, v31
	v_max_f32_e32 v27, 0, v27
	v_max_f32_e32 v20, 0, v20
	v_max_f32_e32 v16, 0, v16
	v_max_f32_e32 v21, 0, v21
	v_max_f32_e32 v17, 0, v17
	v_max_f32_e32 v22, 0, v22
	v_max_f32_e32 v18, 0, v18
	v_max_f32_e32 v23, 0, v23
	v_max_f32_e32 v19, 0, v19
	v_pk_mul_f32 v[28:29], v[28:29], v[28:29]
	v_pk_mul_f32 v[24:25], v[24:25], v[24:25]
	v_pk_mul_f32 v[30:31], v[30:31], v[30:31]
	v_pk_mul_f32 v[26:27], v[26:27], v[26:27]
	v_pk_mul_f32 v[20:21], v[20:21], v[20:21]
	v_pk_mul_f32 v[32:33], v[16:17], v[16:17]
	v_pk_mul_f32 v[22:23], v[22:23], v[22:23]
	v_pk_mul_f32 v[34:35], v[18:19], v[18:19]
	v_cvt_pk_bf16_f32 v16, v28, v29
	v_cvt_pk_bf16_f32 v17, v30, v31
	v_cvt_pk_bf16_f32 v18, v24, v25
	v_cvt_pk_bf16_f32 v19, v26, v27
	v_cvt_pk_bf16_f32 v20, v20, v21
	v_cvt_pk_bf16_f32 v21, v22, v23
	v_cvt_pk_bf16_f32 v22, v32, v33
	v_cvt_pk_bf16_f32 v23, v34, v35
	buffer_store_dwordx4 v[16:19], v36, s[12:15], 0 offen sc1
	buffer_store_dwordx4 v[20:23], v36, s[12:15], 0 offen offset:256 sc1
	global_load_dword v16, v[146:147], off offset:704
	s_andn2_b64 vcc, exec, s[6:7]
	v_add_u32_e32 v20, 0x160000, v149
	s_mov_b64 s[6:7], -1
	s_waitcnt vmcnt(0)
	v_fmamk_f32 v16, v16, 0x3a800000, v154
	v_mul_f32_e32 v17, 0x4b800000, v16
	v_cmp_gt_f32_e64 s[8:9], s57, v16
	s_nop 1
	v_cndmask_b32_e64 v16, v16, v17, s[8:9]
	v_rsq_f32_e32 v16, v16
	s_nop 0
	v_mul_f32_e32 v17, 0x45800000, v16
	v_cndmask_b32_e64 v16, v16, v17, s[8:9]
	v_pk_mul_f32 v[14:15], v[14:15], v[16:17] op_sel_hi:[1,0]
	v_pk_mul_f32 v[12:13], v[12:13], v[16:17] op_sel_hi:[1,0]
	v_pk_mul_f32 v[10:11], v[10:11], v[16:17] op_sel_hi:[1,0]
	v_pk_mul_f32 v[8:9], v[8:9], v[16:17] op_sel_hi:[1,0]
	v_pk_mul_f32 v[6:7], v[6:7], v[16:17] op_sel_hi:[1,0]
	v_pk_mul_f32 v[4:5], v[4:5], v[16:17] op_sel_hi:[1,0]
	v_pk_mul_f32 v[2:3], v[2:3], v[16:17] op_sel_hi:[1,0]
	v_pk_mul_f32 v[0:1], v[0:1], v[16:17] op_sel_hi:[1,0]
	v_max_f32_e32 v12, 0, v12
	v_max_f32_e32 v8, 0, v8
	v_max_f32_e32 v13, 0, v13
	v_max_f32_e32 v9, 0, v9
	v_max_f32_e32 v14, 0, v14
	v_max_f32_e32 v10, 0, v10
	v_max_f32_e32 v15, 0, v15
	v_max_f32_e32 v11, 0, v11
	v_max_f32_e32 v4, 0, v4
	v_max_f32_e32 v0, 0, v0
	v_max_f32_e32 v5, 0, v5
	v_max_f32_e32 v1, 0, v1
	v_max_f32_e32 v6, 0, v6
	v_max_f32_e32 v2, 0, v2
	v_max_f32_e32 v7, 0, v7
	v_max_f32_e32 v3, 0, v3
	v_pk_mul_f32 v[12:13], v[12:13], v[12:13]
	v_pk_mul_f32 v[8:9], v[8:9], v[8:9]
	v_pk_mul_f32 v[14:15], v[14:15], v[14:15]
	v_pk_mul_f32 v[10:11], v[10:11], v[10:11]
	v_pk_mul_f32 v[4:5], v[4:5], v[4:5]
	v_pk_mul_f32 v[16:17], v[0:1], v[0:1]
	v_pk_mul_f32 v[6:7], v[6:7], v[6:7]
	v_pk_mul_f32 v[18:19], v[2:3], v[2:3]
	v_cvt_pk_bf16_f32 v0, v12, v13
	v_cvt_pk_bf16_f32 v1, v14, v15
	v_cvt_pk_bf16_f32 v2, v8, v9
	v_cvt_pk_bf16_f32 v3, v10, v11
	v_cvt_pk_bf16_f32 v4, v4, v5
	v_cvt_pk_bf16_f32 v5, v6, v7
	v_cvt_pk_bf16_f32 v6, v16, v17
	v_cvt_pk_bf16_f32 v7, v18, v19
	buffer_store_dwordx4 v[0:3], v20, s[12:15], 0 offen sc1
	buffer_store_dwordx4 v[4:7], v20, s[12:15], 0 offen offset:256 sc1
	s_branch .Lpp11_done
; __device__ __forceinline__ unsigned cvt_pk_bf16(float lo, float hi) { f32x2_t v = {lo, hi}; bf16x2_t b = __builtin_convertvector(v, bf16x2_t); return __builtin_bit_cast(unsigned, b); }
;     __device__ __forceinline__ void operator()(const f32x4 (&acc)[2][2][4][2], const Unit& u, int wr, int wc, int fr, int fq) const {
;     ...
;             for (int m = 0; m < 4; ++m) { const int row = row0 + ai * HALF + m * 16;
;                 const float rs = rowsq ? rsqrtf(rowsq[row] * (1.0f / 1024.0f) + 1e-6f) : 1.0f;
; #pragma unroll
;                 for (int bj = 0; bj < 2; ++bj) { f32x4 v0 = acc[ai][bj][m][0] * rs, v1 = acc[ai][bj][m][1] * rs;
;                     if (ACT == 1) {
; #pragma unroll
;                         for (int e = 0; e < 4; ++e) { const float a0 = fmaxf(v0[e], 0.f), a1 = fmaxf(v1[e], 0.f); v0[e] = a0 * a0; v1[e] = a1 * a1; } }
;                     u32x4 w; w.x = cvt_pk_bf16(v0[0], v0[1]); w.y = cvt_pk_bf16(v0[2], v0[3]); w.z = cvt_pk_bf16(v1[0], v1[1]); w.w = cvt_pk_bf16(v1[2], v1[3]);
;                     __builtin_amdgcn_raw_buffer_store_b128(w, rsrc, (unsigned)(((size_t)row * ldc + col0 + bj * HALF) * 2), 0,   16); } }
.Lpp11_plain:
	v_lshl_add_u32 v148, s8, 8, v129
	v_ashrrev_i32_e32 v149, 31, v148
	v_lshl_add_u64 v[146:147], v[148:149], 2, s[10:11]
	global_load_dword v156, v[146:147], off
	v_lshl_or_b32 v164, s9, 9, v155
	v_lshl_add_u32 v149, v148, 13, v164
	s_waitcnt vmcnt(0)
	v_fmamk_f32 v156, v156, 0x3a800000, v154
	v_mul_f32_e32 v157, 0x4b800000, v156
	v_cmp_gt_f32_e32 vcc, s57, v156
	s_nop 1
	v_cndmask_b32_e32 v156, v156, v157, vcc
	v_rsq_f32_e32 v160, v156
	v_or_b32_e32 v156, 16, v148
	v_ashrrev_i32_e32 v157, 31, v156
	v_lshl_add_u64 v[158:159], v[156:157], 2, s[10:11]
	v_mul_f32_e32 v157, 0x45800000, v160
	v_cndmask_b32_e32 v160, v160, v157, vcc
	v_pk_mul_f32 v[126:127], v[126:127], v[160:161] op_sel_hi:[1,0]
	v_pk_mul_f32 v[124:125], v[124:125], v[160:161] op_sel_hi:[1,0]
	v_pk_mul_f32 v[122:123], v[122:123], v[160:161] op_sel_hi:[1,0]
	v_pk_mul_f32 v[120:121], v[120:121], v[160:161] op_sel_hi:[1,0]
	v_pk_mul_f32 v[118:119], v[118:119], v[160:161] op_sel_hi:[1,0]
	v_pk_mul_f32 v[116:117], v[116:117], v[160:161] op_sel_hi:[1,0]
	v_pk_mul_f32 v[114:115], v[114:115], v[160:161] op_sel_hi:[1,0]
	v_pk_mul_f32 v[112:113], v[112:113], v[160:161] op_sel_hi:[1,0]
	v_max_f32_e32 v124, 0, v124
	v_max_f32_e32 v120, 0, v120
	v_max_f32_e32 v125, 0, v125
	v_max_f32_e32 v121, 0, v121
	v_max_f32_e32 v126, 0, v126
	v_max_f32_e32 v122, 0, v122
	v_max_f32_e32 v127, 0, v127
	v_max_f32_e32 v123, 0, v123
	v_max_f32_e32 v116, 0, v116
	v_max_f32_e32 v112, 0, v112
	v_max_f32_e32 v117, 0, v117
	v_max_f32_e32 v113, 0, v113
	v_max_f32_e32 v118, 0, v118
	v_max_f32_e32 v114, 0, v114
	v_max_f32_e32 v119, 0, v119
	v_max_f32_e32 v115, 0, v115
	v_pk_mul_f32 v[124:125], v[124:125], v[124:125]
	v_pk_mul_f32 v[120:121], v[120:121], v[120:121]
	v_pk_mul_f32 v[126:127], v[126:127], v[126:127]
	v_pk_mul_f32 v[122:123], v[122:123], v[122:123]
	v_pk_mul_f32 v[116:117], v[116:117], v[116:117]
	v_pk_mul_f32 v[160:161], v[112:113], v[112:113]
	v_pk_mul_f32 v[118:119], v[118:119], v[118:119]
	v_pk_mul_f32 v[162:163], v[114:115], v[114:115]
	v_cvt_pk_bf16_f32 v112, v124, v125
	v_cvt_pk_bf16_f32 v113, v126, v127
	v_cvt_pk_bf16_f32 v114, v120, v121
	v_cvt_pk_bf16_f32 v115, v122, v123
	v_cvt_pk_bf16_f32 v116, v116, v117
	v_cvt_pk_bf16_f32 v117, v118, v119
	v_cvt_pk_bf16_f32 v118, v160, v161
	v_cvt_pk_bf16_f32 v119, v162, v163
	buffer_store_dwordx4 v[112:115], v149, s[12:15], 0 offen
	buffer_store_dwordx4 v[116:119], v149, s[12:15], 0 offen offset:256
	global_load_dword v113, v[158:159], off
	v_or_b32_e32 v112, 32, v148
	v_lshl_add_u32 v120, v156, 13, v164
	s_waitcnt vmcnt(0)
	v_fmamk_f32 v113, v113, 0x3a800000, v154
	v_mul_f32_e32 v114, 0x4b800000, v113
	v_cmp_gt_f32_e32 vcc, s57, v113
	s_nop 1
	v_cndmask_b32_e32 v113, v113, v114, vcc
	v_rsq_f32_e32 v116, v113
	v_ashrrev_i32_e32 v113, 31, v112
	v_lshl_add_u64 v[114:115], v[112:113], 2, s[10:11]
	v_mul_f32_e32 v113, 0x45800000, v116
	v_cndmask_b32_e32 v116, v116, v113, vcc
	v_pk_mul_f32 v[110:111], v[110:111], v[116:117] op_sel_hi:[1,0]
	v_pk_mul_f32 v[108:109], v[108:109], v[116:117] op_sel_hi:[1,0]
	v_pk_mul_f32 v[106:107], v[106:107], v[116:117] op_sel_hi:[1,0]
	v_pk_mul_f32 v[104:105], v[104:105], v[116:117] op_sel_hi:[1,0]
	v_pk_mul_f32 v[102:103], v[102:103], v[116:117] op_sel_hi:[1,0]
	v_pk_mul_f32 v[100:101], v[100:101], v[116:117] op_sel_hi:[1,0]
	v_pk_mul_f32 v[98:99], v[98:99], v[116:117] op_sel_hi:[1,0]
	v_pk_mul_f32 v[96:97], v[96:97], v[116:117] op_sel_hi:[1,0]
	v_max_f32_e32 v108, 0, v108
	v_max_f32_e32 v104, 0, v104
	v_max_f32_e32 v109, 0, v109
	v_max_f32_e32 v105, 0, v105
	v_max_f32_e32 v110, 0, v110
	v_max_f32_e32 v106, 0, v106
	v_max_f32_e32 v111, 0, v111
	v_max_f32_e32 v107, 0, v107
	v_max_f32_e32 v100, 0, v100
	v_max_f32_e32 v96, 0, v96
	v_max_f32_e32 v101, 0, v101
	v_max_f32_e32 v97, 0, v97
	v_max_f32_e32 v102, 0, v102
	v_max_f32_e32 v98, 0, v98
	v_max_f32_e32 v103, 0, v103
	v_max_f32_e32 v99, 0, v99
	v_pk_mul_f32 v[108:109], v[108:109], v[108:109]
	v_pk_mul_f32 v[104:105], v[104:105], v[104:105]
	v_pk_mul_f32 v[110:111], v[110:111], v[110:111]
	v_pk_mul_f32 v[106:107], v[106:107], v[106:107]
	v_pk_mul_f32 v[100:101], v[100:101], v[100:101]
	v_pk_mul_f32 v[116:117], v[96:97], v[96:97]
	v_pk_mul_f32 v[102:103], v[102:103], v[102:103]
	v_pk_mul_f32 v[118:119], v[98:99], v[98:99]
	v_cvt_pk_bf16_f32 v96, v108, v109
	v_cvt_pk_bf16_f32 v97, v110, v111
	v_cvt_pk_bf16_f32 v98, v104, v105
	v_cvt_pk_bf16_f32 v99, v106, v107
	v_cvt_pk_bf16_f32 v100, v100, v101
	v_cvt_pk_bf16_f32 v101, v102, v103
	v_cvt_pk_bf16_f32 v102, v116, v117
	v_cvt_pk_bf16_f32 v103, v118, v119
	buffer_store_dwordx4 v[96:99], v120, s[12:15], 0 offen
	buffer_store_dwordx4 v[100:103], v120, s[12:15], 0 offen offset:256
	global_load_dword v97, v[114:115], off
	v_or_b32_e32 v96, 48, v148
	v_lshl_add_u32 v104, v112, 13, v164
	s_waitcnt vmcnt(0)
; __device__ __forceinline__ unsigned cvt_pk_bf16(float lo, float hi) { f32x2_t v = {lo, hi}; bf16x2_t b = __builtin_convertvector(v, bf16x2_t); return __builtin_bit_cast(unsigned, b); }
;     __device__ __forceinline__ void operator()(const f32x4 (&acc)[2][2][4][2], const Unit& u, int wr, int wc, int fr, int fq) const {
;     ...
;             for (int m = 0; m < 4; ++m) { const int row = row0 + ai * HALF + m * 16;
;                 const float rs = rowsq ? rsqrtf(rowsq[row] * (1.0f / 1024.0f) + 1e-6f) : 1.0f;
; #pragma unroll
;                 for (int bj = 0; bj < 2; ++bj) { f32x4 v0 = acc[ai][bj][m][0] * rs, v1 = acc[ai][bj][m][1] * rs;
;                     if (ACT == 1) {
; #pragma unroll
;                         for (int e = 0; e < 4; ++e) { const float a0 = fmaxf(v0[e], 0.f), a1 = fmaxf(v1[e], 0.f); v0[e] = a0 * a0; v1[e] = a1 * a1; } }
;                     u32x4 w; w.x = cvt_pk_bf16(v0[0], v0[1]); w.y = cvt_pk_bf16(v0[2], v0[3]); w.z = cvt_pk_bf16(v1[0], v1[1]); w.w = cvt_pk_bf16(v1[2], v1[3]);
;                     __builtin_amdgcn_raw_buffer_store_b128(w, rsrc, (unsigned)(((size_t)row * ldc + col0 + bj * HALF) * 2), 0,   16); } }
	v_fmamk_f32 v97, v97, 0x3a800000, v154
	v_mul_f32_e32 v98, 0x4b800000, v97
	v_cmp_gt_f32_e32 vcc, s57, v97
	s_nop 1
	v_cndmask_b32_e32 v97, v97, v98, vcc
	v_rsq_f32_e32 v100, v97
	v_ashrrev_i32_e32 v97, 31, v96
	v_lshl_add_u64 v[98:99], v[96:97], 2, s[10:11]
	v_mul_f32_e32 v97, 0x45800000, v100
	v_cndmask_b32_e32 v100, v100, v97, vcc
	v_pk_mul_f32 v[94:95], v[94:95], v[100:101] op_sel_hi:[1,0]
	v_pk_mul_f32 v[92:93], v[92:93], v[100:101] op_sel_hi:[1,0]
	v_pk_mul_f32 v[90:91], v[90:91], v[100:101] op_sel_hi:[1,0]
	v_pk_mul_f32 v[88:89], v[88:89], v[100:101] op_sel_hi:[1,0]
	v_pk_mul_f32 v[86:87], v[86:87], v[100:101] op_sel_hi:[1,0]
	v_pk_mul_f32 v[84:85], v[84:85], v[100:101] op_sel_hi:[1,0]
	v_pk_mul_f32 v[82:83], v[82:83], v[100:101] op_sel_hi:[1,0]
	v_pk_mul_f32 v[80:81], v[80:81], v[100:101] op_sel_hi:[1,0]
	v_max_f32_e32 v92, 0, v92
	v_max_f32_e32 v88, 0, v88
	v_max_f32_e32 v93, 0, v93
	v_max_f32_e32 v89, 0, v89
	v_max_f32_e32 v94, 0, v94
	v_max_f32_e32 v90, 0, v90
	v_max_f32_e32 v95, 0, v95
	v_max_f32_e32 v91, 0, v91
	v_max_f32_e32 v84, 0, v84
	v_max_f32_e32 v80, 0, v80
	v_max_f32_e32 v85, 0, v85
	v_max_f32_e32 v81, 0, v81
	v_max_f32_e32 v86, 0, v86
	v_max_f32_e32 v82, 0, v82
	v_max_f32_e32 v87, 0, v87
	v_max_f32_e32 v83, 0, v83
	v_pk_mul_f32 v[92:93], v[92:93], v[92:93]
	v_pk_mul_f32 v[88:89], v[88:89], v[88:89]
	v_pk_mul_f32 v[94:95], v[94:95], v[94:95]
	v_pk_mul_f32 v[90:91], v[90:91], v[90:91]
	v_pk_mul_f32 v[84:85], v[84:85], v[84:85]
	v_pk_mul_f32 v[100:101], v[80:81], v[80:81]
	v_pk_mul_f32 v[86:87], v[86:87], v[86:87]
	v_pk_mul_f32 v[102:103], v[82:83], v[82:83]
	v_cvt_pk_bf16_f32 v80, v92, v93
	v_cvt_pk_bf16_f32 v81, v94, v95
	v_cvt_pk_bf16_f32 v82, v88, v89
	v_cvt_pk_bf16_f32 v83, v90, v91
	v_cvt_pk_bf16_f32 v84, v84, v85
	v_cvt_pk_bf16_f32 v85, v86, v87
	v_cvt_pk_bf16_f32 v86, v100, v101
	v_cvt_pk_bf16_f32 v87, v102, v103
	buffer_store_dwordx4 v[80:83], v104, s[12:15], 0 offen
	buffer_store_dwordx4 v[84:87], v104, s[12:15], 0 offen offset:256
	global_load_dword v80, v[98:99], off
	s_waitcnt vmcnt(0)
	v_fmamk_f32 v80, v80, 0x3a800000, v154
	v_mul_f32_e32 v81, 0x4b800000, v80
	v_cmp_gt_f32_e32 vcc, s57, v80
	v_lshl_add_u32 v84, v96, 13, v164
	s_nop 0
	v_cndmask_b32_e32 v80, v80, v81, vcc
	v_rsq_f32_e32 v80, v80
	s_nop 0
	v_mul_f32_e32 v81, 0x45800000, v80
	v_cndmask_b32_e32 v80, v80, v81, vcc
	v_pk_mul_f32 v[78:79], v[78:79], v[80:81] op_sel_hi:[1,0]
	v_pk_mul_f32 v[76:77], v[76:77], v[80:81] op_sel_hi:[1,0]
	v_pk_mul_f32 v[74:75], v[74:75], v[80:81] op_sel_hi:[1,0]
	v_pk_mul_f32 v[72:73], v[72:73], v[80:81] op_sel_hi:[1,0]
	v_pk_mul_f32 v[70:71], v[70:71], v[80:81] op_sel_hi:[1,0]
	v_pk_mul_f32 v[68:69], v[68:69], v[80:81] op_sel_hi:[1,0]
	v_pk_mul_f32 v[66:67], v[66:67], v[80:81] op_sel_hi:[1,0]
	v_pk_mul_f32 v[64:65], v[64:65], v[80:81] op_sel_hi:[1,0]
	v_max_f32_e32 v76, 0, v76
	v_max_f32_e32 v72, 0, v72
	v_max_f32_e32 v77, 0, v77
	v_max_f32_e32 v73, 0, v73
	v_max_f32_e32 v78, 0, v78
	v_max_f32_e32 v74, 0, v74
	v_max_f32_e32 v79, 0, v79
	v_max_f32_e32 v75, 0, v75
	v_max_f32_e32 v68, 0, v68
	v_max_f32_e32 v64, 0, v64
	v_max_f32_e32 v69, 0, v69
	v_max_f32_e32 v65, 0, v65
	v_max_f32_e32 v70, 0, v70
	v_max_f32_e32 v66, 0, v66
	v_max_f32_e32 v71, 0, v71
	v_max_f32_e32 v67, 0, v67
	v_pk_mul_f32 v[76:77], v[76:77], v[76:77]
	v_pk_mul_f32 v[72:73], v[72:73], v[72:73]
	v_pk_mul_f32 v[78:79], v[78:79], v[78:79]
	v_pk_mul_f32 v[74:75], v[74:75], v[74:75]
	v_pk_mul_f32 v[68:69], v[68:69], v[68:69]
	v_pk_mul_f32 v[80:81], v[64:65], v[64:65]
	v_pk_mul_f32 v[70:71], v[70:71], v[70:71]
	v_pk_mul_f32 v[82:83], v[66:67], v[66:67]
	v_cvt_pk_bf16_f32 v64, v76, v77
	v_cvt_pk_bf16_f32 v65, v78, v79
	v_cvt_pk_bf16_f32 v66, v72, v73
	v_cvt_pk_bf16_f32 v67, v74, v75
	v_cvt_pk_bf16_f32 v68, v68, v69
	v_cvt_pk_bf16_f32 v69, v70, v71
	v_cvt_pk_bf16_f32 v70, v80, v81
	v_cvt_pk_bf16_f32 v71, v82, v83
	buffer_store_dwordx4 v[64:67], v84, s[12:15], 0 offen
	buffer_store_dwordx4 v[68:71], v84, s[12:15], 0 offen offset:256
	global_load_dword v64, v[146:147], off offset:512
	s_waitcnt vmcnt(0)
	v_fmamk_f32 v64, v64, 0x3a800000, v154
	v_mul_f32_e32 v65, 0x4b800000, v64
	v_cmp_gt_f32_e32 vcc, s57, v64
	v_add_u32_e32 v68, 0x100000, v149
	s_nop 0
	v_cndmask_b32_e32 v64, v64, v65, vcc
	v_rsq_f32_e32 v64, v64
	s_nop 0
	v_mul_f32_e32 v65, 0x45800000, v64
	v_cndmask_b32_e32 v64, v64, v65, vcc
	v_pk_mul_f32 v[62:63], v[62:63], v[64:65] op_sel_hi:[1,0]
	v_pk_mul_f32 v[60:61], v[60:61], v[64:65] op_sel_hi:[1,0]
	v_pk_mul_f32 v[58:59], v[58:59], v[64:65] op_sel_hi:[1,0]
	v_pk_mul_f32 v[56:57], v[56:57], v[64:65] op_sel_hi:[1,0]
	v_pk_mul_f32 v[54:55], v[54:55], v[64:65] op_sel_hi:[1,0]
	v_pk_mul_f32 v[52:53], v[52:53], v[64:65] op_sel_hi:[1,0]
	v_pk_mul_f32 v[50:51], v[50:51], v[64:65] op_sel_hi:[1,0]
	v_pk_mul_f32 v[48:49], v[48:49], v[64:65] op_sel_hi:[1,0]
	v_max_f32_e32 v60, 0, v60
	v_max_f32_e32 v56, 0, v56
	v_max_f32_e32 v61, 0, v61
	v_max_f32_e32 v57, 0, v57
	v_max_f32_e32 v62, 0, v62
	v_max_f32_e32 v58, 0, v58
	v_max_f32_e32 v63, 0, v63
	v_max_f32_e32 v59, 0, v59
	v_max_f32_e32 v52, 0, v52
	v_max_f32_e32 v48, 0, v48
	v_max_f32_e32 v53, 0, v53
	v_max_f32_e32 v49, 0, v49
	v_max_f32_e32 v54, 0, v54
	v_max_f32_e32 v50, 0, v50
	v_max_f32_e32 v55, 0, v55
	v_max_f32_e32 v51, 0, v51
	v_pk_mul_f32 v[60:61], v[60:61], v[60:61]
	v_pk_mul_f32 v[56:57], v[56:57], v[56:57]
	v_pk_mul_f32 v[62:63], v[62:63], v[62:63]
	v_pk_mul_f32 v[58:59], v[58:59], v[58:59]
	v_pk_mul_f32 v[52:53], v[52:53], v[52:53]
	v_pk_mul_f32 v[64:65], v[48:49], v[48:49]
	v_pk_mul_f32 v[54:55], v[54:55], v[54:55]
	v_pk_mul_f32 v[66:67], v[50:51], v[50:51]
	v_cvt_pk_bf16_f32 v48, v60, v61
	v_cvt_pk_bf16_f32 v49, v62, v63
	v_cvt_pk_bf16_f32 v50, v56, v57
	v_cvt_pk_bf16_f32 v51, v58, v59
	v_cvt_pk_bf16_f32 v52, v52, v53
	v_cvt_pk_bf16_f32 v53, v54, v55
	v_cvt_pk_bf16_f32 v54, v64, v65
	v_cvt_pk_bf16_f32 v55, v66, v67
	buffer_store_dwordx4 v[48:51], v68, s[12:15], 0 offen
	buffer_store_dwordx4 v[52:55], v68, s[12:15], 0 offen offset:256
	global_load_dword v48, v[146:147], off offset:576
	s_waitcnt vmcnt(0)
; __device__ __forceinline__ unsigned cvt_pk_bf16(float lo, float hi) { f32x2_t v = {lo, hi}; bf16x2_t b = __builtin_convertvector(v, bf16x2_t); return __builtin_bit_cast(unsigned, b); }
;     __device__ __forceinline__ void operator()(const f32x4 (&acc)[2][2][4][2], const Unit& u, int wr, int wc, int fr, int fq) const {
;     ...
;             for (int m = 0; m < 4; ++m) { const int row = row0 + ai * HALF + m * 16;
;                 const float rs = rowsq ? rsqrtf(rowsq[row] * (1.0f / 1024.0f) + 1e-6f) : 1.0f;
; #pragma unroll
;                 for (int bj = 0; bj < 2; ++bj) { f32x4 v0 = acc[ai][bj][m][0] * rs, v1 = acc[ai][bj][m][1] * rs;
;                     if (ACT == 1) {
; #pragma unroll
;                         for (int e = 0; e < 4; ++e) { const float a0 = fmaxf(v0[e], 0.f), a1 = fmaxf(v1[e], 0.f); v0[e] = a0 * a0; v1[e] = a1 * a1; } }
;                     u32x4 w; w.x = cvt_pk_bf16(v0[0], v0[1]); w.y = cvt_pk_bf16(v0[2], v0[3]); w.z = cvt_pk_bf16(v1[0], v1[1]); w.w = cvt_pk_bf16(v1[2], v1[3]);
;                     __builtin_amdgcn_raw_buffer_store_b128(w, rsrc, (unsigned)(((size_t)row * ldc + col0 + bj * HALF) * 2), 0,   16); } }
	v_fmamk_f32 v48, v48, 0x3a800000, v154
	v_mul_f32_e32 v49, 0x4b800000, v48
	v_cmp_gt_f32_e32 vcc, s57, v48
	v_add_u32_e32 v52, 0x120000, v149
	s_nop 0
	v_cndmask_b32_e32 v48, v48, v49, vcc
	v_rsq_f32_e32 v48, v48
	s_nop 0
	v_mul_f32_e32 v49, 0x45800000, v48
	v_cndmask_b32_e32 v48, v48, v49, vcc
	v_pk_mul_f32 v[46:47], v[46:47], v[48:49] op_sel_hi:[1,0]
	v_pk_mul_f32 v[44:45], v[44:45], v[48:49] op_sel_hi:[1,0]
	v_pk_mul_f32 v[42:43], v[42:43], v[48:49] op_sel_hi:[1,0]
	v_pk_mul_f32 v[40:41], v[40:41], v[48:49] op_sel_hi:[1,0]
	v_pk_mul_f32 v[38:39], v[38:39], v[48:49] op_sel_hi:[1,0]
	v_pk_mul_f32 v[36:37], v[36:37], v[48:49] op_sel_hi:[1,0]
	v_pk_mul_f32 v[34:35], v[34:35], v[48:49] op_sel_hi:[1,0]
	v_pk_mul_f32 v[32:33], v[32:33], v[48:49] op_sel_hi:[1,0]
	v_max_f32_e32 v44, 0, v44
	v_max_f32_e32 v40, 0, v40
	v_max_f32_e32 v45, 0, v45
	v_max_f32_e32 v41, 0, v41
	v_max_f32_e32 v46, 0, v46
	v_max_f32_e32 v42, 0, v42
	v_max_f32_e32 v47, 0, v47
	v_max_f32_e32 v43, 0, v43
	v_max_f32_e32 v36, 0, v36
	v_max_f32_e32 v32, 0, v32
	v_max_f32_e32 v37, 0, v37
	v_max_f32_e32 v33, 0, v33
	v_max_f32_e32 v38, 0, v38
	v_max_f32_e32 v34, 0, v34
	v_max_f32_e32 v39, 0, v39
	v_max_f32_e32 v35, 0, v35
	v_pk_mul_f32 v[44:45], v[44:45], v[44:45]
	v_pk_mul_f32 v[40:41], v[40:41], v[40:41]
	v_pk_mul_f32 v[46:47], v[46:47], v[46:47]
	v_pk_mul_f32 v[42:43], v[42:43], v[42:43]
	v_pk_mul_f32 v[36:37], v[36:37], v[36:37]
	v_pk_mul_f32 v[48:49], v[32:33], v[32:33]
	v_pk_mul_f32 v[38:39], v[38:39], v[38:39]
	v_pk_mul_f32 v[50:51], v[34:35], v[34:35]
	v_cvt_pk_bf16_f32 v32, v44, v45
	v_cvt_pk_bf16_f32 v33, v46, v47
	v_cvt_pk_bf16_f32 v34, v40, v41
	v_cvt_pk_bf16_f32 v35, v42, v43
	v_cvt_pk_bf16_f32 v36, v36, v37
	v_cvt_pk_bf16_f32 v37, v38, v39
	v_cvt_pk_bf16_f32 v38, v48, v49
	v_cvt_pk_bf16_f32 v39, v50, v51
	buffer_store_dwordx4 v[32:35], v52, s[12:15], 0 offen
	buffer_store_dwordx4 v[36:39], v52, s[12:15], 0 offen offset:256
	global_load_dword v32, v[146:147], off offset:640
	s_waitcnt vmcnt(0)
	v_fmamk_f32 v32, v32, 0x3a800000, v154
	v_mul_f32_e32 v33, 0x4b800000, v32
	v_cmp_gt_f32_e32 vcc, s57, v32
	v_add_u32_e32 v36, 0x140000, v149
	s_nop 0
	v_cndmask_b32_e32 v32, v32, v33, vcc
	v_rsq_f32_e32 v32, v32
	s_nop 0
	v_mul_f32_e32 v33, 0x45800000, v32
	v_cndmask_b32_e32 v32, v32, v33, vcc
	v_pk_mul_f32 v[30:31], v[30:31], v[32:33] op_sel_hi:[1,0]
	v_pk_mul_f32 v[28:29], v[28:29], v[32:33] op_sel_hi:[1,0]
	v_pk_mul_f32 v[26:27], v[26:27], v[32:33] op_sel_hi:[1,0]
	v_pk_mul_f32 v[24:25], v[24:25], v[32:33] op_sel_hi:[1,0]
	v_pk_mul_f32 v[22:23], v[22:23], v[32:33] op_sel_hi:[1,0]
	v_pk_mul_f32 v[20:21], v[20:21], v[32:33] op_sel_hi:[1,0]
	v_pk_mul_f32 v[18:19], v[18:19], v[32:33] op_sel_hi:[1,0]
	v_pk_mul_f32 v[16:17], v[16:17], v[32:33] op_sel_hi:[1,0]
	v_max_f32_e32 v28, 0, v28
	v_max_f32_e32 v24, 0, v24
	v_max_f32_e32 v29, 0, v29
	v_max_f32_e32 v25, 0, v25
	v_max_f32_e32 v30, 0, v30
	v_max_f32_e32 v26, 0, v26
	v_max_f32_e32 v31, 0, v31
	v_max_f32_e32 v27, 0, v27
	v_max_f32_e32 v20, 0, v20
	v_max_f32_e32 v16, 0, v16
	v_max_f32_e32 v21, 0, v21
	v_max_f32_e32 v17, 0, v17
	v_max_f32_e32 v22, 0, v22
	v_max_f32_e32 v18, 0, v18
	v_max_f32_e32 v23, 0, v23
	v_max_f32_e32 v19, 0, v19
	v_pk_mul_f32 v[28:29], v[28:29], v[28:29]
	v_pk_mul_f32 v[24:25], v[24:25], v[24:25]
	v_pk_mul_f32 v[30:31], v[30:31], v[30:31]
	v_pk_mul_f32 v[26:27], v[26:27], v[26:27]
	v_pk_mul_f32 v[20:21], v[20:21], v[20:21]
	v_pk_mul_f32 v[32:33], v[16:17], v[16:17]
	v_pk_mul_f32 v[22:23], v[22:23], v[22:23]
	v_pk_mul_f32 v[34:35], v[18:19], v[18:19]
	v_cvt_pk_bf16_f32 v16, v28, v29
	v_cvt_pk_bf16_f32 v17, v30, v31
	v_cvt_pk_bf16_f32 v18, v24, v25
	v_cvt_pk_bf16_f32 v19, v26, v27
	v_cvt_pk_bf16_f32 v20, v20, v21
	v_cvt_pk_bf16_f32 v21, v22, v23
	v_cvt_pk_bf16_f32 v22, v32, v33
	v_cvt_pk_bf16_f32 v23, v34, v35
	buffer_store_dwordx4 v[16:19], v36, s[12:15], 0 offen
	buffer_store_dwordx4 v[20:23], v36, s[12:15], 0 offen offset:256
	global_load_dword v16, v[146:147], off offset:704
	s_andn2_b64 vcc, exec, s[6:7]
	v_add_u32_e32 v20, 0x160000, v149
	s_mov_b64 s[6:7], -1
	s_waitcnt vmcnt(0)
	v_fmamk_f32 v16, v16, 0x3a800000, v154
	v_mul_f32_e32 v17, 0x4b800000, v16
	v_cmp_gt_f32_e64 s[8:9], s57, v16
	s_nop 1
	v_cndmask_b32_e64 v16, v16, v17, s[8:9]
	v_rsq_f32_e32 v16, v16
	s_nop 0
	v_mul_f32_e32 v17, 0x45800000, v16
	v_cndmask_b32_e64 v16, v16, v17, s[8:9]
	v_pk_mul_f32 v[14:15], v[14:15], v[16:17] op_sel_hi:[1,0]
	v_pk_mul_f32 v[12:13], v[12:13], v[16:17] op_sel_hi:[1,0]
	v_pk_mul_f32 v[10:11], v[10:11], v[16:17] op_sel_hi:[1,0]
	v_pk_mul_f32 v[8:9], v[8:9], v[16:17] op_sel_hi:[1,0]
	v_pk_mul_f32 v[6:7], v[6:7], v[16:17] op_sel_hi:[1,0]
	v_pk_mul_f32 v[4:5], v[4:5], v[16:17] op_sel_hi:[1,0]
	v_pk_mul_f32 v[2:3], v[2:3], v[16:17] op_sel_hi:[1,0]
	v_pk_mul_f32 v[0:1], v[0:1], v[16:17] op_sel_hi:[1,0]
	v_max_f32_e32 v12, 0, v12
	v_max_f32_e32 v8, 0, v8
	v_max_f32_e32 v13, 0, v13
	v_max_f32_e32 v9, 0, v9
	v_max_f32_e32 v14, 0, v14
	v_max_f32_e32 v10, 0, v10
	v_max_f32_e32 v15, 0, v15
	v_max_f32_e32 v11, 0, v11
	v_max_f32_e32 v4, 0, v4
	v_max_f32_e32 v0, 0, v0
	v_max_f32_e32 v5, 0, v5
	v_max_f32_e32 v1, 0, v1
	v_max_f32_e32 v6, 0, v6
	v_max_f32_e32 v2, 0, v2
	v_max_f32_e32 v7, 0, v7
	v_max_f32_e32 v3, 0, v3
	v_pk_mul_f32 v[12:13], v[12:13], v[12:13]
	v_pk_mul_f32 v[8:9], v[8:9], v[8:9]
	v_pk_mul_f32 v[14:15], v[14:15], v[14:15]
	v_pk_mul_f32 v[10:11], v[10:11], v[10:11]
	v_pk_mul_f32 v[4:5], v[4:5], v[4:5]
	v_pk_mul_f32 v[16:17], v[0:1], v[0:1]
	v_pk_mul_f32 v[6:7], v[6:7], v[6:7]
	v_pk_mul_f32 v[18:19], v[2:3], v[2:3]
	v_cvt_pk_bf16_f32 v0, v12, v13
	v_cvt_pk_bf16_f32 v1, v14, v15
	v_cvt_pk_bf16_f32 v2, v8, v9
	v_cvt_pk_bf16_f32 v3, v10, v11
	v_cvt_pk_bf16_f32 v4, v4, v5
	v_cvt_pk_bf16_f32 v5, v6, v7
	v_cvt_pk_bf16_f32 v6, v16, v17
	v_cvt_pk_bf16_f32 v7, v18, v19
	buffer_store_dwordx4 v[0:3], v20, s[12:15], 0 offen
	buffer_store_dwordx4 v[4:7], v20, s[12:15], 0 offen offset:256
.Lpp11_done:
	s_cbranch_vccnz .LBB0_897
	s_andn2_b64 vcc, exec, s[24:25]
	s_cbranch_vccnz .LBB0_896
	s_barrier
	s_branch .LBB0_896
